# all projection tiles on in-register epilogue (V tiles via wave-private LDS transpose), old epilogue removed, next-tile first-DMA prefetch with counted K-loop entry, K rotation
# speedup vs baseline: 1.0337x; 1.0062x over previous
.LBB0_126:
	v_writelane_b32 v254, s52, 25
	s_nop 1
	v_writelane_b32 v254, s53, 26
	v_writelane_b32 v254, s54, 27
	v_writelane_b32 v254, s55, 28
	v_writelane_b32 v254, s56, 29
	v_writelane_b32 v254, s57, 30
	v_writelane_b32 v254, s58, 31
	v_writelane_b32 v254, s59, 32
	v_writelane_b32 v254, s60, 33
	v_writelane_b32 v254, s61, 34
	v_writelane_b32 v254, s62, 35
	v_writelane_b32 v254, s63, 36
	v_writelane_b32 v254, s64, 37
	v_writelane_b32 v254, s65, 38
	v_writelane_b32 v254, s66, 39
	v_writelane_b32 v254, s67, 40
	s_or_b64 exec, exec, s[0:1]
	v_mov_b32_e32 v144, v178
	s_mov_b64 s[0:1], 0
	v_readlane_b32 s2, v254, 0
	s_waitcnt lgkmcnt(0)
	s_barrier
	v_readlane_b32 s3, v254, 1
	s_add_u32 s21, s2, s0
	s_addc_u32 s33, s3, s1
	s_cmpk_lt_i32 s88, 0x440
	s_cselect_b64 s[2:3], -1, 0
	v_writelane_b32 v254, s2, 41
	s_cmpk_gt_i32 s88, 0x43f
	s_nop 0
	v_writelane_b32 v254, s3, 42
	s_cbranch_scc1 .LBB0_179
	s_add_u32 s41, s21, 0xa120000
	s_addc_u32 s49, s33, 0
	s_add_u32 s2, s21, 0x14920000
	v_and_b32_e32 v0, 63, v144
	v_lshlrev_b32_e32 v3, 8, v144
	v_lshlrev_b32_e32 v4, 4, v144
	s_movk_i32 s4, 0x70
	s_addc_u32 s3, s33, 0
	v_and_b32_e32 v3, 0x3800, v3
	v_bitop3_b32 v0, v0, s4, v4 bitop3:0x48
	s_add_u32 s6, s21, 0x1ad20000
	v_and_b32_e32 v1, 31, v144
	v_bfe_u32 v2, v144, 5, 1
	v_or_b32_e32 v145, v0, v3
	v_bitop3_b32 v185, v0, 64, v3 bitop3:0x36
	v_lshrrev_b32_e32 v0, 1, v144
	s_mov_b32 s4, 0x1ffff80
	s_addc_u32 s7, s33, 0
	v_bfe_u32 v3, v144, 1, 3
	v_and_or_b32 v1, v0, s4, v1
	v_bitop3_b32 v0, v2, v0, 7 bitop3:0x78
	s_add_u32 s8, s21, 0x1ada0000
	v_lshlrev_b32_e32 v188, 4, v0
	v_bitop3_b32 v0, v2, v3, 2 bitop3:0x36
	s_addc_u32 s9, s33, 0
	v_lshlrev_b32_e32 v189, 4, v0
	v_bitop3_b32 v0, v2, v3, 4 bitop3:0x36
	s_add_u32 s10, s21, 0x1ade0000
	v_lshlrev_b32_e32 v190, 4, v0
	v_bitop3_b32 v0, v2, v3, 6 bitop3:0x36
	s_addc_u32 s11, s33, 0
	v_lshlrev_b32_e32 v191, 4, v0
	v_and_b32_e32 v0, 64, v179
	s_lshl_b32 s60, s90, 3
	v_readlane_b32 s4, v254, 0
	v_add_u32_e32 v0, 64, v0
	v_readlane_b32 s5, v254, 1
	s_add_u32 s0, s4, s0
	v_lshlrev_b32_e32 v186, 7, v1
	v_lshlrev_b32_e32 v1, 7, v144
	v_cmp_lt_i32_e32 vcc, v184, v0
	s_addc_u32 s1, s5, s1
	v_and_b32_e32 v187, 0x6f80, v1
	v_cndmask_b32_e32 v1, v179, v184, vcc
	v_cmp_lt_i32_e32 vcc, v183, v0
	s_add_u32 s12, s0, 0xc120008
	v_lshlrev_b32_e32 v192, 2, v1
	v_cndmask_b32_e32 v1, v179, v183, vcc
	v_cmp_lt_i32_e32 vcc, v182, v0
	s_addc_u32 s13, s1, 0
	s_lshl_b32 s61, s88, 2
	s_lshl_b32 s62, s90, 2
	v_cndmask_b32_e32 v0, v179, v182, vcc
	s_add_u32 s14, s0, 0xc120108
	s_movk_i32 s18, 0xde00
	v_lshlrev_b32_e32 v193, 2, v1
	v_lshlrev_b32_e32 v194, 2, v0
	s_addc_u32 s15, s1, 0
	s_mov_b32 s17, 0
	s_movk_i32 s63, 0x410
	s_movk_i32 s64, 0x100
	v_mov_b32_e32 v147, 0
	s_mov_b32 s19, -1
	v_mov_b32_e32 v195, 0x358637bd
	s_mov_b32 s65, 0x800000
	s_movk_i32 s66, 0x2200
	s_mov_b32 s20, 0x3e000000
	s_mov_b64 s[22:23], 0x44000
	v_mov_b32_e32 v196, 0x20800
	v_readlane_b32 s67, v254, 22
	s_mov_b32 s80, 0
	s_mov_b32 s68, s88
	s_branch .LBB0_129

.LBB0_129:
	s_lshl_b32 s0, s68, 3
	s_and_b32 s16, s0, 56
	s_bfe_u32 s0, s68, 0x30003
	s_or_b32 s24, s16, s0
	s_lshl_b32 s38, s68, 2
	s_lshr_b32 s25, s68, 3
	s_and_b32 s50, s38, 0xffffff00
	s_lshl_b32 s0, s24, 19
	s_add_u32 s4, s41, s0
	s_addc_u32 s5, s49, 0
	s_ashr_i32 s51, s50, 31
	s_lshl_b64 s[0:1], s[50:51], 11
	s_add_u32 s26, s21, s0
	v_readfirstlane_b32 s0, v144
	s_addc_u32 s27, s33, s1
	s_ashr_i32 s28, s0, 6
	s_lshl_b32 s0, s28, 5
	s_ashr_i32 s1, s0, 31
	s_lshl_b64 s[0:1], s[0:1], 11
	s_add_u32 s4, s4, s0
	s_addc_u32 s5, s5, s1
	s_add_u32 s0, s26, s0
	s_addc_u32 s1, s27, s1
	s_lshl_b32 s26, s28, 12
	s_add_i32 s27, s26, 0x8000
	s_and_b32 s81, s24, 7
	s_lshl_b32 s81, s81, 8
	s_add_u32 s4, s4, s81
	s_addc_u32 s5, s5, 0
	s_add_u32 s0, s0, s81
	s_addc_u32 s1, s1, 0
	s_cmp_eq_u32 s80, 1
	s_cbranch_scc1 .Lpf_skip_L0
	s_add_u32 s28, s4, 0x4000
	s_barrier
	s_mov_b32 m0, s26
	global_load_lds_dwordx4 v145, s[4:5]
	s_addc_u32 s29, s5, 0
	s_or_b32 s30, s26, 0x400
	s_mov_b32 m0, s30
	global_load_lds_dwordx4 v185, s[28:29]
	s_add_u32 s28, s4, 0x8000
	s_addc_u32 s29, s5, 0
	s_or_b32 s30, s26, 0x800
	s_mov_b32 m0, s30
	global_load_lds_dwordx4 v145, s[28:29]
	s_add_u32 s28, s4, 0xc000
	s_addc_u32 s29, s5, 0
	s_or_b32 s30, s26, 0xc00
	s_mov_b32 m0, s30
	global_load_lds_dwordx4 v185, s[28:29]
	s_add_u32 s28, s0, 0x4000
	s_mov_b32 m0, s27
	global_load_lds_dwordx4 v145, s[0:1]
	s_addc_u32 s29, s1, 0
	s_add_i32 s27, s26, 0x8400
	s_mov_b32 m0, s27
	global_load_lds_dwordx4 v185, s[28:29]
	s_add_u32 s28, s0, 0x8000
	s_addc_u32 s29, s1, 0
	s_add_i32 s27, s26, 0x8800
	s_mov_b32 m0, s27
	global_load_lds_dwordx4 v145, s[28:29]
	s_add_u32 s28, s0, 0xc000
	s_addc_u32 s29, s1, 0
	s_add_i32 s27, s26, 0x8c00
	s_mov_b32 m0, s27
	global_load_lds_dwordx4 v185, s[28:29]
.Lpf_skip_L0:
	s_sub_u32 s4, s4, s81
	s_subb_u32 s5, s5, 0
	s_sub_u32 s0, s0, s81
	s_subb_u32 s1, s1, 0
	s_add_u32 s27, s0, 0xc000
	s_addc_u32 s28, s1, 0
	s_add_u32 s29, s0, 0x8000
	s_addc_u32 s30, s1, 0
	s_add_u32 s31, s0, 0x4000
	s_addc_u32 s34, s1, 0
	s_add_u32 s35, s0, 0x0
	s_addc_u32 s36, s1, 0
	s_add_u32 s37, s4, 0xc000
	s_addc_u32 s39, s5, 0
	s_add_u32 s40, s4, 0x8000
	s_addc_u32 s42, s5, 0
	s_add_u32 s43, s4, 0x4000
	s_addc_u32 s44, s5, 0
	s_add_u32 s45, s4, 0x0
	s_addc_u32 s46, s5, 0
	s_mov_b64 s[0:1], 0
	s_mov_b32 s48, s17
	s_mov_b32 s47, s17
	v_mov_b32_e32 v0, v147
	v_mov_b32_e32 v1, v147
	v_mov_b32_e32 v2, v147
	v_mov_b32_e32 v3, v147
	v_mov_b32_e32 v4, v147
	v_mov_b32_e32 v5, v147
	v_mov_b32_e32 v6, v147
	v_mov_b32_e32 v7, v147
	v_mov_b32_e32 v8, v147
	v_mov_b32_e32 v9, v147
	v_mov_b32_e32 v10, v147
	v_mov_b32_e32 v11, v147
	v_mov_b32_e32 v12, v147
	v_mov_b32_e32 v13, v147
	v_mov_b32_e32 v14, v147
	v_mov_b32_e32 v15, v147
	v_mov_b32_e32 v16, v147
	v_mov_b32_e32 v17, v147
	v_mov_b32_e32 v18, v147
	v_mov_b32_e32 v19, v147
	v_mov_b32_e32 v20, v147
	v_mov_b32_e32 v21, v147
	v_mov_b32_e32 v22, v147
	v_mov_b32_e32 v23, v147
	v_mov_b32_e32 v24, v147
	v_mov_b32_e32 v25, v147
	v_mov_b32_e32 v26, v147
	v_mov_b32_e32 v27, v147
	v_mov_b32_e32 v28, v147
	v_mov_b32_e32 v29, v147
	v_mov_b32_e32 v30, v147
	v_mov_b32_e32 v31, v147
	v_mov_b32_e32 v32, v147
	v_mov_b32_e32 v33, v147
	v_mov_b32_e32 v34, v147
	v_mov_b32_e32 v35, v147
	v_mov_b32_e32 v36, v147
	v_mov_b32_e32 v37, v147
	v_mov_b32_e32 v38, v147
	v_mov_b32_e32 v39, v147
	v_mov_b32_e32 v40, v147
	v_mov_b32_e32 v41, v147
	v_mov_b32_e32 v42, v147
	v_mov_b32_e32 v43, v147
	v_mov_b32_e32 v44, v147
	v_mov_b32_e32 v45, v147
	v_mov_b32_e32 v46, v147
	v_mov_b32_e32 v47, v147
	v_mov_b32_e32 v48, v147
	v_mov_b32_e32 v49, v147
	v_mov_b32_e32 v50, v147
	v_mov_b32_e32 v51, v147
	v_mov_b32_e32 v52, v147
	v_mov_b32_e32 v53, v147
	v_mov_b32_e32 v54, v147
	v_mov_b32_e32 v55, v147
	v_mov_b32_e32 v56, v147
	v_mov_b32_e32 v57, v147
	v_mov_b32_e32 v58, v147
	v_mov_b32_e32 v59, v147
	v_mov_b32_e32 v60, v147
	v_mov_b32_e32 v61, v147
	v_mov_b32_e32 v62, v147
	v_mov_b32_e32 v63, v147
	v_mov_b32_e32 v64, v147
	v_mov_b32_e32 v65, v147
	v_mov_b32_e32 v66, v147
	v_mov_b32_e32 v67, v147
	v_mov_b32_e32 v68, v147
	v_mov_b32_e32 v69, v147
	v_mov_b32_e32 v70, v147
	v_mov_b32_e32 v71, v147
	v_mov_b32_e32 v72, v147
	v_mov_b32_e32 v73, v147
	v_mov_b32_e32 v74, v147
	v_mov_b32_e32 v75, v147
	v_mov_b32_e32 v76, v147
	v_mov_b32_e32 v77, v147
	v_mov_b32_e32 v78, v147
	v_mov_b32_e32 v79, v147
	v_mov_b32_e32 v80, v147
	v_mov_b32_e32 v81, v147
	v_mov_b32_e32 v82, v147
	v_mov_b32_e32 v83, v147
	v_mov_b32_e32 v84, v147
	v_mov_b32_e32 v85, v147
	v_mov_b32_e32 v86, v147
	v_mov_b32_e32 v87, v147
	v_mov_b32_e32 v88, v147
	v_mov_b32_e32 v89, v147
	v_mov_b32_e32 v90, v147
	v_mov_b32_e32 v91, v147
	v_mov_b32_e32 v92, v147
	v_mov_b32_e32 v93, v147
	v_mov_b32_e32 v94, v147
	v_mov_b32_e32 v95, v147
	v_mov_b32_e32 v96, v147
	v_mov_b32_e32 v97, v147
	v_mov_b32_e32 v98, v147
	v_mov_b32_e32 v99, v147
	v_mov_b32_e32 v100, v147
	v_mov_b32_e32 v101, v147
	v_mov_b32_e32 v102, v147
	v_mov_b32_e32 v103, v147
	v_mov_b32_e32 v104, v147
	v_mov_b32_e32 v105, v147
	v_mov_b32_e32 v106, v147
	v_mov_b32_e32 v107, v147
	v_mov_b32_e32 v108, v147
	v_mov_b32_e32 v109, v147
	v_mov_b32_e32 v110, v147
	v_mov_b32_e32 v111, v147
	v_mov_b32_e32 v112, v147
	v_mov_b32_e32 v113, v147
	v_mov_b32_e32 v114, v147
	v_mov_b32_e32 v115, v147
	v_mov_b32_e32 v116, v147
	v_mov_b32_e32 v117, v147
	v_mov_b32_e32 v118, v147
	v_mov_b32_e32 v119, v147
	v_mov_b32_e32 v120, v147
	v_mov_b32_e32 v121, v147
	v_mov_b32_e32 v122, v147
	v_mov_b32_e32 v123, v147
	v_mov_b32_e32 v124, v147
	v_mov_b32_e32 v125, v147
	v_mov_b32_e32 v126, v147
	v_mov_b32_e32 v127, v147
	s_cmp_eq_u32 s80, 1
	s_cbranch_scc0 .LBB0_131
	s_mov_b32 s80, 0
	s_waitcnt vmcnt(16)
	s_barrier
	s_branch .Lkin_L0

.Lkin_L0:
	s_cmp_lt_u32 s47, 15
	s_mov_b64 s[4:5], -1
	s_cbranch_scc1 .LBB0_133
	s_add_i32 s52, s48, 0x10000
	s_mov_b64 s[4:5], 0

.LBB0_135:
	s_mov_b32 s98, 0
	s_mov_b32 s99, s68
.Lpe_entry_L0:
	s_nop 7
	s_and_b32 s24, s99, 7
	s_lshl_b32 s24, s24, 3
	s_bfe_u32 s25, s99, 0x30003
	s_or_b32 s24, s24, s25
	s_lshr_b32 s25, s99, 6
	v_readfirstlane_b32 s26, v178
	v_readlane_b32 s72, v254, 0
	v_readlane_b32 s73, v254, 1
	s_lshr_b32 s26, s26, 6
	s_lshr_b32 s27, s26, 2
	s_and_b32 s28, s26, 3
	s_lshl_b32 s29, s24, 8
	s_lshl_b32 s30, s27, 7
	s_add_u32 s29, s29, s30
	s_lshl_b32 s30, s25, 8
	s_lshl_b32 s31, s28, 6
	s_add_u32 s30, s30, s31
	s_lshl_b32 s31, s29, 5
	s_add_u32 s94, s72, 0x1ad20000
	s_addc_u32 s95, s73, 0
	s_add_u32 s94, s94, s31
	s_addc_u32 s95, s95, 0
	v_and_b32_e32 v197, 31, v179
	v_lshrrev_b32_e32 v146, 5, v179
	v_lshlrev_b32_e32 v180, 5, v197
	v_lshlrev_b32_e32 v146, 4, v146
	global_load_dwordx4 v[128:131], v180, s[94:95] offset:0
	global_load_dwordx4 v[132:135], v180, s[94:95] offset:16
	global_load_dwordx4 v[136:139], v180, s[94:95] offset:1024
	global_load_dwordx4 v[140:143], v180, s[94:95] offset:1040
	global_load_dwordx4 v[164:167], v180, s[94:95] offset:2048
	global_load_dwordx4 v[168:171], v180, s[94:95] offset:2064
	global_load_dwordx4 v[246:249], v180, s[94:95] offset:3072
	global_load_dwordx4 v[250:253], v180, s[94:95] offset:3088
	s_mul_i32 s31, s29, 0x2200
	s_lshl_b32 s32, s30, 1
	s_add_u32 s31, s31, s32
	s_add_u32 s74, s72, 0xc120000
	s_addc_u32 s75, s73, 0
	s_add_u32 s74, s74, s31
	s_addc_u32 s75, s75, 0
	v_mul_u32_u24_e32 v181, 0x2200, v197
	v_add_u32_e32 v181, v181, v146
	s_sub_u32 s34, s25, 4
	s_cmp_lt_u32 s34, 2
	s_cbranch_scc1 .Lpe_vt_all_L0
	s_cmp_eq_u32 s25, 8
	s_cbranch_scc0 .Lpe_notv_L0
	s_barrier
	s_cmp_ge_u32 s28, 2
	s_cbranch_scc1 .Lpe_vt_L0
	s_branch .Lpe_notv_L0
.Lpe_vt_all_L0:
	s_barrier
	s_branch .Lpe_vt_L0
.Lpe_notv_L0:
	s_cmp_ge_u32 s25, 9
	s_cbranch_scc1 .Lpe_gates_L0
	s_lshr_b32 s34, s25, 1
	s_cmp_ge_u32 s25, 6
	s_cselect_b32 s35, 1, 0
	s_sub_u32 s34, s34, s35
	s_lshl_b32 s35, s98, 2
	s_add_u32 s35, s35, s34
	s_lshl_b32 s35, s35, 8
	v_readlane_b32 s82, v254, 14
	v_readlane_b32 s83, v254, 15
	s_add_u32 s82, s82, s35
	s_addc_u32 s83, s83, 0
	global_load_dwordx4 v[198:201], v146, s[82:83] offset:0
	global_load_dwordx4 v[202:205], v146, s[82:83] offset:32
	global_load_dwordx4 v[206:209], v146, s[82:83] offset:64
	global_load_dwordx4 v[210:213], v146, s[82:83] offset:96
	global_load_dwordx4 v[214:217], v146, s[82:83] offset:128
	global_load_dwordx4 v[218:221], v146, s[82:83] offset:160
	global_load_dwordx4 v[222:225], v146, s[82:83] offset:192
	global_load_dwordx4 v[226:229], v146, s[82:83] offset:224
	s_and_b32 s35, s34, 1
	s_cmp_eq_u32 s35, 0
	s_cselect_b32 s36, 0x3e000000, 1.0
	s_and_b32 s35, s29, 0x7ff
	s_lshl_b32 s35, s35, 7
	s_add_u32 s96, s72, 0x1ada0000
	s_addc_u32 s97, s73, 0
	s_add_u32 s96, s96, s35
	s_addc_u32 s97, s97, 0
	s_add_u32 s100, s96, 0x40000
	s_addc_u32 s101, s97, 0
	s_cmp_ge_u32 s34, 2
	s_cselect_b32 s37, 1, 0
	s_waitcnt vmcnt(8)
	v_lshlrev_b32_e32 v180, 7, v197
	v_add_u32_e32 v180, v180, v146
	v_mov_b32_e32 v197, 0x358637bd
	v_pk_add_f32 v[128:129], v[128:129], v[130:131]
	v_pk_add_f32 v[132:133], v[132:133], v[134:135]
	v_pk_add_f32 v[136:137], v[136:137], v[138:139]
	v_pk_add_f32 v[140:141], v[140:141], v[142:143]
	v_pk_add_f32 v[164:165], v[164:165], v[166:167]
	v_pk_add_f32 v[168:169], v[168:169], v[170:171]
	v_pk_add_f32 v[246:247], v[246:247], v[248:249]
	v_pk_add_f32 v[250:251], v[250:251], v[252:253]
	v_pk_add_f32 v[128:129], v[128:129], v[132:133]
	v_pk_add_f32 v[136:137], v[136:137], v[140:141]
	v_pk_add_f32 v[164:165], v[164:165], v[168:169]
	v_pk_add_f32 v[246:247], v[246:247], v[250:251]
	v_add_f32_e32 v128, v128, v129
	v_add_f32_e32 v136, v136, v137
	v_add_f32_e32 v164, v164, v165
	v_add_f32_e32 v246, v246, v247
	v_fmamk_f32 v128, v128, 0x3a800000, v197
	v_fmamk_f32 v136, v136, 0x3a800000, v197
	v_fmamk_f32 v164, v164, 0x3a800000, v197
	v_fmamk_f32 v246, v246, 0x3a800000, v197
	v_rsq_f32_e32 v172, v128
	v_rsq_f32_e32 v173, v136
	v_rsq_f32_e32 v174, v164
	v_rsq_f32_e32 v175, v246
	s_nop 0
	s_add_u32 s76, s99, s90
	s_cmp_lt_u32 s76, 0x440
	s_cselect_b32 s80, 1, 0
	s_cselect_b32 s83, 0x200000, 0
	s_lshl_b32 s76, s24, 19
	s_lshl_b32 s77, s26, 16
	s_add_u32 s76, s76, s77
	s_and_b32 s77, s24, 7
	s_lshl_b32 s77, s77, 8
	s_add_u32 s76, s76, s77
	s_add_u32 s78, s72, 0xa120000
	s_addc_u32 s79, s73, 0
	s_add_u32 s78, s78, s76
	s_addc_u32 s79, s79, 0
	s_lshl_b32 s76, s25, 19
	s_add_u32 s76, s76, s83
	s_add_u32 s76, s76, s77
	s_lshl_b32 s77, s26, 16
	s_add_u32 s76, s76, s77
	s_add_u32 s82, s72, 0x0
	s_addc_u32 s83, s73, 0
	s_add_u32 s82, s82, s76
	s_addc_u32 s83, s83, 0
	s_lshl_b32 s76, s26, 12
	s_mov_b32 m0, s76
	s_nop 0
	global_load_lds_dwordx4 v145, s[78:79]
	s_add_u32 s78, s78, 0x4000
	s_addc_u32 s79, s79, 0
	s_add_u32 s76, s76, 0x400
	s_mov_b32 m0, s76
	s_nop 0
	global_load_lds_dwordx4 v185, s[78:79]
	s_add_u32 s78, s78, 0x4000
	s_addc_u32 s79, s79, 0
	s_add_u32 s76, s76, 0x400
	s_mov_b32 m0, s76
	s_nop 0
	global_load_lds_dwordx4 v145, s[78:79]
	s_add_u32 s78, s78, 0x4000
	s_addc_u32 s79, s79, 0
	s_add_u32 s76, s76, 0x400
	s_mov_b32 m0, s76
	s_nop 0
	global_load_lds_dwordx4 v185, s[78:79]
	s_add_u32 s78, s78, 0x4000
	s_addc_u32 s79, s79, 0
	s_add_u32 s76, s76, 0x400
	s_add_u32 s76, s76, 0x7000
	s_mov_b32 m0, s76
	s_nop 0
	global_load_lds_dwordx4 v145, s[82:83]
	s_add_u32 s82, s82, 0x4000
	s_addc_u32 s83, s83, 0
	s_add_u32 s76, s76, 0x400
	s_mov_b32 m0, s76
	s_nop 0
	global_load_lds_dwordx4 v185, s[82:83]
	s_add_u32 s82, s82, 0x4000
	s_addc_u32 s83, s83, 0
	s_add_u32 s76, s76, 0x400
	s_mov_b32 m0, s76
	s_nop 0
	global_load_lds_dwordx4 v145, s[82:83]
	s_add_u32 s82, s82, 0x4000
	s_addc_u32 s83, s83, 0
	s_add_u32 s76, s76, 0x400
	s_mov_b32 m0, s76
	s_nop 0
	global_load_lds_dwordx4 v185, s[82:83]
	s_add_u32 s82, s82, 0x4000
	s_addc_u32 s83, s83, 0
	s_add_u32 s76, s76, 0x400
	s_cmp_eq_u32 s37, 0
	s_cbranch_scc1 .Lpe_norope_ld_L0
	global_load_dwordx4 v[230:233], v180, s[96:97] offset:0
	global_load_dwordx4 v[234:237], v180, s[96:97] offset:32
	global_load_dwordx4 v[238:241], v180, s[96:97] offset:64
	global_load_dwordx4 v[242:245], v180, s[96:97] offset:96
	global_load_dwordx4 v[148:151], v180, s[100:101] offset:0
	global_load_dwordx4 v[152:155], v180, s[100:101] offset:32
	global_load_dwordx4 v[156:159], v180, s[100:101] offset:64
	global_load_dwordx4 v[160:163], v180, s[100:101] offset:96
.Lpe_norope_ld_L0:
	v_pk_mul_f32 v[128:129], v[0:1], v[0:1]
	v_pk_mul_f32 v[130:131], v[16:17], v[16:17]
	v_pk_mul_f32 v[132:133], v[32:33], v[32:33]
	v_pk_mul_f32 v[134:135], v[48:49], v[48:49]
	v_pk_mul_f32 v[136:137], v[64:65], v[64:65]
	v_pk_mul_f32 v[138:139], v[80:81], v[80:81]
	v_pk_mul_f32 v[140:141], v[96:97], v[96:97]
	v_pk_mul_f32 v[142:143], v[112:113], v[112:113]
	v_pk_fma_f32 v[128:129], v[2:3], v[2:3], v[128:129]
	v_pk_fma_f32 v[130:131], v[18:19], v[18:19], v[130:131]
	v_pk_fma_f32 v[132:133], v[34:35], v[34:35], v[132:133]
	v_pk_fma_f32 v[134:135], v[50:51], v[50:51], v[134:135]
	v_pk_fma_f32 v[136:137], v[66:67], v[66:67], v[136:137]
	v_pk_fma_f32 v[138:139], v[82:83], v[82:83], v[138:139]
	v_pk_fma_f32 v[140:141], v[98:99], v[98:99], v[140:141]
	v_pk_fma_f32 v[142:143], v[114:115], v[114:115], v[142:143]
	v_pk_fma_f32 v[128:129], v[4:5], v[4:5], v[128:129]
	v_pk_fma_f32 v[130:131], v[20:21], v[20:21], v[130:131]
	v_pk_fma_f32 v[132:133], v[36:37], v[36:37], v[132:133]
	v_pk_fma_f32 v[134:135], v[52:53], v[52:53], v[134:135]
	v_pk_fma_f32 v[136:137], v[68:69], v[68:69], v[136:137]
	v_pk_fma_f32 v[138:139], v[84:85], v[84:85], v[138:139]
	v_pk_fma_f32 v[140:141], v[100:101], v[100:101], v[140:141]
	v_pk_fma_f32 v[142:143], v[116:117], v[116:117], v[142:143]
	v_pk_fma_f32 v[128:129], v[6:7], v[6:7], v[128:129]
	v_pk_fma_f32 v[130:131], v[22:23], v[22:23], v[130:131]
	v_pk_fma_f32 v[132:133], v[38:39], v[38:39], v[132:133]
	v_pk_fma_f32 v[134:135], v[54:55], v[54:55], v[134:135]
	v_pk_fma_f32 v[136:137], v[70:71], v[70:71], v[136:137]
	v_pk_fma_f32 v[138:139], v[86:87], v[86:87], v[138:139]
	v_pk_fma_f32 v[140:141], v[102:103], v[102:103], v[140:141]
	v_pk_fma_f32 v[142:143], v[118:119], v[118:119], v[142:143]
	v_pk_fma_f32 v[128:129], v[8:9], v[8:9], v[128:129]
	v_pk_fma_f32 v[130:131], v[24:25], v[24:25], v[130:131]
	v_pk_fma_f32 v[132:133], v[40:41], v[40:41], v[132:133]
	v_pk_fma_f32 v[134:135], v[56:57], v[56:57], v[134:135]
	v_pk_fma_f32 v[136:137], v[72:73], v[72:73], v[136:137]
	v_pk_fma_f32 v[138:139], v[88:89], v[88:89], v[138:139]
	v_pk_fma_f32 v[140:141], v[104:105], v[104:105], v[140:141]
	v_pk_fma_f32 v[142:143], v[120:121], v[120:121], v[142:143]
	v_pk_fma_f32 v[128:129], v[10:11], v[10:11], v[128:129]
	v_pk_fma_f32 v[130:131], v[26:27], v[26:27], v[130:131]
	v_pk_fma_f32 v[132:133], v[42:43], v[42:43], v[132:133]
	v_pk_fma_f32 v[134:135], v[58:59], v[58:59], v[134:135]
	v_pk_fma_f32 v[136:137], v[74:75], v[74:75], v[136:137]
	v_pk_fma_f32 v[138:139], v[90:91], v[90:91], v[138:139]
	v_pk_fma_f32 v[140:141], v[106:107], v[106:107], v[140:141]
	v_pk_fma_f32 v[142:143], v[122:123], v[122:123], v[142:143]
	v_pk_fma_f32 v[128:129], v[12:13], v[12:13], v[128:129]
	v_pk_fma_f32 v[130:131], v[28:29], v[28:29], v[130:131]
	v_pk_fma_f32 v[132:133], v[44:45], v[44:45], v[132:133]
	v_pk_fma_f32 v[134:135], v[60:61], v[60:61], v[134:135]
	v_pk_fma_f32 v[136:137], v[76:77], v[76:77], v[136:137]
	v_pk_fma_f32 v[138:139], v[92:93], v[92:93], v[138:139]
	v_pk_fma_f32 v[140:141], v[108:109], v[108:109], v[140:141]
	v_pk_fma_f32 v[142:143], v[124:125], v[124:125], v[142:143]
	v_pk_fma_f32 v[128:129], v[14:15], v[14:15], v[128:129]
	v_pk_fma_f32 v[130:131], v[30:31], v[30:31], v[130:131]
	v_pk_fma_f32 v[132:133], v[46:47], v[46:47], v[132:133]
	v_pk_fma_f32 v[134:135], v[62:63], v[62:63], v[134:135]
	v_pk_fma_f32 v[136:137], v[78:79], v[78:79], v[136:137]
	v_pk_fma_f32 v[138:139], v[94:95], v[94:95], v[138:139]
	v_pk_fma_f32 v[140:141], v[110:111], v[110:111], v[140:141]
	v_pk_fma_f32 v[142:143], v[126:127], v[126:127], v[142:143]
	v_pk_add_f32 v[128:129], v[128:129], v[130:131]
	v_pk_add_f32 v[132:133], v[132:133], v[134:135]
	v_pk_add_f32 v[136:137], v[136:137], v[138:139]
	v_pk_add_f32 v[140:141], v[140:141], v[142:143]
	v_add_f32_e32 v164, v128, v129
	v_add_f32_e32 v165, v132, v133
	v_add_f32_e32 v166, v136, v137
	v_add_f32_e32 v167, v140, v141
	v_mov_b32_e32 v168, v164
	v_mov_b32_e32 v169, v165
	v_mov_b32_e32 v170, v166
	v_mov_b32_e32 v171, v167
	s_nop 1
	v_permlane32_swap_b32_e32 v168, v164
	v_permlane32_swap_b32_e32 v169, v165
	v_permlane32_swap_b32_e32 v170, v166
	v_permlane32_swap_b32_e32 v171, v167
	v_add_f32_e32 v164, v164, v168
	v_add_f32_e32 v165, v165, v169
	v_add_f32_e32 v166, v166, v170
	v_add_f32_e32 v167, v167, v171
	v_mul_f32_e32 v168, v172, v172
	v_mul_f32_e32 v169, v173, v173
	v_mul_f32_e32 v170, v174, v174
	v_mul_f32_e32 v171, v175, v175
	v_mul_f32_e32 v168, v168, v164
	v_mul_f32_e32 v169, v169, v165
	v_mul_f32_e32 v170, v170, v166
	v_mul_f32_e32 v171, v171, v167
	v_fmamk_f32 v168, v168, 0x3c800000, v197
	v_fmamk_f32 v169, v169, 0x3c800000, v197
	v_fmamk_f32 v170, v170, 0x3c800000, v197
	v_fmamk_f32 v171, v171, 0x3c800000, v197
	v_rsq_f32_e32 v168, v168
	v_rsq_f32_e32 v169, v169
	v_rsq_f32_e32 v170, v170
	v_rsq_f32_e32 v171, v171
	s_nop 0
	v_mul_f32_e32 v172, v172, v168
	v_mul_f32_e32 v173, v173, v169
	v_mul_f32_e32 v174, v174, v170
	v_mul_f32_e32 v175, v175, v171
	v_mul_f32_e32 v172, s36, v172
	v_mul_f32_e32 v173, s36, v173
	v_mul_f32_e32 v174, s36, v174
	v_mul_f32_e32 v175, s36, v175
	v_pk_mul_f32 v[0:1], v[0:1], v[172:173] op_sel_hi:[1,0]
	v_pk_mul_f32 v[2:3], v[2:3], v[172:173] op_sel_hi:[1,0]
	v_pk_mul_f32 v[4:5], v[4:5], v[172:173] op_sel_hi:[1,0]
	v_pk_mul_f32 v[6:7], v[6:7], v[172:173] op_sel_hi:[1,0]
	v_pk_mul_f32 v[8:9], v[8:9], v[172:173] op_sel_hi:[1,0]
	v_pk_mul_f32 v[10:11], v[10:11], v[172:173] op_sel_hi:[1,0]
	v_pk_mul_f32 v[12:13], v[12:13], v[172:173] op_sel_hi:[1,0]
	v_pk_mul_f32 v[14:15], v[14:15], v[172:173] op_sel_hi:[1,0]
	v_pk_mul_f32 v[16:17], v[16:17], v[172:173] op_sel_hi:[1,0]
	v_pk_mul_f32 v[18:19], v[18:19], v[172:173] op_sel_hi:[1,0]
	v_pk_mul_f32 v[20:21], v[20:21], v[172:173] op_sel_hi:[1,0]
	v_pk_mul_f32 v[22:23], v[22:23], v[172:173] op_sel_hi:[1,0]
	v_pk_mul_f32 v[24:25], v[24:25], v[172:173] op_sel_hi:[1,0]
	v_pk_mul_f32 v[26:27], v[26:27], v[172:173] op_sel_hi:[1,0]
	v_pk_mul_f32 v[28:29], v[28:29], v[172:173] op_sel_hi:[1,0]
	v_pk_mul_f32 v[30:31], v[30:31], v[172:173] op_sel_hi:[1,0]
	s_cmp_eq_u32 s37, 0
	s_cbranch_scc1 .Lpe_wg_norope_L0
	s_waitcnt vmcnt(16)
	s_branch .Lpe_wg_done_L0
.Lpe_wg_norope_L0:
	s_waitcnt vmcnt(8)

.Lpe_gates_L0:
	s_lshl_b32 s35, s98, 11
	s_add_u32 s35, s35, s30
	s_sub_u32 s35, s35, 0x900
	s_lshl_b32 s35, s35, 2
	v_readlane_b32 s82, v254, 12
	v_readlane_b32 s83, v254, 13
	s_add_u32 s82, s82, s35
	s_addc_u32 s83, s83, 0
	global_load_dwordx4 v[198:201], v146, s[82:83] offset:0
	global_load_dwordx4 v[202:205], v146, s[82:83] offset:32
	global_load_dwordx4 v[206:209], v146, s[82:83] offset:64
	global_load_dwordx4 v[210:213], v146, s[82:83] offset:96
	global_load_dwordx4 v[214:217], v146, s[82:83] offset:128
	global_load_dwordx4 v[218:221], v146, s[82:83] offset:160
	global_load_dwordx4 v[222:225], v146, s[82:83] offset:192
	global_load_dwordx4 v[226:229], v146, s[82:83] offset:224
	s_waitcnt vmcnt(8)
	v_mov_b32_e32 v197, 0x358637bd
	v_pk_add_f32 v[128:129], v[128:129], v[130:131]
	v_pk_add_f32 v[132:133], v[132:133], v[134:135]
	v_pk_add_f32 v[136:137], v[136:137], v[138:139]
	v_pk_add_f32 v[140:141], v[140:141], v[142:143]
	v_pk_add_f32 v[164:165], v[164:165], v[166:167]
	v_pk_add_f32 v[168:169], v[168:169], v[170:171]
	v_pk_add_f32 v[246:247], v[246:247], v[248:249]
	v_pk_add_f32 v[250:251], v[250:251], v[252:253]
	v_pk_add_f32 v[128:129], v[128:129], v[132:133]
	v_pk_add_f32 v[136:137], v[136:137], v[140:141]
	v_pk_add_f32 v[164:165], v[164:165], v[168:169]
	v_pk_add_f32 v[246:247], v[246:247], v[250:251]
	v_add_f32_e32 v128, v128, v129
	v_add_f32_e32 v136, v136, v137
	v_add_f32_e32 v164, v164, v165
	v_add_f32_e32 v246, v246, v247
	v_fmamk_f32 v128, v128, 0x3a800000, v197
	v_fmamk_f32 v136, v136, 0x3a800000, v197
	v_fmamk_f32 v164, v164, 0x3a800000, v197
	v_fmamk_f32 v246, v246, 0x3a800000, v197
	v_rsq_f32_e32 v172, v128
	v_rsq_f32_e32 v173, v136
	v_rsq_f32_e32 v174, v164
	v_rsq_f32_e32 v175, v246
	s_nop 0
	s_add_u32 s76, s99, s90
	s_cmp_lt_u32 s76, 0x440
	s_cselect_b32 s80, 1, 0
	s_cselect_b32 s83, 0x200000, 0
	s_lshl_b32 s76, s24, 19
	s_lshl_b32 s77, s26, 16
	s_add_u32 s76, s76, s77
	s_and_b32 s77, s24, 7
	s_lshl_b32 s77, s77, 8
	s_add_u32 s76, s76, s77
	s_add_u32 s78, s72, 0xa120000
	s_addc_u32 s79, s73, 0
	s_add_u32 s78, s78, s76
	s_addc_u32 s79, s79, 0
	s_lshl_b32 s76, s25, 19
	s_add_u32 s76, s76, s83
	s_add_u32 s76, s76, s77
	s_lshl_b32 s77, s26, 16
	s_add_u32 s76, s76, s77
	s_add_u32 s82, s72, 0x0
	s_addc_u32 s83, s73, 0
	s_add_u32 s82, s82, s76
	s_addc_u32 s83, s83, 0
	s_lshl_b32 s76, s26, 12
	s_mov_b32 m0, s76
	s_nop 0
	global_load_lds_dwordx4 v145, s[78:79]
	s_add_u32 s78, s78, 0x4000
	s_addc_u32 s79, s79, 0
	s_add_u32 s76, s76, 0x400
	s_mov_b32 m0, s76
	s_nop 0
	global_load_lds_dwordx4 v185, s[78:79]
	s_add_u32 s78, s78, 0x4000
	s_addc_u32 s79, s79, 0
	s_add_u32 s76, s76, 0x400
	s_mov_b32 m0, s76
	s_nop 0
	global_load_lds_dwordx4 v145, s[78:79]
	s_add_u32 s78, s78, 0x4000
	s_addc_u32 s79, s79, 0
	s_add_u32 s76, s76, 0x400
	s_mov_b32 m0, s76
	s_nop 0
	global_load_lds_dwordx4 v185, s[78:79]
	s_add_u32 s78, s78, 0x4000
	s_addc_u32 s79, s79, 0
	s_add_u32 s76, s76, 0x400
	s_add_u32 s76, s76, 0x7000
	s_mov_b32 m0, s76
	s_nop 0
	global_load_lds_dwordx4 v145, s[82:83]
	s_add_u32 s82, s82, 0x4000
	s_addc_u32 s83, s83, 0
	s_add_u32 s76, s76, 0x400
	s_mov_b32 m0, s76
	s_nop 0
	global_load_lds_dwordx4 v185, s[82:83]
	s_add_u32 s82, s82, 0x4000
	s_addc_u32 s83, s83, 0
	s_add_u32 s76, s76, 0x400
	s_mov_b32 m0, s76
	s_nop 0
	global_load_lds_dwordx4 v145, s[82:83]
	s_add_u32 s82, s82, 0x4000
	s_addc_u32 s83, s83, 0
	s_add_u32 s76, s76, 0x400
	s_mov_b32 m0, s76
	s_nop 0
	global_load_lds_dwordx4 v185, s[82:83]
	s_add_u32 s82, s82, 0x4000
	s_addc_u32 s83, s83, 0
	s_add_u32 s76, s76, 0x400
	v_mul_f32_e32 v172, 0xbfb8aa3b, v172
	v_mul_f32_e32 v173, 0xbfb8aa3b, v173
	v_mul_f32_e32 v174, 0xbfb8aa3b, v174
	v_mul_f32_e32 v175, 0xbfb8aa3b, v175
	s_waitcnt vmcnt(8)
	v_mul_f32_e32 v198, 0xbfb8aa3b, v198
	v_mul_f32_e32 v199, 0xbfb8aa3b, v199
	v_mul_f32_e32 v200, 0xbfb8aa3b, v200
	v_mul_f32_e32 v201, 0xbfb8aa3b, v201
	v_mul_f32_e32 v202, 0xbfb8aa3b, v202
	v_mul_f32_e32 v203, 0xbfb8aa3b, v203
	v_mul_f32_e32 v204, 0xbfb8aa3b, v204
	v_mul_f32_e32 v205, 0xbfb8aa3b, v205
	v_mul_f32_e32 v206, 0xbfb8aa3b, v206
	v_mul_f32_e32 v207, 0xbfb8aa3b, v207
	v_mul_f32_e32 v208, 0xbfb8aa3b, v208
	v_mul_f32_e32 v209, 0xbfb8aa3b, v209
	v_mul_f32_e32 v210, 0xbfb8aa3b, v210
	v_mul_f32_e32 v211, 0xbfb8aa3b, v211
	v_mul_f32_e32 v212, 0xbfb8aa3b, v212
	v_mul_f32_e32 v213, 0xbfb8aa3b, v213
	v_mul_f32_e32 v214, 0xbfb8aa3b, v214
	v_mul_f32_e32 v215, 0xbfb8aa3b, v215
	v_mul_f32_e32 v216, 0xbfb8aa3b, v216
	v_mul_f32_e32 v217, 0xbfb8aa3b, v217
	v_mul_f32_e32 v218, 0xbfb8aa3b, v218
	v_mul_f32_e32 v219, 0xbfb8aa3b, v219
	v_mul_f32_e32 v220, 0xbfb8aa3b, v220
	v_mul_f32_e32 v221, 0xbfb8aa3b, v221
	v_mul_f32_e32 v222, 0xbfb8aa3b, v222
	v_mul_f32_e32 v223, 0xbfb8aa3b, v223
	v_mul_f32_e32 v224, 0xbfb8aa3b, v224
	v_mul_f32_e32 v225, 0xbfb8aa3b, v225
	v_mul_f32_e32 v226, 0xbfb8aa3b, v226
	v_mul_f32_e32 v227, 0xbfb8aa3b, v227
	v_mul_f32_e32 v228, 0xbfb8aa3b, v228
	v_mul_f32_e32 v229, 0xbfb8aa3b, v229
	v_pk_fma_f32 v[0:1], v[0:1], v[172:173], v[198:199] op_sel_hi:[1,0,1]
	v_pk_fma_f32 v[2:3], v[2:3], v[172:173], v[200:201] op_sel_hi:[1,0,1]
	v_pk_fma_f32 v[4:5], v[4:5], v[172:173], v[202:203] op_sel_hi:[1,0,1]
	v_pk_fma_f32 v[6:7], v[6:7], v[172:173], v[204:205] op_sel_hi:[1,0,1]
	v_pk_fma_f32 v[8:9], v[8:9], v[172:173], v[206:207] op_sel_hi:[1,0,1]
	v_pk_fma_f32 v[10:11], v[10:11], v[172:173], v[208:209] op_sel_hi:[1,0,1]
	v_pk_fma_f32 v[12:13], v[12:13], v[172:173], v[210:211] op_sel_hi:[1,0,1]
	v_pk_fma_f32 v[14:15], v[14:15], v[172:173], v[212:213] op_sel_hi:[1,0,1]
	v_pk_fma_f32 v[16:17], v[16:17], v[172:173], v[214:215] op_sel_hi:[1,0,1]
	v_pk_fma_f32 v[18:19], v[18:19], v[172:173], v[216:217] op_sel_hi:[1,0,1]
	v_pk_fma_f32 v[20:21], v[20:21], v[172:173], v[218:219] op_sel_hi:[1,0,1]
	v_pk_fma_f32 v[22:23], v[22:23], v[172:173], v[220:221] op_sel_hi:[1,0,1]
	v_pk_fma_f32 v[24:25], v[24:25], v[172:173], v[222:223] op_sel_hi:[1,0,1]
	v_pk_fma_f32 v[26:27], v[26:27], v[172:173], v[224:225] op_sel_hi:[1,0,1]
	v_pk_fma_f32 v[28:29], v[28:29], v[172:173], v[226:227] op_sel_hi:[1,0,1]
	v_pk_fma_f32 v[30:31], v[30:31], v[172:173], v[228:229] op_sel_hi:[1,0,1]
	v_exp_f32_e32 v0, v0
	v_exp_f32_e32 v1, v1
	v_exp_f32_e32 v2, v2
	v_exp_f32_e32 v3, v3
	v_exp_f32_e32 v4, v4
	v_exp_f32_e32 v5, v5
	v_exp_f32_e32 v6, v6
	v_exp_f32_e32 v7, v7
	v_exp_f32_e32 v8, v8
	v_exp_f32_e32 v9, v9
	v_exp_f32_e32 v10, v10
	v_exp_f32_e32 v11, v11
	v_exp_f32_e32 v12, v12
	v_exp_f32_e32 v13, v13
	v_exp_f32_e32 v14, v14
	v_exp_f32_e32 v15, v15
	v_exp_f32_e32 v16, v16
	v_exp_f32_e32 v17, v17
	v_exp_f32_e32 v18, v18
	v_exp_f32_e32 v19, v19
	v_exp_f32_e32 v20, v20
	v_exp_f32_e32 v21, v21
	v_exp_f32_e32 v22, v22
	v_exp_f32_e32 v23, v23
	v_exp_f32_e32 v24, v24
	v_exp_f32_e32 v25, v25
	v_exp_f32_e32 v26, v26
	v_exp_f32_e32 v27, v27
	v_exp_f32_e32 v28, v28
	v_exp_f32_e32 v29, v29
	v_exp_f32_e32 v30, v30
	v_exp_f32_e32 v31, v31
	v_pk_add_f32 v[0:1], v[0:1], 1.0 op_sel_hi:[1,0]
	v_pk_add_f32 v[2:3], v[2:3], 1.0 op_sel_hi:[1,0]
	v_pk_add_f32 v[4:5], v[4:5], 1.0 op_sel_hi:[1,0]
	v_pk_add_f32 v[6:7], v[6:7], 1.0 op_sel_hi:[1,0]
	v_pk_add_f32 v[8:9], v[8:9], 1.0 op_sel_hi:[1,0]
	v_pk_add_f32 v[10:11], v[10:11], 1.0 op_sel_hi:[1,0]
	v_pk_add_f32 v[12:13], v[12:13], 1.0 op_sel_hi:[1,0]
	v_pk_add_f32 v[14:15], v[14:15], 1.0 op_sel_hi:[1,0]
	v_pk_add_f32 v[16:17], v[16:17], 1.0 op_sel_hi:[1,0]
	v_pk_add_f32 v[18:19], v[18:19], 1.0 op_sel_hi:[1,0]
	v_pk_add_f32 v[20:21], v[20:21], 1.0 op_sel_hi:[1,0]
	v_pk_add_f32 v[22:23], v[22:23], 1.0 op_sel_hi:[1,0]
	v_pk_add_f32 v[24:25], v[24:25], 1.0 op_sel_hi:[1,0]
	v_pk_add_f32 v[26:27], v[26:27], 1.0 op_sel_hi:[1,0]
	v_pk_add_f32 v[28:29], v[28:29], 1.0 op_sel_hi:[1,0]
	v_pk_add_f32 v[30:31], v[30:31], 1.0 op_sel_hi:[1,0]
	v_rcp_f32_e32 v0, v0
	v_rcp_f32_e32 v1, v1
	v_rcp_f32_e32 v2, v2
	v_rcp_f32_e32 v3, v3
	v_rcp_f32_e32 v4, v4
	v_rcp_f32_e32 v5, v5
	v_rcp_f32_e32 v6, v6
	v_rcp_f32_e32 v7, v7
	v_rcp_f32_e32 v8, v8
	v_rcp_f32_e32 v9, v9
	v_rcp_f32_e32 v10, v10
	v_rcp_f32_e32 v11, v11
	v_rcp_f32_e32 v12, v12
	v_rcp_f32_e32 v13, v13
	v_rcp_f32_e32 v14, v14
	v_rcp_f32_e32 v15, v15
	v_rcp_f32_e32 v16, v16
	v_rcp_f32_e32 v17, v17
	v_rcp_f32_e32 v18, v18
	v_rcp_f32_e32 v19, v19
	v_rcp_f32_e32 v20, v20
	v_rcp_f32_e32 v21, v21
	v_rcp_f32_e32 v22, v22
	v_rcp_f32_e32 v23, v23
	v_rcp_f32_e32 v24, v24
	v_rcp_f32_e32 v25, v25
	v_rcp_f32_e32 v26, v26
	v_rcp_f32_e32 v27, v27
	v_rcp_f32_e32 v28, v28
	v_rcp_f32_e32 v29, v29
	v_rcp_f32_e32 v30, v30
	v_rcp_f32_e32 v31, v31
	s_nop 0
	v_cvt_pk_bf16_f32 v0, v0, v1
	v_cvt_pk_bf16_f32 v1, v2, v3
	v_cvt_pk_bf16_f32 v2, v4, v5
	v_cvt_pk_bf16_f32 v3, v6, v7
	v_cvt_pk_bf16_f32 v4, v8, v9
	v_cvt_pk_bf16_f32 v5, v10, v11
	v_cvt_pk_bf16_f32 v6, v12, v13
	v_cvt_pk_bf16_f32 v7, v14, v15
	v_cvt_pk_bf16_f32 v16, v16, v17
	v_cvt_pk_bf16_f32 v17, v18, v19
	v_cvt_pk_bf16_f32 v18, v20, v21
	v_cvt_pk_bf16_f32 v19, v22, v23
	v_cvt_pk_bf16_f32 v20, v24, v25
	v_cvt_pk_bf16_f32 v21, v26, v27
	v_cvt_pk_bf16_f32 v22, v28, v29
	v_cvt_pk_bf16_f32 v23, v30, v31
	v_permlane32_swap_b32_e32 v0, v2
	v_permlane32_swap_b32_e32 v1, v3
	v_permlane32_swap_b32_e32 v4, v6
	v_permlane32_swap_b32_e32 v5, v7
	v_permlane32_swap_b32_e32 v16, v18
	v_permlane32_swap_b32_e32 v17, v19
	v_permlane32_swap_b32_e32 v20, v22
	v_permlane32_swap_b32_e32 v21, v23
	global_store_dwordx4 v181, v[0:3], s[74:75] offset:0
	global_store_dwordx4 v181, v[4:7], s[74:75] offset:32
	global_store_dwordx4 v181, v[16:19], s[74:75] offset:64
	global_store_dwordx4 v181, v[20:23], s[74:75] offset:96
	s_add_u32 s74, s74, 0x44000
	s_addc_u32 s75, s75, 0
	v_pk_fma_f32 v[32:33], v[32:33], v[172:173], v[198:199] op_sel:[0,1,0] op_sel_hi:[1,1,1]
	v_pk_fma_f32 v[34:35], v[34:35], v[172:173], v[200:201] op_sel:[0,1,0] op_sel_hi:[1,1,1]
	v_pk_fma_f32 v[36:37], v[36:37], v[172:173], v[202:203] op_sel:[0,1,0] op_sel_hi:[1,1,1]
	v_pk_fma_f32 v[38:39], v[38:39], v[172:173], v[204:205] op_sel:[0,1,0] op_sel_hi:[1,1,1]
	v_pk_fma_f32 v[40:41], v[40:41], v[172:173], v[206:207] op_sel:[0,1,0] op_sel_hi:[1,1,1]
	v_pk_fma_f32 v[42:43], v[42:43], v[172:173], v[208:209] op_sel:[0,1,0] op_sel_hi:[1,1,1]
	v_pk_fma_f32 v[44:45], v[44:45], v[172:173], v[210:211] op_sel:[0,1,0] op_sel_hi:[1,1,1]
	v_pk_fma_f32 v[46:47], v[46:47], v[172:173], v[212:213] op_sel:[0,1,0] op_sel_hi:[1,1,1]
	v_pk_fma_f32 v[48:49], v[48:49], v[172:173], v[214:215] op_sel:[0,1,0] op_sel_hi:[1,1,1]
	v_pk_fma_f32 v[50:51], v[50:51], v[172:173], v[216:217] op_sel:[0,1,0] op_sel_hi:[1,1,1]
	v_pk_fma_f32 v[52:53], v[52:53], v[172:173], v[218:219] op_sel:[0,1,0] op_sel_hi:[1,1,1]
	v_pk_fma_f32 v[54:55], v[54:55], v[172:173], v[220:221] op_sel:[0,1,0] op_sel_hi:[1,1,1]
	v_pk_fma_f32 v[56:57], v[56:57], v[172:173], v[222:223] op_sel:[0,1,0] op_sel_hi:[1,1,1]
	v_pk_fma_f32 v[58:59], v[58:59], v[172:173], v[224:225] op_sel:[0,1,0] op_sel_hi:[1,1,1]
	v_pk_fma_f32 v[60:61], v[60:61], v[172:173], v[226:227] op_sel:[0,1,0] op_sel_hi:[1,1,1]
	v_pk_fma_f32 v[62:63], v[62:63], v[172:173], v[228:229] op_sel:[0,1,0] op_sel_hi:[1,1,1]
	v_exp_f32_e32 v32, v32
	v_exp_f32_e32 v33, v33
	v_exp_f32_e32 v34, v34
	v_exp_f32_e32 v35, v35
	v_exp_f32_e32 v36, v36
	v_exp_f32_e32 v37, v37
	v_exp_f32_e32 v38, v38
	v_exp_f32_e32 v39, v39
	v_exp_f32_e32 v40, v40
	v_exp_f32_e32 v41, v41
	v_exp_f32_e32 v42, v42
	v_exp_f32_e32 v43, v43
	v_exp_f32_e32 v44, v44
	v_exp_f32_e32 v45, v45
	v_exp_f32_e32 v46, v46
	v_exp_f32_e32 v47, v47
	v_exp_f32_e32 v48, v48
	v_exp_f32_e32 v49, v49
	v_exp_f32_e32 v50, v50
	v_exp_f32_e32 v51, v51
	v_exp_f32_e32 v52, v52
	v_exp_f32_e32 v53, v53
	v_exp_f32_e32 v54, v54
	v_exp_f32_e32 v55, v55
	v_exp_f32_e32 v56, v56
	v_exp_f32_e32 v57, v57
	v_exp_f32_e32 v58, v58
	v_exp_f32_e32 v59, v59
	v_exp_f32_e32 v60, v60
	v_exp_f32_e32 v61, v61
	v_exp_f32_e32 v62, v62
	v_exp_f32_e32 v63, v63
	v_pk_add_f32 v[32:33], v[32:33], 1.0 op_sel_hi:[1,0]
	v_pk_add_f32 v[34:35], v[34:35], 1.0 op_sel_hi:[1,0]
	v_pk_add_f32 v[36:37], v[36:37], 1.0 op_sel_hi:[1,0]
	v_pk_add_f32 v[38:39], v[38:39], 1.0 op_sel_hi:[1,0]
	v_pk_add_f32 v[40:41], v[40:41], 1.0 op_sel_hi:[1,0]
	v_pk_add_f32 v[42:43], v[42:43], 1.0 op_sel_hi:[1,0]
	v_pk_add_f32 v[44:45], v[44:45], 1.0 op_sel_hi:[1,0]
	v_pk_add_f32 v[46:47], v[46:47], 1.0 op_sel_hi:[1,0]
	v_pk_add_f32 v[48:49], v[48:49], 1.0 op_sel_hi:[1,0]
	v_pk_add_f32 v[50:51], v[50:51], 1.0 op_sel_hi:[1,0]
	v_pk_add_f32 v[52:53], v[52:53], 1.0 op_sel_hi:[1,0]
	v_pk_add_f32 v[54:55], v[54:55], 1.0 op_sel_hi:[1,0]
	v_pk_add_f32 v[56:57], v[56:57], 1.0 op_sel_hi:[1,0]
	v_pk_add_f32 v[58:59], v[58:59], 1.0 op_sel_hi:[1,0]
	v_pk_add_f32 v[60:61], v[60:61], 1.0 op_sel_hi:[1,0]
	v_pk_add_f32 v[62:63], v[62:63], 1.0 op_sel_hi:[1,0]
	v_rcp_f32_e32 v32, v32
	v_rcp_f32_e32 v33, v33
	v_rcp_f32_e32 v34, v34
	v_rcp_f32_e32 v35, v35
	v_rcp_f32_e32 v36, v36
	v_rcp_f32_e32 v37, v37
	v_rcp_f32_e32 v38, v38
	v_rcp_f32_e32 v39, v39
	v_rcp_f32_e32 v40, v40
	v_rcp_f32_e32 v41, v41
	v_rcp_f32_e32 v42, v42
	v_rcp_f32_e32 v43, v43
	v_rcp_f32_e32 v44, v44
	v_rcp_f32_e32 v45, v45
	v_rcp_f32_e32 v46, v46
	v_rcp_f32_e32 v47, v47
	v_rcp_f32_e32 v48, v48
	v_rcp_f32_e32 v49, v49
	v_rcp_f32_e32 v50, v50
	v_rcp_f32_e32 v51, v51
	v_rcp_f32_e32 v52, v52
	v_rcp_f32_e32 v53, v53
	v_rcp_f32_e32 v54, v54
	v_rcp_f32_e32 v55, v55
	v_rcp_f32_e32 v56, v56
	v_rcp_f32_e32 v57, v57
	v_rcp_f32_e32 v58, v58
	v_rcp_f32_e32 v59, v59
	v_rcp_f32_e32 v60, v60
	v_rcp_f32_e32 v61, v61
	v_rcp_f32_e32 v62, v62
	v_rcp_f32_e32 v63, v63
	s_nop 0
	v_cvt_pk_bf16_f32 v32, v32, v33
	v_cvt_pk_bf16_f32 v33, v34, v35
	v_cvt_pk_bf16_f32 v34, v36, v37
	v_cvt_pk_bf16_f32 v35, v38, v39
	v_cvt_pk_bf16_f32 v36, v40, v41
	v_cvt_pk_bf16_f32 v37, v42, v43
	v_cvt_pk_bf16_f32 v38, v44, v45
	v_cvt_pk_bf16_f32 v39, v46, v47
	v_cvt_pk_bf16_f32 v48, v48, v49
	v_cvt_pk_bf16_f32 v49, v50, v51
	v_cvt_pk_bf16_f32 v50, v52, v53
	v_cvt_pk_bf16_f32 v51, v54, v55
	v_cvt_pk_bf16_f32 v52, v56, v57
	v_cvt_pk_bf16_f32 v53, v58, v59
	v_cvt_pk_bf16_f32 v54, v60, v61
	v_cvt_pk_bf16_f32 v55, v62, v63
	v_permlane32_swap_b32_e32 v32, v34
	v_permlane32_swap_b32_e32 v33, v35
	v_permlane32_swap_b32_e32 v36, v38
	v_permlane32_swap_b32_e32 v37, v39
	v_permlane32_swap_b32_e32 v48, v50
	v_permlane32_swap_b32_e32 v49, v51
	v_permlane32_swap_b32_e32 v52, v54
	v_permlane32_swap_b32_e32 v53, v55
	global_store_dwordx4 v181, v[32:35], s[74:75] offset:0
	global_store_dwordx4 v181, v[36:39], s[74:75] offset:32
	global_store_dwordx4 v181, v[48:51], s[74:75] offset:64
	global_store_dwordx4 v181, v[52:55], s[74:75] offset:96
	s_add_u32 s74, s74, 0x44000
	s_addc_u32 s75, s75, 0
	v_pk_fma_f32 v[64:65], v[64:65], v[174:175], v[198:199] op_sel_hi:[1,0,1]
	v_pk_fma_f32 v[66:67], v[66:67], v[174:175], v[200:201] op_sel_hi:[1,0,1]
	v_pk_fma_f32 v[68:69], v[68:69], v[174:175], v[202:203] op_sel_hi:[1,0,1]
	v_pk_fma_f32 v[70:71], v[70:71], v[174:175], v[204:205] op_sel_hi:[1,0,1]
	v_pk_fma_f32 v[72:73], v[72:73], v[174:175], v[206:207] op_sel_hi:[1,0,1]
	v_pk_fma_f32 v[74:75], v[74:75], v[174:175], v[208:209] op_sel_hi:[1,0,1]
	v_pk_fma_f32 v[76:77], v[76:77], v[174:175], v[210:211] op_sel_hi:[1,0,1]
	v_pk_fma_f32 v[78:79], v[78:79], v[174:175], v[212:213] op_sel_hi:[1,0,1]
	v_pk_fma_f32 v[80:81], v[80:81], v[174:175], v[214:215] op_sel_hi:[1,0,1]
	v_pk_fma_f32 v[82:83], v[82:83], v[174:175], v[216:217] op_sel_hi:[1,0,1]
	v_pk_fma_f32 v[84:85], v[84:85], v[174:175], v[218:219] op_sel_hi:[1,0,1]
	v_pk_fma_f32 v[86:87], v[86:87], v[174:175], v[220:221] op_sel_hi:[1,0,1]
	v_pk_fma_f32 v[88:89], v[88:89], v[174:175], v[222:223] op_sel_hi:[1,0,1]
	v_pk_fma_f32 v[90:91], v[90:91], v[174:175], v[224:225] op_sel_hi:[1,0,1]
	v_pk_fma_f32 v[92:93], v[92:93], v[174:175], v[226:227] op_sel_hi:[1,0,1]
	v_pk_fma_f32 v[94:95], v[94:95], v[174:175], v[228:229] op_sel_hi:[1,0,1]
	v_exp_f32_e32 v64, v64
	v_exp_f32_e32 v65, v65
	v_exp_f32_e32 v66, v66
	v_exp_f32_e32 v67, v67
	v_exp_f32_e32 v68, v68
	v_exp_f32_e32 v69, v69
	v_exp_f32_e32 v70, v70
	v_exp_f32_e32 v71, v71
	v_exp_f32_e32 v72, v72
	v_exp_f32_e32 v73, v73
	v_exp_f32_e32 v74, v74
	v_exp_f32_e32 v75, v75
	v_exp_f32_e32 v76, v76
	v_exp_f32_e32 v77, v77
	v_exp_f32_e32 v78, v78
	v_exp_f32_e32 v79, v79
	v_exp_f32_e32 v80, v80
	v_exp_f32_e32 v81, v81
	v_exp_f32_e32 v82, v82
	v_exp_f32_e32 v83, v83
	v_exp_f32_e32 v84, v84
	v_exp_f32_e32 v85, v85
	v_exp_f32_e32 v86, v86
	v_exp_f32_e32 v87, v87
	v_exp_f32_e32 v88, v88
	v_exp_f32_e32 v89, v89
	v_exp_f32_e32 v90, v90
	v_exp_f32_e32 v91, v91
	v_exp_f32_e32 v92, v92
	v_exp_f32_e32 v93, v93
	v_exp_f32_e32 v94, v94
	v_exp_f32_e32 v95, v95
	v_pk_add_f32 v[64:65], v[64:65], 1.0 op_sel_hi:[1,0]
	v_pk_add_f32 v[66:67], v[66:67], 1.0 op_sel_hi:[1,0]
	v_pk_add_f32 v[68:69], v[68:69], 1.0 op_sel_hi:[1,0]
	v_pk_add_f32 v[70:71], v[70:71], 1.0 op_sel_hi:[1,0]
	v_pk_add_f32 v[72:73], v[72:73], 1.0 op_sel_hi:[1,0]
	v_pk_add_f32 v[74:75], v[74:75], 1.0 op_sel_hi:[1,0]
	v_pk_add_f32 v[76:77], v[76:77], 1.0 op_sel_hi:[1,0]
	v_pk_add_f32 v[78:79], v[78:79], 1.0 op_sel_hi:[1,0]
	v_pk_add_f32 v[80:81], v[80:81], 1.0 op_sel_hi:[1,0]
	v_pk_add_f32 v[82:83], v[82:83], 1.0 op_sel_hi:[1,0]
	v_pk_add_f32 v[84:85], v[84:85], 1.0 op_sel_hi:[1,0]
	v_pk_add_f32 v[86:87], v[86:87], 1.0 op_sel_hi:[1,0]
	v_pk_add_f32 v[88:89], v[88:89], 1.0 op_sel_hi:[1,0]
	v_pk_add_f32 v[90:91], v[90:91], 1.0 op_sel_hi:[1,0]
	v_pk_add_f32 v[92:93], v[92:93], 1.0 op_sel_hi:[1,0]
	v_pk_add_f32 v[94:95], v[94:95], 1.0 op_sel_hi:[1,0]
	v_rcp_f32_e32 v64, v64
	v_rcp_f32_e32 v65, v65
	v_rcp_f32_e32 v66, v66
	v_rcp_f32_e32 v67, v67
	v_rcp_f32_e32 v68, v68
	v_rcp_f32_e32 v69, v69
	v_rcp_f32_e32 v70, v70
	v_rcp_f32_e32 v71, v71
	v_rcp_f32_e32 v72, v72
	v_rcp_f32_e32 v73, v73
	v_rcp_f32_e32 v74, v74
	v_rcp_f32_e32 v75, v75
	v_rcp_f32_e32 v76, v76
	v_rcp_f32_e32 v77, v77
	v_rcp_f32_e32 v78, v78
	v_rcp_f32_e32 v79, v79
	v_rcp_f32_e32 v80, v80
	v_rcp_f32_e32 v81, v81
	v_rcp_f32_e32 v82, v82
	v_rcp_f32_e32 v83, v83
	v_rcp_f32_e32 v84, v84
	v_rcp_f32_e32 v85, v85
	v_rcp_f32_e32 v86, v86
	v_rcp_f32_e32 v87, v87
	v_rcp_f32_e32 v88, v88
	v_rcp_f32_e32 v89, v89
	v_rcp_f32_e32 v90, v90
	v_rcp_f32_e32 v91, v91
	v_rcp_f32_e32 v92, v92
	v_rcp_f32_e32 v93, v93
	v_rcp_f32_e32 v94, v94
	v_rcp_f32_e32 v95, v95
	s_nop 0
	v_cvt_pk_bf16_f32 v64, v64, v65
	v_cvt_pk_bf16_f32 v65, v66, v67
	v_cvt_pk_bf16_f32 v66, v68, v69
	v_cvt_pk_bf16_f32 v67, v70, v71
	v_cvt_pk_bf16_f32 v68, v72, v73
	v_cvt_pk_bf16_f32 v69, v74, v75
	v_cvt_pk_bf16_f32 v70, v76, v77
	v_cvt_pk_bf16_f32 v71, v78, v79
	v_cvt_pk_bf16_f32 v80, v80, v81
	v_cvt_pk_bf16_f32 v81, v82, v83
	v_cvt_pk_bf16_f32 v82, v84, v85
	v_cvt_pk_bf16_f32 v83, v86, v87
	v_cvt_pk_bf16_f32 v84, v88, v89
	v_cvt_pk_bf16_f32 v85, v90, v91
	v_cvt_pk_bf16_f32 v86, v92, v93
	v_cvt_pk_bf16_f32 v87, v94, v95
	v_permlane32_swap_b32_e32 v64, v66
	v_permlane32_swap_b32_e32 v65, v67
	v_permlane32_swap_b32_e32 v68, v70
	v_permlane32_swap_b32_e32 v69, v71
	v_permlane32_swap_b32_e32 v80, v82
	v_permlane32_swap_b32_e32 v81, v83
	v_permlane32_swap_b32_e32 v84, v86
	v_permlane32_swap_b32_e32 v85, v87
	global_store_dwordx4 v181, v[64:67], s[74:75] offset:0
	global_store_dwordx4 v181, v[68:71], s[74:75] offset:32
	global_store_dwordx4 v181, v[80:83], s[74:75] offset:64
	global_store_dwordx4 v181, v[84:87], s[74:75] offset:96
	s_add_u32 s74, s74, 0x44000
	s_addc_u32 s75, s75, 0
	v_pk_fma_f32 v[96:97], v[96:97], v[174:175], v[198:199] op_sel:[0,1,0] op_sel_hi:[1,1,1]
	v_pk_fma_f32 v[98:99], v[98:99], v[174:175], v[200:201] op_sel:[0,1,0] op_sel_hi:[1,1,1]
	v_pk_fma_f32 v[100:101], v[100:101], v[174:175], v[202:203] op_sel:[0,1,0] op_sel_hi:[1,1,1]
	v_pk_fma_f32 v[102:103], v[102:103], v[174:175], v[204:205] op_sel:[0,1,0] op_sel_hi:[1,1,1]
	v_pk_fma_f32 v[104:105], v[104:105], v[174:175], v[206:207] op_sel:[0,1,0] op_sel_hi:[1,1,1]
	v_pk_fma_f32 v[106:107], v[106:107], v[174:175], v[208:209] op_sel:[0,1,0] op_sel_hi:[1,1,1]
	v_pk_fma_f32 v[108:109], v[108:109], v[174:175], v[210:211] op_sel:[0,1,0] op_sel_hi:[1,1,1]
	v_pk_fma_f32 v[110:111], v[110:111], v[174:175], v[212:213] op_sel:[0,1,0] op_sel_hi:[1,1,1]
	v_pk_fma_f32 v[112:113], v[112:113], v[174:175], v[214:215] op_sel:[0,1,0] op_sel_hi:[1,1,1]
	v_pk_fma_f32 v[114:115], v[114:115], v[174:175], v[216:217] op_sel:[0,1,0] op_sel_hi:[1,1,1]
	v_pk_fma_f32 v[116:117], v[116:117], v[174:175], v[218:219] op_sel:[0,1,0] op_sel_hi:[1,1,1]
	v_pk_fma_f32 v[118:119], v[118:119], v[174:175], v[220:221] op_sel:[0,1,0] op_sel_hi:[1,1,1]
	v_pk_fma_f32 v[120:121], v[120:121], v[174:175], v[222:223] op_sel:[0,1,0] op_sel_hi:[1,1,1]
	v_pk_fma_f32 v[122:123], v[122:123], v[174:175], v[224:225] op_sel:[0,1,0] op_sel_hi:[1,1,1]
	v_pk_fma_f32 v[124:125], v[124:125], v[174:175], v[226:227] op_sel:[0,1,0] op_sel_hi:[1,1,1]
	v_pk_fma_f32 v[126:127], v[126:127], v[174:175], v[228:229] op_sel:[0,1,0] op_sel_hi:[1,1,1]
	v_exp_f32_e32 v96, v96
	v_exp_f32_e32 v97, v97
	v_exp_f32_e32 v98, v98
	v_exp_f32_e32 v99, v99
	v_exp_f32_e32 v100, v100
	v_exp_f32_e32 v101, v101
	v_exp_f32_e32 v102, v102
	v_exp_f32_e32 v103, v103
	v_exp_f32_e32 v104, v104
	v_exp_f32_e32 v105, v105
	v_exp_f32_e32 v106, v106
	v_exp_f32_e32 v107, v107
	v_exp_f32_e32 v108, v108
	v_exp_f32_e32 v109, v109
	v_exp_f32_e32 v110, v110
	v_exp_f32_e32 v111, v111
	v_exp_f32_e32 v112, v112
	v_exp_f32_e32 v113, v113
	v_exp_f32_e32 v114, v114
	v_exp_f32_e32 v115, v115
	v_exp_f32_e32 v116, v116
	v_exp_f32_e32 v117, v117
	v_exp_f32_e32 v118, v118
	v_exp_f32_e32 v119, v119
	v_exp_f32_e32 v120, v120
	v_exp_f32_e32 v121, v121
	v_exp_f32_e32 v122, v122
	v_exp_f32_e32 v123, v123
	v_exp_f32_e32 v124, v124
	v_exp_f32_e32 v125, v125
	v_exp_f32_e32 v126, v126
	v_exp_f32_e32 v127, v127
	v_pk_add_f32 v[96:97], v[96:97], 1.0 op_sel_hi:[1,0]
	v_pk_add_f32 v[98:99], v[98:99], 1.0 op_sel_hi:[1,0]
	v_pk_add_f32 v[100:101], v[100:101], 1.0 op_sel_hi:[1,0]
	v_pk_add_f32 v[102:103], v[102:103], 1.0 op_sel_hi:[1,0]
	v_pk_add_f32 v[104:105], v[104:105], 1.0 op_sel_hi:[1,0]
	v_pk_add_f32 v[106:107], v[106:107], 1.0 op_sel_hi:[1,0]
	v_pk_add_f32 v[108:109], v[108:109], 1.0 op_sel_hi:[1,0]
	v_pk_add_f32 v[110:111], v[110:111], 1.0 op_sel_hi:[1,0]
	v_pk_add_f32 v[112:113], v[112:113], 1.0 op_sel_hi:[1,0]
	v_pk_add_f32 v[114:115], v[114:115], 1.0 op_sel_hi:[1,0]
	v_pk_add_f32 v[116:117], v[116:117], 1.0 op_sel_hi:[1,0]
	v_pk_add_f32 v[118:119], v[118:119], 1.0 op_sel_hi:[1,0]
	v_pk_add_f32 v[120:121], v[120:121], 1.0 op_sel_hi:[1,0]
	v_pk_add_f32 v[122:123], v[122:123], 1.0 op_sel_hi:[1,0]
	v_pk_add_f32 v[124:125], v[124:125], 1.0 op_sel_hi:[1,0]
	v_pk_add_f32 v[126:127], v[126:127], 1.0 op_sel_hi:[1,0]
	v_rcp_f32_e32 v96, v96
	v_rcp_f32_e32 v97, v97
	v_rcp_f32_e32 v98, v98
	v_rcp_f32_e32 v99, v99
	v_rcp_f32_e32 v100, v100
	v_rcp_f32_e32 v101, v101
	v_rcp_f32_e32 v102, v102
	v_rcp_f32_e32 v103, v103
	v_rcp_f32_e32 v104, v104
	v_rcp_f32_e32 v105, v105
	v_rcp_f32_e32 v106, v106
	v_rcp_f32_e32 v107, v107
	v_rcp_f32_e32 v108, v108
	v_rcp_f32_e32 v109, v109
	v_rcp_f32_e32 v110, v110
	v_rcp_f32_e32 v111, v111
	v_rcp_f32_e32 v112, v112
	v_rcp_f32_e32 v113, v113
	v_rcp_f32_e32 v114, v114
	v_rcp_f32_e32 v115, v115
	v_rcp_f32_e32 v116, v116
	v_rcp_f32_e32 v117, v117
	v_rcp_f32_e32 v118, v118
	v_rcp_f32_e32 v119, v119
	v_rcp_f32_e32 v120, v120
	v_rcp_f32_e32 v121, v121
	v_rcp_f32_e32 v122, v122
	v_rcp_f32_e32 v123, v123
	v_rcp_f32_e32 v124, v124
	v_rcp_f32_e32 v125, v125
	v_rcp_f32_e32 v126, v126
	v_rcp_f32_e32 v127, v127
	s_nop 0
	v_cvt_pk_bf16_f32 v96, v96, v97
	v_cvt_pk_bf16_f32 v97, v98, v99
	v_cvt_pk_bf16_f32 v98, v100, v101
	v_cvt_pk_bf16_f32 v99, v102, v103
	v_cvt_pk_bf16_f32 v100, v104, v105
	v_cvt_pk_bf16_f32 v101, v106, v107
	v_cvt_pk_bf16_f32 v102, v108, v109
	v_cvt_pk_bf16_f32 v103, v110, v111
	v_cvt_pk_bf16_f32 v112, v112, v113
	v_cvt_pk_bf16_f32 v113, v114, v115
	v_cvt_pk_bf16_f32 v114, v116, v117
	v_cvt_pk_bf16_f32 v115, v118, v119
	v_cvt_pk_bf16_f32 v116, v120, v121
	v_cvt_pk_bf16_f32 v117, v122, v123
	v_cvt_pk_bf16_f32 v118, v124, v125
	v_cvt_pk_bf16_f32 v119, v126, v127
	v_permlane32_swap_b32_e32 v96, v98
	v_permlane32_swap_b32_e32 v97, v99
	v_permlane32_swap_b32_e32 v100, v102
	v_permlane32_swap_b32_e32 v101, v103
	v_permlane32_swap_b32_e32 v112, v114
	v_permlane32_swap_b32_e32 v113, v115
	v_permlane32_swap_b32_e32 v116, v118
	v_permlane32_swap_b32_e32 v117, v119
	global_store_dwordx4 v181, v[96:99], s[74:75] offset:0
	global_store_dwordx4 v181, v[100:103], s[74:75] offset:32
	global_store_dwordx4 v181, v[112:115], s[74:75] offset:64
	global_store_dwordx4 v181, v[116:119], s[74:75] offset:96
	s_branch .Lpe_ret_L0
.Lpe_vt_L0:
	s_lshl_b32 s35, s34, 2
	s_add_u32 s35, s35, s28
	s_add_u32 s36, s28, 6
	s_cmp_eq_u32 s25, 8
	s_cselect_b32 s35, s36, s35
	s_lshr_b32 s36, s29, 11
	s_mul_i32 s36, s36, 10
	s_add_u32 s36, s36, s35
	s_lshl_b32 s36, s36, 18
	s_and_b32 s37, s29, 0x7ff
	s_lshl_b32 s37, s37, 1
	s_add_u32 s36, s36, s37
	s_add_u32 s38, s72, 0x14920000
	s_addc_u32 s39, s73, 0
	s_add_u32 s38, s38, s36
	s_addc_u32 s39, s39, 0
	s_mul_i32 s36, s26, 10240
	s_add_u32 s36, s36, 0x10000
	v_lshlrev_b32_e32 v180, 1, v197
	v_mul_u32_u24_e32 v181, 36, v146
	v_add3_u32 v180, v180, v181, s36
	v_lshrrev_b32_e32 v181, 3, v179
	v_and_b32_e32 v146, 7, v179
	v_lshlrev_b32_e32 v146, 4, v146
	v_mul_u32_u24_e32 v198, 144, v181
	v_add3_u32 v198, v198, v146, s36
	v_lshl_add_u32 v199, v181, 12, v146
	s_waitcnt vmcnt(0)
	v_mov_b32_e32 v197, 0x358637bd
	v_pk_add_f32 v[128:129], v[128:129], v[130:131]
	v_pk_add_f32 v[132:133], v[132:133], v[134:135]
	v_pk_add_f32 v[136:137], v[136:137], v[138:139]
	v_pk_add_f32 v[140:141], v[140:141], v[142:143]
	v_pk_add_f32 v[164:165], v[164:165], v[166:167]
	v_pk_add_f32 v[168:169], v[168:169], v[170:171]
	v_pk_add_f32 v[246:247], v[246:247], v[248:249]
	v_pk_add_f32 v[250:251], v[250:251], v[252:253]
	v_pk_add_f32 v[128:129], v[128:129], v[132:133]
	v_pk_add_f32 v[136:137], v[136:137], v[140:141]
	v_pk_add_f32 v[164:165], v[164:165], v[168:169]
	v_pk_add_f32 v[246:247], v[246:247], v[250:251]
	v_add_f32_e32 v128, v128, v129
	v_add_f32_e32 v136, v136, v137
	v_add_f32_e32 v164, v164, v165
	v_add_f32_e32 v246, v246, v247
	v_fmamk_f32 v128, v128, 0x3a800000, v197
	v_fmamk_f32 v136, v136, 0x3a800000, v197
	v_fmamk_f32 v164, v164, 0x3a800000, v197
	v_fmamk_f32 v246, v246, 0x3a800000, v197
	v_rsq_f32_e32 v172, v128
	v_rsq_f32_e32 v173, v136
	v_rsq_f32_e32 v174, v164
	v_rsq_f32_e32 v175, v246
	s_nop 0
	s_add_u32 s76, s99, s90
	s_cmp_lt_u32 s76, 0x440
	s_cselect_b32 s80, 1, 0
	s_cselect_b32 s83, 0x200000, 0
	s_lshl_b32 s76, s24, 19
	s_lshl_b32 s77, s26, 16
	s_add_u32 s76, s76, s77
	s_and_b32 s77, s24, 7
	s_lshl_b32 s77, s77, 8
	s_add_u32 s76, s76, s77
	s_add_u32 s78, s72, 0xa120000
	s_addc_u32 s79, s73, 0
	s_add_u32 s78, s78, s76
	s_addc_u32 s79, s79, 0
	s_lshl_b32 s76, s25, 19
	s_add_u32 s76, s76, s83
	s_add_u32 s76, s76, s77
	s_lshl_b32 s77, s26, 16
	s_add_u32 s76, s76, s77
	s_add_u32 s82, s72, 0x0
	s_addc_u32 s83, s73, 0
	s_add_u32 s82, s82, s76
	s_addc_u32 s83, s83, 0
	s_lshl_b32 s76, s26, 12
	s_mov_b32 m0, s76
	s_nop 0
	global_load_lds_dwordx4 v145, s[78:79]
	s_add_u32 s78, s78, 0x4000
	s_addc_u32 s79, s79, 0
	s_add_u32 s76, s76, 0x400
	s_mov_b32 m0, s76
	s_nop 0
	global_load_lds_dwordx4 v185, s[78:79]
	s_add_u32 s78, s78, 0x4000
	s_addc_u32 s79, s79, 0
	s_add_u32 s76, s76, 0x400
	s_mov_b32 m0, s76
	s_nop 0
	global_load_lds_dwordx4 v145, s[78:79]
	s_add_u32 s78, s78, 0x4000
	s_addc_u32 s79, s79, 0
	s_add_u32 s76, s76, 0x400
	s_mov_b32 m0, s76
	s_nop 0
	global_load_lds_dwordx4 v185, s[78:79]
	s_add_u32 s78, s78, 0x4000
	s_addc_u32 s79, s79, 0
	s_add_u32 s76, s76, 0x400
	s_add_u32 s76, s76, 0x7000
	s_mov_b32 m0, s76
	s_nop 0
	global_load_lds_dwordx4 v145, s[82:83]
	s_add_u32 s82, s82, 0x4000
	s_addc_u32 s83, s83, 0
	s_add_u32 s76, s76, 0x400
	s_mov_b32 m0, s76
	s_nop 0
	global_load_lds_dwordx4 v185, s[82:83]
	s_add_u32 s82, s82, 0x4000
	s_addc_u32 s83, s83, 0
	s_add_u32 s76, s76, 0x400
	s_mov_b32 m0, s76
	s_nop 0
	global_load_lds_dwordx4 v145, s[82:83]
	s_add_u32 s82, s82, 0x4000
	s_addc_u32 s83, s83, 0
	s_add_u32 s76, s76, 0x400
	s_mov_b32 m0, s76
	s_nop 0
	global_load_lds_dwordx4 v185, s[82:83]
	s_add_u32 s82, s82, 0x4000
	s_addc_u32 s83, s83, 0
	s_add_u32 s76, s76, 0x400
	v_pk_mul_f32 v[0:1], v[0:1], v[172:173] op_sel_hi:[1,0]
	v_pk_mul_f32 v[2:3], v[2:3], v[172:173] op_sel_hi:[1,0]
	v_pk_mul_f32 v[4:5], v[4:5], v[172:173] op_sel_hi:[1,0]
	v_pk_mul_f32 v[6:7], v[6:7], v[172:173] op_sel_hi:[1,0]
	v_pk_mul_f32 v[8:9], v[8:9], v[172:173] op_sel_hi:[1,0]
	v_pk_mul_f32 v[10:11], v[10:11], v[172:173] op_sel_hi:[1,0]
	v_pk_mul_f32 v[12:13], v[12:13], v[172:173] op_sel_hi:[1,0]
	v_pk_mul_f32 v[14:15], v[14:15], v[172:173] op_sel_hi:[1,0]
	v_pk_mul_f32 v[16:17], v[16:17], v[172:173] op_sel_hi:[1,0]
	v_pk_mul_f32 v[18:19], v[18:19], v[172:173] op_sel_hi:[1,0]
	v_pk_mul_f32 v[20:21], v[20:21], v[172:173] op_sel_hi:[1,0]
	v_pk_mul_f32 v[22:23], v[22:23], v[172:173] op_sel_hi:[1,0]
	v_pk_mul_f32 v[24:25], v[24:25], v[172:173] op_sel_hi:[1,0]
	v_pk_mul_f32 v[26:27], v[26:27], v[172:173] op_sel_hi:[1,0]
	v_pk_mul_f32 v[28:29], v[28:29], v[172:173] op_sel_hi:[1,0]
	v_pk_mul_f32 v[30:31], v[30:31], v[172:173] op_sel_hi:[1,0]
	v_pk_mul_f32 v[32:33], v[32:33], v[172:173] op_sel:[0,1] op_sel_hi:[1,1]
	v_pk_mul_f32 v[34:35], v[34:35], v[172:173] op_sel:[0,1] op_sel_hi:[1,1]
	v_pk_mul_f32 v[36:37], v[36:37], v[172:173] op_sel:[0,1] op_sel_hi:[1,1]
	v_pk_mul_f32 v[38:39], v[38:39], v[172:173] op_sel:[0,1] op_sel_hi:[1,1]
	v_pk_mul_f32 v[40:41], v[40:41], v[172:173] op_sel:[0,1] op_sel_hi:[1,1]
	v_pk_mul_f32 v[42:43], v[42:43], v[172:173] op_sel:[0,1] op_sel_hi:[1,1]
	v_pk_mul_f32 v[44:45], v[44:45], v[172:173] op_sel:[0,1] op_sel_hi:[1,1]
	v_pk_mul_f32 v[46:47], v[46:47], v[172:173] op_sel:[0,1] op_sel_hi:[1,1]
	v_pk_mul_f32 v[48:49], v[48:49], v[172:173] op_sel:[0,1] op_sel_hi:[1,1]
	v_pk_mul_f32 v[50:51], v[50:51], v[172:173] op_sel:[0,1] op_sel_hi:[1,1]
	v_pk_mul_f32 v[52:53], v[52:53], v[172:173] op_sel:[0,1] op_sel_hi:[1,1]
	v_pk_mul_f32 v[54:55], v[54:55], v[172:173] op_sel:[0,1] op_sel_hi:[1,1]
	v_pk_mul_f32 v[56:57], v[56:57], v[172:173] op_sel:[0,1] op_sel_hi:[1,1]
	v_pk_mul_f32 v[58:59], v[58:59], v[172:173] op_sel:[0,1] op_sel_hi:[1,1]
	v_pk_mul_f32 v[60:61], v[60:61], v[172:173] op_sel:[0,1] op_sel_hi:[1,1]
	v_pk_mul_f32 v[62:63], v[62:63], v[172:173] op_sel:[0,1] op_sel_hi:[1,1]
	v_pk_mul_f32 v[64:65], v[64:65], v[174:175] op_sel_hi:[1,0]
	v_pk_mul_f32 v[66:67], v[66:67], v[174:175] op_sel_hi:[1,0]
	v_pk_mul_f32 v[68:69], v[68:69], v[174:175] op_sel_hi:[1,0]
	v_pk_mul_f32 v[70:71], v[70:71], v[174:175] op_sel_hi:[1,0]
	v_pk_mul_f32 v[72:73], v[72:73], v[174:175] op_sel_hi:[1,0]
	v_pk_mul_f32 v[74:75], v[74:75], v[174:175] op_sel_hi:[1,0]
	v_pk_mul_f32 v[76:77], v[76:77], v[174:175] op_sel_hi:[1,0]
	v_pk_mul_f32 v[78:79], v[78:79], v[174:175] op_sel_hi:[1,0]
	v_pk_mul_f32 v[80:81], v[80:81], v[174:175] op_sel_hi:[1,0]
	v_pk_mul_f32 v[82:83], v[82:83], v[174:175] op_sel_hi:[1,0]
	v_pk_mul_f32 v[84:85], v[84:85], v[174:175] op_sel_hi:[1,0]
	v_pk_mul_f32 v[86:87], v[86:87], v[174:175] op_sel_hi:[1,0]
	v_pk_mul_f32 v[88:89], v[88:89], v[174:175] op_sel_hi:[1,0]
	v_pk_mul_f32 v[90:91], v[90:91], v[174:175] op_sel_hi:[1,0]
	v_pk_mul_f32 v[92:93], v[92:93], v[174:175] op_sel_hi:[1,0]
	v_pk_mul_f32 v[94:95], v[94:95], v[174:175] op_sel_hi:[1,0]
	v_pk_mul_f32 v[96:97], v[96:97], v[174:175] op_sel:[0,1] op_sel_hi:[1,1]
	v_pk_mul_f32 v[98:99], v[98:99], v[174:175] op_sel:[0,1] op_sel_hi:[1,1]
	v_pk_mul_f32 v[100:101], v[100:101], v[174:175] op_sel:[0,1] op_sel_hi:[1,1]
	v_pk_mul_f32 v[102:103], v[102:103], v[174:175] op_sel:[0,1] op_sel_hi:[1,1]
	v_pk_mul_f32 v[104:105], v[104:105], v[174:175] op_sel:[0,1] op_sel_hi:[1,1]
	v_pk_mul_f32 v[106:107], v[106:107], v[174:175] op_sel:[0,1] op_sel_hi:[1,1]
	v_pk_mul_f32 v[108:109], v[108:109], v[174:175] op_sel:[0,1] op_sel_hi:[1,1]
	v_pk_mul_f32 v[110:111], v[110:111], v[174:175] op_sel:[0,1] op_sel_hi:[1,1]
	v_pk_mul_f32 v[112:113], v[112:113], v[174:175] op_sel:[0,1] op_sel_hi:[1,1]
	v_pk_mul_f32 v[114:115], v[114:115], v[174:175] op_sel:[0,1] op_sel_hi:[1,1]
	v_pk_mul_f32 v[116:117], v[116:117], v[174:175] op_sel:[0,1] op_sel_hi:[1,1]
	v_pk_mul_f32 v[118:119], v[118:119], v[174:175] op_sel:[0,1] op_sel_hi:[1,1]
	v_pk_mul_f32 v[120:121], v[120:121], v[174:175] op_sel:[0,1] op_sel_hi:[1,1]
	v_pk_mul_f32 v[122:123], v[122:123], v[174:175] op_sel:[0,1] op_sel_hi:[1,1]
	v_pk_mul_f32 v[124:125], v[124:125], v[174:175] op_sel:[0,1] op_sel_hi:[1,1]
	v_pk_mul_f32 v[126:127], v[126:127], v[174:175] op_sel:[0,1] op_sel_hi:[1,1]
	v_cvt_pk_bf16_f32 v0, v0, v1
	v_cvt_pk_bf16_f32 v1, v2, v3
	v_cvt_pk_bf16_f32 v2, v4, v5
	v_cvt_pk_bf16_f32 v3, v6, v7
	v_cvt_pk_bf16_f32 v4, v8, v9
	v_cvt_pk_bf16_f32 v5, v10, v11
	v_cvt_pk_bf16_f32 v6, v12, v13
	v_cvt_pk_bf16_f32 v7, v14, v15
	ds_write_b16 v180, v0 offset:0
	ds_write_b16_d16_hi v180, v0 offset:144
	ds_write_b16 v180, v1 offset:288
	ds_write_b16_d16_hi v180, v1 offset:432
	ds_write_b16 v180, v2 offset:1152
	ds_write_b16_d16_hi v180, v2 offset:1296
	ds_write_b16 v180, v3 offset:1440
	ds_write_b16_d16_hi v180, v3 offset:1584
	ds_write_b16 v180, v4 offset:2304
	ds_write_b16_d16_hi v180, v4 offset:2448
	ds_write_b16 v180, v5 offset:2592
	ds_write_b16_d16_hi v180, v5 offset:2736
	ds_write_b16 v180, v6 offset:3456
	ds_write_b16_d16_hi v180, v6 offset:3600
	ds_write_b16 v180, v7 offset:3744
	ds_write_b16_d16_hi v180, v7 offset:3888
	v_cvt_pk_bf16_f32 v16, v16, v17
	v_cvt_pk_bf16_f32 v17, v18, v19
	v_cvt_pk_bf16_f32 v18, v20, v21
	v_cvt_pk_bf16_f32 v19, v22, v23
	v_cvt_pk_bf16_f32 v20, v24, v25
	v_cvt_pk_bf16_f32 v21, v26, v27
	v_cvt_pk_bf16_f32 v22, v28, v29
	v_cvt_pk_bf16_f32 v23, v30, v31
	ds_write_b16 v180, v16 offset:4608
	ds_write_b16_d16_hi v180, v16 offset:4752
	ds_write_b16 v180, v17 offset:4896
	ds_write_b16_d16_hi v180, v17 offset:5040
	ds_write_b16 v180, v18 offset:5760
	ds_write_b16_d16_hi v180, v18 offset:5904
	ds_write_b16 v180, v19 offset:6048
	ds_write_b16_d16_hi v180, v19 offset:6192
	ds_write_b16 v180, v20 offset:6912
	ds_write_b16_d16_hi v180, v20 offset:7056
	ds_write_b16 v180, v21 offset:7200
	ds_write_b16_d16_hi v180, v21 offset:7344
	ds_write_b16 v180, v22 offset:8064
	ds_write_b16_d16_hi v180, v22 offset:8208
	ds_write_b16 v180, v23 offset:8352
	ds_write_b16_d16_hi v180, v23 offset:8496
	v_cvt_pk_bf16_f32 v32, v32, v33
	v_cvt_pk_bf16_f32 v33, v34, v35
	v_cvt_pk_bf16_f32 v34, v36, v37
	v_cvt_pk_bf16_f32 v35, v38, v39
	v_cvt_pk_bf16_f32 v36, v40, v41
	v_cvt_pk_bf16_f32 v37, v42, v43
	v_cvt_pk_bf16_f32 v38, v44, v45
	v_cvt_pk_bf16_f32 v39, v46, v47
	ds_write_b16 v180, v32 offset:64
	ds_write_b16_d16_hi v180, v32 offset:208
	ds_write_b16 v180, v33 offset:352
	ds_write_b16_d16_hi v180, v33 offset:496
	ds_write_b16 v180, v34 offset:1216
	ds_write_b16_d16_hi v180, v34 offset:1360
	ds_write_b16 v180, v35 offset:1504
	ds_write_b16_d16_hi v180, v35 offset:1648
	ds_write_b16 v180, v36 offset:2368
	ds_write_b16_d16_hi v180, v36 offset:2512
	ds_write_b16 v180, v37 offset:2656
	ds_write_b16_d16_hi v180, v37 offset:2800
	ds_write_b16 v180, v38 offset:3520
	ds_write_b16_d16_hi v180, v38 offset:3664
	ds_write_b16 v180, v39 offset:3808
	ds_write_b16_d16_hi v180, v39 offset:3952
	v_cvt_pk_bf16_f32 v48, v48, v49
	v_cvt_pk_bf16_f32 v49, v50, v51
	v_cvt_pk_bf16_f32 v50, v52, v53
	v_cvt_pk_bf16_f32 v51, v54, v55
	v_cvt_pk_bf16_f32 v52, v56, v57
	v_cvt_pk_bf16_f32 v53, v58, v59
	v_cvt_pk_bf16_f32 v54, v60, v61
	v_cvt_pk_bf16_f32 v55, v62, v63
	ds_write_b16 v180, v48 offset:4672
	ds_write_b16_d16_hi v180, v48 offset:4816
	ds_write_b16 v180, v49 offset:4960
	ds_write_b16_d16_hi v180, v49 offset:5104
	ds_write_b16 v180, v50 offset:5824
	ds_write_b16_d16_hi v180, v50 offset:5968
	ds_write_b16 v180, v51 offset:6112
	ds_write_b16_d16_hi v180, v51 offset:6256
	ds_write_b16 v180, v52 offset:6976
	ds_write_b16_d16_hi v180, v52 offset:7120
	ds_write_b16 v180, v53 offset:7264
	ds_write_b16_d16_hi v180, v53 offset:7408
	ds_write_b16 v180, v54 offset:8128
	ds_write_b16_d16_hi v180, v54 offset:8272
	ds_write_b16 v180, v55 offset:8416
	ds_write_b16_d16_hi v180, v55 offset:8560
	s_waitcnt lgkmcnt(0)
	ds_read_b128 v[0:3], v198 offset:0
	ds_read_b128 v[4:7], v198 offset:1152
	ds_read_b128 v[8:11], v198 offset:2304
	ds_read_b128 v[12:15], v198 offset:3456
	ds_read_b128 v[16:19], v198 offset:4608
	ds_read_b128 v[20:23], v198 offset:5760
	ds_read_b128 v[24:27], v198 offset:6912
	ds_read_b128 v[28:31], v198 offset:8064
	s_waitcnt lgkmcnt(7)
	global_store_dwordx4 v199, v[0:3], s[38:39]
	s_add_u32 s38, s38, 0x8000
	s_addc_u32 s39, s39, 0
	s_waitcnt lgkmcnt(6)
	global_store_dwordx4 v199, v[4:7], s[38:39]
	s_add_u32 s38, s38, 0x8000
	s_addc_u32 s39, s39, 0
	s_waitcnt lgkmcnt(5)
	global_store_dwordx4 v199, v[8:11], s[38:39]
	s_add_u32 s38, s38, 0x8000
	s_addc_u32 s39, s39, 0
	s_waitcnt lgkmcnt(4)
	global_store_dwordx4 v199, v[12:15], s[38:39]
	s_add_u32 s38, s38, 0x8000
	s_addc_u32 s39, s39, 0
	s_waitcnt lgkmcnt(3)
	global_store_dwordx4 v199, v[16:19], s[38:39]
	s_add_u32 s38, s38, 0x8000
	s_addc_u32 s39, s39, 0
	s_waitcnt lgkmcnt(2)
	global_store_dwordx4 v199, v[20:23], s[38:39]
	s_add_u32 s38, s38, 0x8000
	s_addc_u32 s39, s39, 0
	s_waitcnt lgkmcnt(1)
	global_store_dwordx4 v199, v[24:27], s[38:39]
	s_add_u32 s38, s38, 0x8000
	s_addc_u32 s39, s39, 0
	s_waitcnt lgkmcnt(0)
	global_store_dwordx4 v199, v[28:31], s[38:39]
	s_sub_u32 s38, s38, 229248
	s_subb_u32 s39, s39, 0
	v_cvt_pk_bf16_f32 v64, v64, v65
	v_cvt_pk_bf16_f32 v65, v66, v67
	v_cvt_pk_bf16_f32 v66, v68, v69
	v_cvt_pk_bf16_f32 v67, v70, v71
	v_cvt_pk_bf16_f32 v68, v72, v73
	v_cvt_pk_bf16_f32 v69, v74, v75
	v_cvt_pk_bf16_f32 v70, v76, v77
	v_cvt_pk_bf16_f32 v71, v78, v79
	ds_write_b16 v180, v64 offset:0
	ds_write_b16_d16_hi v180, v64 offset:144
	ds_write_b16 v180, v65 offset:288
	ds_write_b16_d16_hi v180, v65 offset:432
	ds_write_b16 v180, v66 offset:1152
	ds_write_b16_d16_hi v180, v66 offset:1296
	ds_write_b16 v180, v67 offset:1440
	ds_write_b16_d16_hi v180, v67 offset:1584
	ds_write_b16 v180, v68 offset:2304
	ds_write_b16_d16_hi v180, v68 offset:2448
	ds_write_b16 v180, v69 offset:2592
	ds_write_b16_d16_hi v180, v69 offset:2736
	ds_write_b16 v180, v70 offset:3456
	ds_write_b16_d16_hi v180, v70 offset:3600
	ds_write_b16 v180, v71 offset:3744
	ds_write_b16_d16_hi v180, v71 offset:3888
	v_cvt_pk_bf16_f32 v80, v80, v81
	v_cvt_pk_bf16_f32 v81, v82, v83
	v_cvt_pk_bf16_f32 v82, v84, v85
	v_cvt_pk_bf16_f32 v83, v86, v87
	v_cvt_pk_bf16_f32 v84, v88, v89
	v_cvt_pk_bf16_f32 v85, v90, v91
	v_cvt_pk_bf16_f32 v86, v92, v93
	v_cvt_pk_bf16_f32 v87, v94, v95
	ds_write_b16 v180, v80 offset:4608
	ds_write_b16_d16_hi v180, v80 offset:4752
	ds_write_b16 v180, v81 offset:4896
	ds_write_b16_d16_hi v180, v81 offset:5040
	ds_write_b16 v180, v82 offset:5760
	ds_write_b16_d16_hi v180, v82 offset:5904
	ds_write_b16 v180, v83 offset:6048
	ds_write_b16_d16_hi v180, v83 offset:6192
	ds_write_b16 v180, v84 offset:6912
	ds_write_b16_d16_hi v180, v84 offset:7056
	ds_write_b16 v180, v85 offset:7200
	ds_write_b16_d16_hi v180, v85 offset:7344
	ds_write_b16 v180, v86 offset:8064
	ds_write_b16_d16_hi v180, v86 offset:8208
	ds_write_b16 v180, v87 offset:8352
	ds_write_b16_d16_hi v180, v87 offset:8496
	v_cvt_pk_bf16_f32 v96, v96, v97
	v_cvt_pk_bf16_f32 v97, v98, v99
	v_cvt_pk_bf16_f32 v98, v100, v101
	v_cvt_pk_bf16_f32 v99, v102, v103
	v_cvt_pk_bf16_f32 v100, v104, v105
	v_cvt_pk_bf16_f32 v101, v106, v107
	v_cvt_pk_bf16_f32 v102, v108, v109
	v_cvt_pk_bf16_f32 v103, v110, v111
	ds_write_b16 v180, v96 offset:64
	ds_write_b16_d16_hi v180, v96 offset:208
	ds_write_b16 v180, v97 offset:352
	ds_write_b16_d16_hi v180, v97 offset:496
	ds_write_b16 v180, v98 offset:1216
	ds_write_b16_d16_hi v180, v98 offset:1360
	ds_write_b16 v180, v99 offset:1504
	ds_write_b16_d16_hi v180, v99 offset:1648
	ds_write_b16 v180, v100 offset:2368
	ds_write_b16_d16_hi v180, v100 offset:2512
	ds_write_b16 v180, v101 offset:2656
	ds_write_b16_d16_hi v180, v101 offset:2800
	ds_write_b16 v180, v102 offset:3520
	ds_write_b16_d16_hi v180, v102 offset:3664
	ds_write_b16 v180, v103 offset:3808
	ds_write_b16_d16_hi v180, v103 offset:3952
	v_cvt_pk_bf16_f32 v112, v112, v113
	v_cvt_pk_bf16_f32 v113, v114, v115
	v_cvt_pk_bf16_f32 v114, v116, v117
	v_cvt_pk_bf16_f32 v115, v118, v119
	v_cvt_pk_bf16_f32 v116, v120, v121
	v_cvt_pk_bf16_f32 v117, v122, v123
	v_cvt_pk_bf16_f32 v118, v124, v125
	v_cvt_pk_bf16_f32 v119, v126, v127
	ds_write_b16 v180, v112 offset:4672
	ds_write_b16_d16_hi v180, v112 offset:4816
	ds_write_b16 v180, v113 offset:4960
	ds_write_b16_d16_hi v180, v113 offset:5104
	ds_write_b16 v180, v114 offset:5824
	ds_write_b16_d16_hi v180, v114 offset:5968
	ds_write_b16 v180, v115 offset:6112
	ds_write_b16_d16_hi v180, v115 offset:6256
	ds_write_b16 v180, v116 offset:6976
	ds_write_b16_d16_hi v180, v116 offset:7120
	ds_write_b16 v180, v117 offset:7264
	ds_write_b16_d16_hi v180, v117 offset:7408
	ds_write_b16 v180, v118 offset:8128
	ds_write_b16_d16_hi v180, v118 offset:8272
	ds_write_b16 v180, v119 offset:8416
	ds_write_b16_d16_hi v180, v119 offset:8560
	s_waitcnt lgkmcnt(0)
	ds_read_b128 v[64:67], v198 offset:0
	ds_read_b128 v[68:71], v198 offset:1152
	ds_read_b128 v[72:75], v198 offset:2304
	ds_read_b128 v[76:79], v198 offset:3456
	ds_read_b128 v[80:83], v198 offset:4608
	ds_read_b128 v[84:87], v198 offset:5760
	ds_read_b128 v[88:91], v198 offset:6912
	ds_read_b128 v[92:95], v198 offset:8064
	s_waitcnt lgkmcnt(7)
	global_store_dwordx4 v199, v[64:67], s[38:39]
	s_add_u32 s38, s38, 0x8000
	s_addc_u32 s39, s39, 0
	s_waitcnt lgkmcnt(6)
	global_store_dwordx4 v199, v[68:71], s[38:39]
	s_add_u32 s38, s38, 0x8000
	s_addc_u32 s39, s39, 0
	s_waitcnt lgkmcnt(5)
	global_store_dwordx4 v199, v[72:75], s[38:39]
	s_add_u32 s38, s38, 0x8000
	s_addc_u32 s39, s39, 0
	s_waitcnt lgkmcnt(4)
	global_store_dwordx4 v199, v[76:79], s[38:39]
	s_add_u32 s38, s38, 0x8000
	s_addc_u32 s39, s39, 0
	s_waitcnt lgkmcnt(3)
	global_store_dwordx4 v199, v[80:83], s[38:39]
	s_add_u32 s38, s38, 0x8000
	s_addc_u32 s39, s39, 0
	s_waitcnt lgkmcnt(2)
	global_store_dwordx4 v199, v[84:87], s[38:39]
	s_add_u32 s38, s38, 0x8000
	s_addc_u32 s39, s39, 0
	s_waitcnt lgkmcnt(1)
	global_store_dwordx4 v199, v[88:91], s[38:39]
	s_add_u32 s38, s38, 0x8000
	s_addc_u32 s39, s39, 0
	s_waitcnt lgkmcnt(0)
	global_store_dwordx4 v199, v[92:95], s[38:39]
.Lpe_ret_L0:
	s_branch .LBB0_128
.LBB0_179:
	s_abs_i32 s0, s90
	v_cvt_f32_u32_e32 v0, s0
	s_sub_i32 s1, 0, s0
	v_readlane_b32 s56, v254, 25
	s_mov_b32 s9, 0
	v_rcp_iflag_f32_e32 v0, v0
	v_readlane_b32 s60, v254, 29
	v_readlane_b32 s61, v254, 30
	v_readlane_b32 s66, v254, 35
	v_mul_f32_e32 v0, 0x4f7ffffe, v0
	v_cvt_u32_f32_e32 v0, v0
	v_readlane_b32 s67, v254, 36
	v_readlane_b32 s68, v254, 37
	v_readlane_b32 s69, v254, 38
	v_readfirstlane_b32 s2, v0
	s_mul_i32 s1, s1, s2
	s_mul_hi_u32 s1, s2, s1
	s_add_i32 s2, s2, s1
	s_mul_hi_u32 s1, s2, 0x43f
	s_mul_i32 s1, s1, s0
	s_sub_i32 s1, 0x43f, s1
	s_sub_i32 s2, s1, s0
	s_cmp_ge_u32 s1, s0
	s_cselect_b32 s1, s2, s1
	s_sub_i32 s2, s1, s0
	s_cmp_ge_u32 s1, s0
	s_cselect_b32 s0, s2, s1
	s_add_i32 s5, s0, 1
	s_sub_i32 s4, s90, s5
	s_cmp_lt_i32 s4, 1
	s_cselect_b64 s[2:3], -1, 0
	s_and_b64 s[0:1], s[2:3], exec
	s_cselect_b32 s0, 0, s5
	s_sub_i32 s8, s88, s0
	s_cmp_gt_i32 s8, -1
	v_readlane_b32 s70, v254, 39
	v_readlane_b32 s71, v254, 40
	v_readlane_b32 s57, v254, 26
	v_readlane_b32 s58, v254, 27
	v_readlane_b32 s59, v254, 28
	v_readlane_b32 s62, v254, 31
	v_readlane_b32 s63, v254, 32
	v_readlane_b32 s64, v254, 33
	v_readlane_b32 s65, v254, 34
	s_cbranch_scc0 .LBB0_189
	s_lshl_b64 s[0:1], s[8:9], 9
	v_ashrrev_i32_e32 v145, 31, v144
	v_lshl_add_u64 v[0:1], s[0:1], 0, v[144:145]
	s_mov_b64 s[0:1], 0xfffff
	v_cmp_lt_u64_e32 vcc, s[0:1], v[0:1]
	s_and_saveexec_b64 s[0:1], vcc
	s_xor_b64 s[0:1], exec, s[0:1]
	s_andn2_saveexec_b64 s[0:1], s[0:1]
	s_cbranch_execz .LBB0_188
	s_and_b64 s[2:3], s[2:3], exec
	s_cselect_b32 s14, s90, s4
	s_add_u32 s10, s21, 0x4120000
	s_addc_u32 s11, s33, 0
	s_add_u32 s12, s60, 0x1000
	s_addc_u32 s13, s61, 0
	s_lshl_b64 s[6:7], s[8:9], 15
	v_lshlrev_b64 v[4:5], 6, v[144:145]
	s_lshl_b64 s[4:5], s[8:9], 20
	v_lshlrev_b64 v[2:3], 11, v[144:145]
	v_lshl_add_u64 v[4:5], s[6:7], 0, v[4:5]
	s_mov_b64 s[6:7], 0x4000000
	s_lshl_b64 s[8:9], s[8:9], 13
	s_ashr_i32 s15, s14, 31
	v_lshl_add_u64 v[2:3], s[4:5], 0, v[2:3]
	v_lshl_add_u64 v[6:7], v[4:5], 0, s[6:7]
	v_lshl_add_u64 v[4:5], v[144:145], 4, s[8:9]
	s_lshl_b64 s[2:3], s[14:15], 9
	s_lshl_b64 s[4:5], s[14:15], 20
	v_lshl_add_u64 v[8:9], s[66:67], 0, v[6:7]
	s_lshl_b64 s[6:7], s[14:15], 15
	s_lshl_b64 s[8:9], s[14:15], 13
	s_mov_b64 s[14:15], 0
	v_mov_b32_e32 v11, 0
	s_mov_b64 s[16:17], 0xfffff
	v_mov_b64_e32 v[12:13], v[4:5]
	v_mov_b64_e32 v[14:15], v[2:3]
	v_mov_b64_e32 v[16:17], v[0:1]

.LBB0_721:
	s_or_b64 exec, exec, s[0:1]
	v_readlane_b32 s2, v254, 41
	v_readlane_b32 s3, v254, 42
	v_mov_b32_e32 v176, v178
	s_mov_b64 s[0:1], 0
	s_andn2_b64 vcc, exec, s[2:3]
	s_waitcnt lgkmcnt(0)
	s_barrier
	s_cbranch_vccnz .LBB0_774
	v_readlane_b32 s2, v254, 0
	v_readlane_b32 s3, v254, 1
	s_add_u32 s4, s2, s0
	s_addc_u32 s5, s3, s1
	s_add_u32 s21, s4, 0xa120000
	s_addc_u32 s47, s5, 0
	s_add_u32 s60, s4, 0x880000
	v_and_b32_e32 v0, 63, v176
	v_lshlrev_b32_e32 v3, 8, v176
	v_lshlrev_b32_e32 v4, 4, v176
	s_movk_i32 s6, 0x70
	s_addc_u32 s61, s5, 0
	v_and_b32_e32 v3, 0x3800, v3
	v_bitop3_b32 v0, v0, s6, v4 bitop3:0x48
	s_add_u32 s0, s4, 0x14920000
	v_and_b32_e32 v1, 31, v176
	v_bfe_u32 v2, v176, 5, 1
	v_or_b32_e32 v177, v0, v3
	v_bitop3_b32 v185, v0, 64, v3 bitop3:0x36
	v_lshrrev_b32_e32 v0, 1, v176
	s_mov_b32 s6, 0x1ffff80
	s_addc_u32 s1, s5, 0
	v_bfe_u32 v3, v176, 1, 3
	v_and_or_b32 v1, v0, s6, v1
	v_bitop3_b32 v0, v2, v0, 7 bitop3:0x78
	s_add_u32 s2, s4, 0x1ad20000
	v_lshlrev_b32_e32 v188, 4, v0
	v_bitop3_b32 v0, v2, v3, 2 bitop3:0x36
	s_addc_u32 s3, s5, 0
	v_lshlrev_b32_e32 v189, 4, v0
	v_bitop3_b32 v0, v2, v3, 4 bitop3:0x36
	s_add_u32 s8, s4, 0x1ada0000
	v_lshlrev_b32_e32 v190, 4, v0
	v_bitop3_b32 v0, v2, v3, 6 bitop3:0x36
	s_addc_u32 s9, s5, 0
	v_lshlrev_b32_e32 v191, 4, v0
	v_and_b32_e32 v0, 64, v179
	s_add_u32 s10, s4, 0x1ade0000
	v_add_u32_e32 v0, 64, v0
	s_addc_u32 s11, s5, 0
	v_lshlrev_b32_e32 v186, 7, v1
	v_lshlrev_b32_e32 v1, 7, v176
	v_cmp_lt_i32_e32 vcc, v184, v0
	v_and_b32_e32 v187, 0x6f80, v1
	s_add_u32 s12, s4, 0xc120008
	v_cndmask_b32_e32 v1, v179, v184, vcc
	v_cmp_lt_i32_e32 vcc, v183, v0
	v_lshlrev_b32_e32 v184, 2, v1
	s_addc_u32 s13, s5, 0
	v_cndmask_b32_e32 v1, v179, v183, vcc
	v_cmp_lt_i32_e32 vcc, v182, v0
	s_lshl_b32 s62, s88, 2
	s_lshl_b32 s63, s90, 2
	v_cndmask_b32_e32 v0, v179, v182, vcc
	s_add_u32 s14, s4, 0xc120108
	s_movk_i32 s18, 0xfe00
	v_lshlrev_b32_e32 v183, 2, v1
	v_lshlrev_b32_e32 v182, 2, v0
	s_addc_u32 s15, s5, 0
	s_mov_b32 s17, 0
	s_movk_i32 s64, 0x410
	v_mov_b32_e32 v145, 0
	s_movk_i32 s65, 0x1c0
	s_mov_b32 s19, -1
	v_mov_b32_e32 v192, 0x358637bd
	s_mov_b32 s66, 0x800000
	s_movk_i32 s67, 0x2200
	s_mov_b32 s20, 0x3e000000
	s_mov_b64 s[22:23], 0x44000
	v_mov_b32_e32 v193, 0x20800
	v_readlane_b32 s85, v254, 22
	s_mov_b32 s80, 0
	s_mov_b32 s86, s88
	s_branch .LBB0_724

.LBB0_724:
	s_lshl_b32 s4, s86, 3
	s_and_b32 s16, s4, 56
	s_bfe_u32 s4, s86, 0x30003
	s_or_b32 s24, s16, s4
	s_lshl_b32 s33, s86, 2
	s_lshr_b32 s25, s86, 3
	s_and_b32 s48, s33, 0xffffff00
	s_lshl_b32 s4, s24, 19
	s_add_u32 s6, s21, s4
	s_addc_u32 s7, s47, 0
	s_ashr_i32 s49, s48, 31
	s_lshl_b64 s[4:5], s[48:49], 11
	s_add_u32 s26, s60, s4
	v_readfirstlane_b32 s4, v176
	s_addc_u32 s27, s61, s5
	s_ashr_i32 s28, s4, 6
	s_lshl_b32 s4, s28, 5
	s_ashr_i32 s5, s4, 31
	s_lshl_b64 s[4:5], s[4:5], 11
	s_add_u32 s6, s6, s4
	s_addc_u32 s7, s7, s5
	s_add_u32 s4, s26, s4
	s_addc_u32 s5, s27, s5
	s_lshl_b32 s26, s28, 12
	s_add_i32 s27, s26, 0x8000
	s_and_b32 s81, s24, 7
	s_lshl_b32 s81, s81, 8
	s_add_u32 s6, s6, s81
	s_addc_u32 s7, s7, 0
	s_add_u32 s4, s4, s81
	s_addc_u32 s5, s5, 0
	s_cmp_eq_u32 s80, 1
	s_cbranch_scc1 .Lpf_skip_L1
	s_add_u32 s28, s6, 0x4000
	s_barrier
	s_mov_b32 m0, s26
	global_load_lds_dwordx4 v177, s[6:7]
	s_addc_u32 s29, s7, 0
	s_or_b32 s30, s26, 0x400
	s_mov_b32 m0, s30
	global_load_lds_dwordx4 v185, s[28:29]
	s_add_u32 s28, s6, 0x8000
	s_addc_u32 s29, s7, 0
	s_or_b32 s30, s26, 0x800
	s_mov_b32 m0, s30
	global_load_lds_dwordx4 v177, s[28:29]
	s_add_u32 s28, s6, 0xc000
	s_addc_u32 s29, s7, 0
	s_or_b32 s30, s26, 0xc00
	s_mov_b32 m0, s30
	global_load_lds_dwordx4 v185, s[28:29]
	s_add_u32 s28, s4, 0x4000
	s_mov_b32 m0, s27
	global_load_lds_dwordx4 v177, s[4:5]
	s_addc_u32 s29, s5, 0
	s_add_i32 s27, s26, 0x8400
	s_mov_b32 m0, s27
	global_load_lds_dwordx4 v185, s[28:29]
	s_add_u32 s28, s4, 0x8000
	s_addc_u32 s29, s5, 0
	s_add_i32 s27, s26, 0x8800
	s_mov_b32 m0, s27
	global_load_lds_dwordx4 v177, s[28:29]
	s_add_u32 s28, s4, 0xc000
	s_addc_u32 s29, s5, 0
	s_add_i32 s27, s26, 0x8c00
	s_mov_b32 m0, s27
	global_load_lds_dwordx4 v185, s[28:29]
.Lpf_skip_L1:
	s_sub_u32 s6, s6, s81
	s_subb_u32 s7, s7, 0
	s_sub_u32 s4, s4, s81
	s_subb_u32 s5, s5, 0
	s_add_u32 s27, s4, 0xc000
	s_addc_u32 s28, s5, 0
	s_add_u32 s29, s4, 0x8000
	s_addc_u32 s30, s5, 0
	s_add_u32 s31, s4, 0x4000
	s_addc_u32 s34, s5, 0
	s_add_u32 s35, s4, 0x0
	s_addc_u32 s36, s5, 0
	s_add_u32 s37, s6, 0xc000
	s_addc_u32 s38, s7, 0
	s_add_u32 s39, s6, 0x8000
	s_addc_u32 s40, s7, 0
	s_add_u32 s41, s6, 0x4000
	s_addc_u32 s42, s7, 0
	s_add_u32 s43, s6, 0x0
	s_addc_u32 s44, s7, 0
	s_mov_b64 s[4:5], 0
	s_mov_b32 s46, s17
	s_mov_b32 s45, s17
	v_mov_b32_e32 v0, v145
	v_mov_b32_e32 v1, v145
	v_mov_b32_e32 v2, v145
	v_mov_b32_e32 v3, v145
	v_mov_b32_e32 v4, v145
	v_mov_b32_e32 v5, v145
	v_mov_b32_e32 v6, v145
	v_mov_b32_e32 v7, v145
	v_mov_b32_e32 v8, v145
	v_mov_b32_e32 v9, v145
	v_mov_b32_e32 v10, v145
	v_mov_b32_e32 v11, v145
	v_mov_b32_e32 v12, v145
	v_mov_b32_e32 v13, v145
	v_mov_b32_e32 v14, v145
	v_mov_b32_e32 v15, v145
	v_mov_b32_e32 v16, v145
	v_mov_b32_e32 v17, v145
	v_mov_b32_e32 v18, v145
	v_mov_b32_e32 v19, v145
	v_mov_b32_e32 v20, v145
	v_mov_b32_e32 v21, v145
	v_mov_b32_e32 v22, v145
	v_mov_b32_e32 v23, v145
	v_mov_b32_e32 v24, v145
	v_mov_b32_e32 v25, v145
	v_mov_b32_e32 v26, v145
	v_mov_b32_e32 v27, v145
	v_mov_b32_e32 v28, v145
	v_mov_b32_e32 v29, v145
	v_mov_b32_e32 v30, v145
	v_mov_b32_e32 v31, v145
	v_mov_b32_e32 v32, v145
	v_mov_b32_e32 v33, v145
	v_mov_b32_e32 v34, v145
	v_mov_b32_e32 v35, v145
	v_mov_b32_e32 v36, v145
	v_mov_b32_e32 v37, v145
	v_mov_b32_e32 v38, v145
	v_mov_b32_e32 v39, v145
	v_mov_b32_e32 v40, v145
	v_mov_b32_e32 v41, v145
	v_mov_b32_e32 v42, v145
	v_mov_b32_e32 v43, v145
	v_mov_b32_e32 v44, v145
	v_mov_b32_e32 v45, v145
	v_mov_b32_e32 v46, v145
	v_mov_b32_e32 v47, v145
	v_mov_b32_e32 v48, v145
	v_mov_b32_e32 v49, v145
	v_mov_b32_e32 v50, v145
	v_mov_b32_e32 v51, v145
	v_mov_b32_e32 v52, v145
	v_mov_b32_e32 v53, v145
	v_mov_b32_e32 v54, v145
	v_mov_b32_e32 v55, v145
	v_mov_b32_e32 v56, v145
	v_mov_b32_e32 v57, v145
	v_mov_b32_e32 v58, v145
	v_mov_b32_e32 v59, v145
	v_mov_b32_e32 v60, v145
	v_mov_b32_e32 v61, v145
	v_mov_b32_e32 v62, v145
	v_mov_b32_e32 v63, v145
	v_mov_b32_e32 v64, v145
	v_mov_b32_e32 v65, v145
	v_mov_b32_e32 v66, v145
	v_mov_b32_e32 v67, v145
	v_mov_b32_e32 v68, v145
	v_mov_b32_e32 v69, v145
	v_mov_b32_e32 v70, v145
	v_mov_b32_e32 v71, v145
	v_mov_b32_e32 v72, v145
	v_mov_b32_e32 v73, v145
	v_mov_b32_e32 v74, v145
	v_mov_b32_e32 v75, v145
	v_mov_b32_e32 v76, v145
	v_mov_b32_e32 v77, v145
	v_mov_b32_e32 v78, v145
	v_mov_b32_e32 v79, v145
	v_mov_b32_e32 v80, v145
	v_mov_b32_e32 v81, v145
	v_mov_b32_e32 v82, v145
	v_mov_b32_e32 v83, v145
	v_mov_b32_e32 v84, v145
	v_mov_b32_e32 v85, v145
	v_mov_b32_e32 v86, v145
	v_mov_b32_e32 v87, v145
	v_mov_b32_e32 v88, v145
	v_mov_b32_e32 v89, v145
	v_mov_b32_e32 v90, v145
	v_mov_b32_e32 v91, v145
	v_mov_b32_e32 v92, v145
	v_mov_b32_e32 v93, v145
	v_mov_b32_e32 v94, v145
	v_mov_b32_e32 v95, v145
	v_mov_b32_e32 v96, v145
	v_mov_b32_e32 v97, v145
	v_mov_b32_e32 v98, v145
	v_mov_b32_e32 v99, v145
	v_mov_b32_e32 v100, v145
	v_mov_b32_e32 v101, v145
	v_mov_b32_e32 v102, v145
	v_mov_b32_e32 v103, v145
	v_mov_b32_e32 v104, v145
	v_mov_b32_e32 v105, v145
	v_mov_b32_e32 v106, v145
	v_mov_b32_e32 v107, v145
	v_mov_b32_e32 v108, v145
	v_mov_b32_e32 v109, v145
	v_mov_b32_e32 v110, v145
	v_mov_b32_e32 v111, v145
	v_mov_b32_e32 v112, v145
	v_mov_b32_e32 v113, v145
	v_mov_b32_e32 v114, v145
	v_mov_b32_e32 v115, v145
	v_mov_b32_e32 v116, v145
	v_mov_b32_e32 v117, v145
	v_mov_b32_e32 v118, v145
	v_mov_b32_e32 v119, v145
	v_mov_b32_e32 v120, v145
	v_mov_b32_e32 v121, v145
	v_mov_b32_e32 v122, v145
	v_mov_b32_e32 v123, v145
	v_mov_b32_e32 v124, v145
	v_mov_b32_e32 v125, v145
	v_mov_b32_e32 v126, v145
	v_mov_b32_e32 v127, v145
	s_cmp_eq_u32 s80, 1
	s_cbranch_scc0 .LBB0_726
	s_mov_b32 s80, 0
	s_waitcnt vmcnt(16)
	s_barrier
	s_branch .Lkin_L1

.Lkin_L1:
	s_cmp_lt_u32 s45, 15
	s_mov_b64 s[6:7], -1
	s_cbranch_scc1 .LBB0_728
	s_add_i32 s50, s46, 0x10000
	s_mov_b64 s[6:7], 0

.LBB0_730:
	s_mov_b32 s98, 1
	s_mov_b32 s99, s86

.Lpe_notv_L1:
	s_cmp_ge_u32 s25, 9
	s_cbranch_scc1 .Lpe_gates_L1
	s_lshr_b32 s34, s25, 1
	s_cmp_ge_u32 s25, 6
	s_cselect_b32 s35, 1, 0
	s_sub_u32 s34, s34, s35
	s_lshl_b32 s35, s98, 2
	s_add_u32 s35, s35, s34
	s_lshl_b32 s35, s35, 8
	v_readlane_b32 s82, v254, 14
	v_readlane_b32 s83, v254, 15
	s_add_u32 s82, s82, s35
	s_addc_u32 s83, s83, 0
	global_load_dwordx4 v[198:201], v146, s[82:83] offset:0
	global_load_dwordx4 v[202:205], v146, s[82:83] offset:32
	global_load_dwordx4 v[206:209], v146, s[82:83] offset:64
	global_load_dwordx4 v[210:213], v146, s[82:83] offset:96
	global_load_dwordx4 v[214:217], v146, s[82:83] offset:128
	global_load_dwordx4 v[218:221], v146, s[82:83] offset:160
	global_load_dwordx4 v[222:225], v146, s[82:83] offset:192
	global_load_dwordx4 v[226:229], v146, s[82:83] offset:224
	s_and_b32 s35, s34, 1
	s_cmp_eq_u32 s35, 0
	s_cselect_b32 s36, 0x3e000000, 1.0
	s_and_b32 s35, s29, 0x7ff
	s_lshl_b32 s35, s35, 7
	s_add_u32 s96, s72, 0x1ada0000
	s_addc_u32 s97, s73, 0
	s_add_u32 s96, s96, s35
	s_addc_u32 s97, s97, 0
	s_add_u32 s100, s96, 0x40000
	s_addc_u32 s101, s97, 0
	s_cmp_ge_u32 s34, 2
	s_cselect_b32 s37, 1, 0
	s_waitcnt vmcnt(8)
	v_lshlrev_b32_e32 v180, 7, v197
	v_add_u32_e32 v180, v180, v146
	v_mov_b32_e32 v197, 0x358637bd
	v_pk_add_f32 v[128:129], v[128:129], v[130:131]
	v_pk_add_f32 v[132:133], v[132:133], v[134:135]
	v_pk_add_f32 v[136:137], v[136:137], v[138:139]
	v_pk_add_f32 v[140:141], v[140:141], v[142:143]
	v_pk_add_f32 v[164:165], v[164:165], v[166:167]
	v_pk_add_f32 v[168:169], v[168:169], v[170:171]
	v_pk_add_f32 v[246:247], v[246:247], v[248:249]
	v_pk_add_f32 v[250:251], v[250:251], v[252:253]
	v_pk_add_f32 v[128:129], v[128:129], v[132:133]
	v_pk_add_f32 v[136:137], v[136:137], v[140:141]
	v_pk_add_f32 v[164:165], v[164:165], v[168:169]
	v_pk_add_f32 v[246:247], v[246:247], v[250:251]
	v_add_f32_e32 v128, v128, v129
	v_add_f32_e32 v136, v136, v137
	v_add_f32_e32 v164, v164, v165
	v_add_f32_e32 v246, v246, v247
	v_fmamk_f32 v128, v128, 0x3a800000, v197
	v_fmamk_f32 v136, v136, 0x3a800000, v197
	v_fmamk_f32 v164, v164, 0x3a800000, v197
	v_fmamk_f32 v246, v246, 0x3a800000, v197
	v_rsq_f32_e32 v172, v128
	v_rsq_f32_e32 v173, v136
	v_rsq_f32_e32 v174, v164
	v_rsq_f32_e32 v175, v246
	s_nop 0
	s_add_u32 s76, s99, s90
	s_cmp_lt_u32 s76, 0x440
	s_cselect_b32 s80, 1, 0
	s_cselect_b32 s83, 0x200000, 0
	s_lshl_b32 s76, s24, 19
	s_lshl_b32 s77, s26, 16
	s_add_u32 s76, s76, s77
	s_and_b32 s77, s24, 7
	s_lshl_b32 s77, s77, 8
	s_add_u32 s76, s76, s77
	s_add_u32 s78, s72, 0xa120000
	s_addc_u32 s79, s73, 0
	s_add_u32 s78, s78, s76
	s_addc_u32 s79, s79, 0
	s_lshl_b32 s76, s25, 19
	s_add_u32 s76, s76, s83
	s_add_u32 s76, s76, s77
	s_lshl_b32 s77, s26, 16
	s_add_u32 s76, s76, s77
	s_add_u32 s82, s72, 0x880000
	s_addc_u32 s83, s73, 0
	s_add_u32 s82, s82, s76
	s_addc_u32 s83, s83, 0
	s_lshl_b32 s76, s26, 12
	s_mov_b32 m0, s76
	s_nop 0
	global_load_lds_dwordx4 v177, s[78:79]
	s_add_u32 s78, s78, 0x4000
	s_addc_u32 s79, s79, 0
	s_add_u32 s76, s76, 0x400
	s_mov_b32 m0, s76
	s_nop 0
	global_load_lds_dwordx4 v185, s[78:79]
	s_add_u32 s78, s78, 0x4000
	s_addc_u32 s79, s79, 0
	s_add_u32 s76, s76, 0x400
	s_mov_b32 m0, s76
	s_nop 0
	global_load_lds_dwordx4 v177, s[78:79]
	s_add_u32 s78, s78, 0x4000
	s_addc_u32 s79, s79, 0
	s_add_u32 s76, s76, 0x400
	s_mov_b32 m0, s76
	s_nop 0
	global_load_lds_dwordx4 v185, s[78:79]
	s_add_u32 s78, s78, 0x4000
	s_addc_u32 s79, s79, 0
	s_add_u32 s76, s76, 0x400
	s_add_u32 s76, s76, 0x7000
	s_mov_b32 m0, s76
	s_nop 0
	global_load_lds_dwordx4 v177, s[82:83]
	s_add_u32 s82, s82, 0x4000
	s_addc_u32 s83, s83, 0
	s_add_u32 s76, s76, 0x400
	s_mov_b32 m0, s76
	s_nop 0
	global_load_lds_dwordx4 v185, s[82:83]
	s_add_u32 s82, s82, 0x4000
	s_addc_u32 s83, s83, 0
	s_add_u32 s76, s76, 0x400
	s_mov_b32 m0, s76
	s_nop 0
	global_load_lds_dwordx4 v177, s[82:83]
	s_add_u32 s82, s82, 0x4000
	s_addc_u32 s83, s83, 0
	s_add_u32 s76, s76, 0x400
	s_mov_b32 m0, s76
	s_nop 0
	global_load_lds_dwordx4 v185, s[82:83]
	s_add_u32 s82, s82, 0x4000
	s_addc_u32 s83, s83, 0
	s_add_u32 s76, s76, 0x400
	s_cmp_eq_u32 s37, 0
	s_cbranch_scc1 .Lpe_norope_ld_L1
	global_load_dwordx4 v[230:233], v180, s[96:97] offset:0
	global_load_dwordx4 v[234:237], v180, s[96:97] offset:32
	global_load_dwordx4 v[238:241], v180, s[96:97] offset:64
	global_load_dwordx4 v[242:245], v180, s[96:97] offset:96
	global_load_dwordx4 v[148:151], v180, s[100:101] offset:0
	global_load_dwordx4 v[152:155], v180, s[100:101] offset:32
	global_load_dwordx4 v[156:159], v180, s[100:101] offset:64
	global_load_dwordx4 v[160:163], v180, s[100:101] offset:96

.Lpe_gates_L1:
	s_lshl_b32 s35, s98, 11
	s_add_u32 s35, s35, s30
	s_sub_u32 s35, s35, 0x900
	s_lshl_b32 s35, s35, 2
	v_readlane_b32 s82, v254, 12
	v_readlane_b32 s83, v254, 13
	s_add_u32 s82, s82, s35
	s_addc_u32 s83, s83, 0
	global_load_dwordx4 v[198:201], v146, s[82:83] offset:0
	global_load_dwordx4 v[202:205], v146, s[82:83] offset:32
	global_load_dwordx4 v[206:209], v146, s[82:83] offset:64
	global_load_dwordx4 v[210:213], v146, s[82:83] offset:96
	global_load_dwordx4 v[214:217], v146, s[82:83] offset:128
	global_load_dwordx4 v[218:221], v146, s[82:83] offset:160
	global_load_dwordx4 v[222:225], v146, s[82:83] offset:192
	global_load_dwordx4 v[226:229], v146, s[82:83] offset:224
	s_waitcnt vmcnt(8)
	v_mov_b32_e32 v197, 0x358637bd
	v_pk_add_f32 v[128:129], v[128:129], v[130:131]
	v_pk_add_f32 v[132:133], v[132:133], v[134:135]
	v_pk_add_f32 v[136:137], v[136:137], v[138:139]
	v_pk_add_f32 v[140:141], v[140:141], v[142:143]
	v_pk_add_f32 v[164:165], v[164:165], v[166:167]
	v_pk_add_f32 v[168:169], v[168:169], v[170:171]
	v_pk_add_f32 v[246:247], v[246:247], v[248:249]
	v_pk_add_f32 v[250:251], v[250:251], v[252:253]
	v_pk_add_f32 v[128:129], v[128:129], v[132:133]
	v_pk_add_f32 v[136:137], v[136:137], v[140:141]
	v_pk_add_f32 v[164:165], v[164:165], v[168:169]
	v_pk_add_f32 v[246:247], v[246:247], v[250:251]
	v_add_f32_e32 v128, v128, v129
	v_add_f32_e32 v136, v136, v137
	v_add_f32_e32 v164, v164, v165
	v_add_f32_e32 v246, v246, v247
	v_fmamk_f32 v128, v128, 0x3a800000, v197
	v_fmamk_f32 v136, v136, 0x3a800000, v197
	v_fmamk_f32 v164, v164, 0x3a800000, v197
	v_fmamk_f32 v246, v246, 0x3a800000, v197
	v_rsq_f32_e32 v172, v128
	v_rsq_f32_e32 v173, v136
	v_rsq_f32_e32 v174, v164
	v_rsq_f32_e32 v175, v246
	s_nop 0
	s_add_u32 s76, s99, s90
	s_cmp_lt_u32 s76, 0x440
	s_cselect_b32 s80, 1, 0
	s_cselect_b32 s83, 0x200000, 0
	s_lshl_b32 s76, s24, 19
	s_lshl_b32 s77, s26, 16
	s_add_u32 s76, s76, s77
	s_and_b32 s77, s24, 7
	s_lshl_b32 s77, s77, 8
	s_add_u32 s76, s76, s77
	s_add_u32 s78, s72, 0xa120000
	s_addc_u32 s79, s73, 0
	s_add_u32 s78, s78, s76
	s_addc_u32 s79, s79, 0
	s_lshl_b32 s76, s25, 19
	s_add_u32 s76, s76, s83
	s_add_u32 s76, s76, s77
	s_lshl_b32 s77, s26, 16
	s_add_u32 s76, s76, s77
	s_add_u32 s82, s72, 0x880000
	s_addc_u32 s83, s73, 0
	s_add_u32 s82, s82, s76
	s_addc_u32 s83, s83, 0
	s_lshl_b32 s76, s26, 12
	s_mov_b32 m0, s76
	s_nop 0
	global_load_lds_dwordx4 v177, s[78:79]
	s_add_u32 s78, s78, 0x4000
	s_addc_u32 s79, s79, 0
	s_add_u32 s76, s76, 0x400
	s_mov_b32 m0, s76
	s_nop 0
	global_load_lds_dwordx4 v185, s[78:79]
	s_add_u32 s78, s78, 0x4000
	s_addc_u32 s79, s79, 0
	s_add_u32 s76, s76, 0x400
	s_mov_b32 m0, s76
	s_nop 0
	global_load_lds_dwordx4 v177, s[78:79]
	s_add_u32 s78, s78, 0x4000
	s_addc_u32 s79, s79, 0
	s_add_u32 s76, s76, 0x400
	s_mov_b32 m0, s76
	s_nop 0
	global_load_lds_dwordx4 v185, s[78:79]
	s_add_u32 s78, s78, 0x4000
	s_addc_u32 s79, s79, 0
	s_add_u32 s76, s76, 0x400
	s_add_u32 s76, s76, 0x7000
	s_mov_b32 m0, s76
	s_nop 0
	global_load_lds_dwordx4 v177, s[82:83]
	s_add_u32 s82, s82, 0x4000
	s_addc_u32 s83, s83, 0
	s_add_u32 s76, s76, 0x400
	s_mov_b32 m0, s76
	s_nop 0
	global_load_lds_dwordx4 v185, s[82:83]
	s_add_u32 s82, s82, 0x4000
	s_addc_u32 s83, s83, 0
	s_add_u32 s76, s76, 0x400
	s_mov_b32 m0, s76
	s_nop 0
	global_load_lds_dwordx4 v177, s[82:83]
	s_add_u32 s82, s82, 0x4000
	s_addc_u32 s83, s83, 0
	s_add_u32 s76, s76, 0x400
	s_mov_b32 m0, s76
	s_nop 0
	global_load_lds_dwordx4 v185, s[82:83]
	s_add_u32 s82, s82, 0x4000
	s_addc_u32 s83, s83, 0
	s_add_u32 s76, s76, 0x400
	v_mul_f32_e32 v172, 0xbfb8aa3b, v172
	v_mul_f32_e32 v173, 0xbfb8aa3b, v173
	v_mul_f32_e32 v174, 0xbfb8aa3b, v174
	v_mul_f32_e32 v175, 0xbfb8aa3b, v175
	s_waitcnt vmcnt(8)
	v_mul_f32_e32 v198, 0xbfb8aa3b, v198
	v_mul_f32_e32 v199, 0xbfb8aa3b, v199
	v_mul_f32_e32 v200, 0xbfb8aa3b, v200
	v_mul_f32_e32 v201, 0xbfb8aa3b, v201
	v_mul_f32_e32 v202, 0xbfb8aa3b, v202
	v_mul_f32_e32 v203, 0xbfb8aa3b, v203
	v_mul_f32_e32 v204, 0xbfb8aa3b, v204
	v_mul_f32_e32 v205, 0xbfb8aa3b, v205
	v_mul_f32_e32 v206, 0xbfb8aa3b, v206
	v_mul_f32_e32 v207, 0xbfb8aa3b, v207
	v_mul_f32_e32 v208, 0xbfb8aa3b, v208
	v_mul_f32_e32 v209, 0xbfb8aa3b, v209
	v_mul_f32_e32 v210, 0xbfb8aa3b, v210
	v_mul_f32_e32 v211, 0xbfb8aa3b, v211
	v_mul_f32_e32 v212, 0xbfb8aa3b, v212
	v_mul_f32_e32 v213, 0xbfb8aa3b, v213
	v_mul_f32_e32 v214, 0xbfb8aa3b, v214
	v_mul_f32_e32 v215, 0xbfb8aa3b, v215
	v_mul_f32_e32 v216, 0xbfb8aa3b, v216
	v_mul_f32_e32 v217, 0xbfb8aa3b, v217
	v_mul_f32_e32 v218, 0xbfb8aa3b, v218
	v_mul_f32_e32 v219, 0xbfb8aa3b, v219
	v_mul_f32_e32 v220, 0xbfb8aa3b, v220
	v_mul_f32_e32 v221, 0xbfb8aa3b, v221
	v_mul_f32_e32 v222, 0xbfb8aa3b, v222
	v_mul_f32_e32 v223, 0xbfb8aa3b, v223
	v_mul_f32_e32 v224, 0xbfb8aa3b, v224
	v_mul_f32_e32 v225, 0xbfb8aa3b, v225
	v_mul_f32_e32 v226, 0xbfb8aa3b, v226
	v_mul_f32_e32 v227, 0xbfb8aa3b, v227
	v_mul_f32_e32 v228, 0xbfb8aa3b, v228
	v_mul_f32_e32 v229, 0xbfb8aa3b, v229
	v_pk_fma_f32 v[0:1], v[0:1], v[172:173], v[198:199] op_sel_hi:[1,0,1]
	v_pk_fma_f32 v[2:3], v[2:3], v[172:173], v[200:201] op_sel_hi:[1,0,1]
	v_pk_fma_f32 v[4:5], v[4:5], v[172:173], v[202:203] op_sel_hi:[1,0,1]
	v_pk_fma_f32 v[6:7], v[6:7], v[172:173], v[204:205] op_sel_hi:[1,0,1]
	v_pk_fma_f32 v[8:9], v[8:9], v[172:173], v[206:207] op_sel_hi:[1,0,1]
	v_pk_fma_f32 v[10:11], v[10:11], v[172:173], v[208:209] op_sel_hi:[1,0,1]
	v_pk_fma_f32 v[12:13], v[12:13], v[172:173], v[210:211] op_sel_hi:[1,0,1]
	v_pk_fma_f32 v[14:15], v[14:15], v[172:173], v[212:213] op_sel_hi:[1,0,1]
	v_pk_fma_f32 v[16:17], v[16:17], v[172:173], v[214:215] op_sel_hi:[1,0,1]
	v_pk_fma_f32 v[18:19], v[18:19], v[172:173], v[216:217] op_sel_hi:[1,0,1]
	v_pk_fma_f32 v[20:21], v[20:21], v[172:173], v[218:219] op_sel_hi:[1,0,1]
	v_pk_fma_f32 v[22:23], v[22:23], v[172:173], v[220:221] op_sel_hi:[1,0,1]
	v_pk_fma_f32 v[24:25], v[24:25], v[172:173], v[222:223] op_sel_hi:[1,0,1]
	v_pk_fma_f32 v[26:27], v[26:27], v[172:173], v[224:225] op_sel_hi:[1,0,1]
	v_pk_fma_f32 v[28:29], v[28:29], v[172:173], v[226:227] op_sel_hi:[1,0,1]
	v_pk_fma_f32 v[30:31], v[30:31], v[172:173], v[228:229] op_sel_hi:[1,0,1]
	v_exp_f32_e32 v0, v0
	v_exp_f32_e32 v1, v1
	v_exp_f32_e32 v2, v2
	v_exp_f32_e32 v3, v3
	v_exp_f32_e32 v4, v4
	v_exp_f32_e32 v5, v5
	v_exp_f32_e32 v6, v6
	v_exp_f32_e32 v7, v7
	v_exp_f32_e32 v8, v8
	v_exp_f32_e32 v9, v9
	v_exp_f32_e32 v10, v10
	v_exp_f32_e32 v11, v11
	v_exp_f32_e32 v12, v12
	v_exp_f32_e32 v13, v13
	v_exp_f32_e32 v14, v14
	v_exp_f32_e32 v15, v15
	v_exp_f32_e32 v16, v16
	v_exp_f32_e32 v17, v17
	v_exp_f32_e32 v18, v18
	v_exp_f32_e32 v19, v19
	v_exp_f32_e32 v20, v20
	v_exp_f32_e32 v21, v21
	v_exp_f32_e32 v22, v22
	v_exp_f32_e32 v23, v23
	v_exp_f32_e32 v24, v24
	v_exp_f32_e32 v25, v25
	v_exp_f32_e32 v26, v26
	v_exp_f32_e32 v27, v27
	v_exp_f32_e32 v28, v28
	v_exp_f32_e32 v29, v29
	v_exp_f32_e32 v30, v30
	v_exp_f32_e32 v31, v31
	v_pk_add_f32 v[0:1], v[0:1], 1.0 op_sel_hi:[1,0]
	v_pk_add_f32 v[2:3], v[2:3], 1.0 op_sel_hi:[1,0]
	v_pk_add_f32 v[4:5], v[4:5], 1.0 op_sel_hi:[1,0]
	v_pk_add_f32 v[6:7], v[6:7], 1.0 op_sel_hi:[1,0]
	v_pk_add_f32 v[8:9], v[8:9], 1.0 op_sel_hi:[1,0]
	v_pk_add_f32 v[10:11], v[10:11], 1.0 op_sel_hi:[1,0]
	v_pk_add_f32 v[12:13], v[12:13], 1.0 op_sel_hi:[1,0]
	v_pk_add_f32 v[14:15], v[14:15], 1.0 op_sel_hi:[1,0]
	v_pk_add_f32 v[16:17], v[16:17], 1.0 op_sel_hi:[1,0]
	v_pk_add_f32 v[18:19], v[18:19], 1.0 op_sel_hi:[1,0]
	v_pk_add_f32 v[20:21], v[20:21], 1.0 op_sel_hi:[1,0]
	v_pk_add_f32 v[22:23], v[22:23], 1.0 op_sel_hi:[1,0]
	v_pk_add_f32 v[24:25], v[24:25], 1.0 op_sel_hi:[1,0]
	v_pk_add_f32 v[26:27], v[26:27], 1.0 op_sel_hi:[1,0]
	v_pk_add_f32 v[28:29], v[28:29], 1.0 op_sel_hi:[1,0]
	v_pk_add_f32 v[30:31], v[30:31], 1.0 op_sel_hi:[1,0]
	v_rcp_f32_e32 v0, v0
	v_rcp_f32_e32 v1, v1
	v_rcp_f32_e32 v2, v2
	v_rcp_f32_e32 v3, v3
	v_rcp_f32_e32 v4, v4
	v_rcp_f32_e32 v5, v5
	v_rcp_f32_e32 v6, v6
	v_rcp_f32_e32 v7, v7
	v_rcp_f32_e32 v8, v8
	v_rcp_f32_e32 v9, v9
	v_rcp_f32_e32 v10, v10
	v_rcp_f32_e32 v11, v11
	v_rcp_f32_e32 v12, v12
	v_rcp_f32_e32 v13, v13
	v_rcp_f32_e32 v14, v14
	v_rcp_f32_e32 v15, v15
	v_rcp_f32_e32 v16, v16
	v_rcp_f32_e32 v17, v17
	v_rcp_f32_e32 v18, v18
	v_rcp_f32_e32 v19, v19
	v_rcp_f32_e32 v20, v20
	v_rcp_f32_e32 v21, v21
	v_rcp_f32_e32 v22, v22
	v_rcp_f32_e32 v23, v23
	v_rcp_f32_e32 v24, v24
	v_rcp_f32_e32 v25, v25
	v_rcp_f32_e32 v26, v26
	v_rcp_f32_e32 v27, v27
	v_rcp_f32_e32 v28, v28
	v_rcp_f32_e32 v29, v29
	v_rcp_f32_e32 v30, v30
	v_rcp_f32_e32 v31, v31
	s_nop 0
	v_cvt_pk_bf16_f32 v0, v0, v1
	v_cvt_pk_bf16_f32 v1, v2, v3
	v_cvt_pk_bf16_f32 v2, v4, v5
	v_cvt_pk_bf16_f32 v3, v6, v7
	v_cvt_pk_bf16_f32 v4, v8, v9
	v_cvt_pk_bf16_f32 v5, v10, v11
	v_cvt_pk_bf16_f32 v6, v12, v13
	v_cvt_pk_bf16_f32 v7, v14, v15
	v_cvt_pk_bf16_f32 v16, v16, v17
	v_cvt_pk_bf16_f32 v17, v18, v19
	v_cvt_pk_bf16_f32 v18, v20, v21
	v_cvt_pk_bf16_f32 v19, v22, v23
	v_cvt_pk_bf16_f32 v20, v24, v25
	v_cvt_pk_bf16_f32 v21, v26, v27
	v_cvt_pk_bf16_f32 v22, v28, v29
	v_cvt_pk_bf16_f32 v23, v30, v31
	v_permlane32_swap_b32_e32 v0, v2
	v_permlane32_swap_b32_e32 v1, v3
	v_permlane32_swap_b32_e32 v4, v6
	v_permlane32_swap_b32_e32 v5, v7
	v_permlane32_swap_b32_e32 v16, v18
	v_permlane32_swap_b32_e32 v17, v19
	v_permlane32_swap_b32_e32 v20, v22
	v_permlane32_swap_b32_e32 v21, v23
	global_store_dwordx4 v181, v[0:3], s[74:75] offset:0
	global_store_dwordx4 v181, v[4:7], s[74:75] offset:32
	global_store_dwordx4 v181, v[16:19], s[74:75] offset:64
	global_store_dwordx4 v181, v[20:23], s[74:75] offset:96
	s_add_u32 s74, s74, 0x44000
	s_addc_u32 s75, s75, 0
	v_pk_fma_f32 v[32:33], v[32:33], v[172:173], v[198:199] op_sel:[0,1,0] op_sel_hi:[1,1,1]
	v_pk_fma_f32 v[34:35], v[34:35], v[172:173], v[200:201] op_sel:[0,1,0] op_sel_hi:[1,1,1]
	v_pk_fma_f32 v[36:37], v[36:37], v[172:173], v[202:203] op_sel:[0,1,0] op_sel_hi:[1,1,1]
	v_pk_fma_f32 v[38:39], v[38:39], v[172:173], v[204:205] op_sel:[0,1,0] op_sel_hi:[1,1,1]
	v_pk_fma_f32 v[40:41], v[40:41], v[172:173], v[206:207] op_sel:[0,1,0] op_sel_hi:[1,1,1]
	v_pk_fma_f32 v[42:43], v[42:43], v[172:173], v[208:209] op_sel:[0,1,0] op_sel_hi:[1,1,1]
	v_pk_fma_f32 v[44:45], v[44:45], v[172:173], v[210:211] op_sel:[0,1,0] op_sel_hi:[1,1,1]
	v_pk_fma_f32 v[46:47], v[46:47], v[172:173], v[212:213] op_sel:[0,1,0] op_sel_hi:[1,1,1]
	v_pk_fma_f32 v[48:49], v[48:49], v[172:173], v[214:215] op_sel:[0,1,0] op_sel_hi:[1,1,1]
	v_pk_fma_f32 v[50:51], v[50:51], v[172:173], v[216:217] op_sel:[0,1,0] op_sel_hi:[1,1,1]
	v_pk_fma_f32 v[52:53], v[52:53], v[172:173], v[218:219] op_sel:[0,1,0] op_sel_hi:[1,1,1]
	v_pk_fma_f32 v[54:55], v[54:55], v[172:173], v[220:221] op_sel:[0,1,0] op_sel_hi:[1,1,1]
	v_pk_fma_f32 v[56:57], v[56:57], v[172:173], v[222:223] op_sel:[0,1,0] op_sel_hi:[1,1,1]
	v_pk_fma_f32 v[58:59], v[58:59], v[172:173], v[224:225] op_sel:[0,1,0] op_sel_hi:[1,1,1]
	v_pk_fma_f32 v[60:61], v[60:61], v[172:173], v[226:227] op_sel:[0,1,0] op_sel_hi:[1,1,1]
	v_pk_fma_f32 v[62:63], v[62:63], v[172:173], v[228:229] op_sel:[0,1,0] op_sel_hi:[1,1,1]
	v_exp_f32_e32 v32, v32
	v_exp_f32_e32 v33, v33
	v_exp_f32_e32 v34, v34
	v_exp_f32_e32 v35, v35
	v_exp_f32_e32 v36, v36
	v_exp_f32_e32 v37, v37
	v_exp_f32_e32 v38, v38
	v_exp_f32_e32 v39, v39
	v_exp_f32_e32 v40, v40
	v_exp_f32_e32 v41, v41
	v_exp_f32_e32 v42, v42
	v_exp_f32_e32 v43, v43
	v_exp_f32_e32 v44, v44
	v_exp_f32_e32 v45, v45
	v_exp_f32_e32 v46, v46
	v_exp_f32_e32 v47, v47
	v_exp_f32_e32 v48, v48
	v_exp_f32_e32 v49, v49
	v_exp_f32_e32 v50, v50
	v_exp_f32_e32 v51, v51
	v_exp_f32_e32 v52, v52
	v_exp_f32_e32 v53, v53
	v_exp_f32_e32 v54, v54
	v_exp_f32_e32 v55, v55
	v_exp_f32_e32 v56, v56
	v_exp_f32_e32 v57, v57
	v_exp_f32_e32 v58, v58
	v_exp_f32_e32 v59, v59
	v_exp_f32_e32 v60, v60
	v_exp_f32_e32 v61, v61
	v_exp_f32_e32 v62, v62
	v_exp_f32_e32 v63, v63
	v_pk_add_f32 v[32:33], v[32:33], 1.0 op_sel_hi:[1,0]
	v_pk_add_f32 v[34:35], v[34:35], 1.0 op_sel_hi:[1,0]
	v_pk_add_f32 v[36:37], v[36:37], 1.0 op_sel_hi:[1,0]
	v_pk_add_f32 v[38:39], v[38:39], 1.0 op_sel_hi:[1,0]
	v_pk_add_f32 v[40:41], v[40:41], 1.0 op_sel_hi:[1,0]
	v_pk_add_f32 v[42:43], v[42:43], 1.0 op_sel_hi:[1,0]
	v_pk_add_f32 v[44:45], v[44:45], 1.0 op_sel_hi:[1,0]
	v_pk_add_f32 v[46:47], v[46:47], 1.0 op_sel_hi:[1,0]
	v_pk_add_f32 v[48:49], v[48:49], 1.0 op_sel_hi:[1,0]
	v_pk_add_f32 v[50:51], v[50:51], 1.0 op_sel_hi:[1,0]
	v_pk_add_f32 v[52:53], v[52:53], 1.0 op_sel_hi:[1,0]
	v_pk_add_f32 v[54:55], v[54:55], 1.0 op_sel_hi:[1,0]
	v_pk_add_f32 v[56:57], v[56:57], 1.0 op_sel_hi:[1,0]
	v_pk_add_f32 v[58:59], v[58:59], 1.0 op_sel_hi:[1,0]
	v_pk_add_f32 v[60:61], v[60:61], 1.0 op_sel_hi:[1,0]
	v_pk_add_f32 v[62:63], v[62:63], 1.0 op_sel_hi:[1,0]
	v_rcp_f32_e32 v32, v32
	v_rcp_f32_e32 v33, v33
	v_rcp_f32_e32 v34, v34
	v_rcp_f32_e32 v35, v35
	v_rcp_f32_e32 v36, v36
	v_rcp_f32_e32 v37, v37
	v_rcp_f32_e32 v38, v38
	v_rcp_f32_e32 v39, v39
	v_rcp_f32_e32 v40, v40
	v_rcp_f32_e32 v41, v41
	v_rcp_f32_e32 v42, v42
	v_rcp_f32_e32 v43, v43
	v_rcp_f32_e32 v44, v44
	v_rcp_f32_e32 v45, v45
	v_rcp_f32_e32 v46, v46
	v_rcp_f32_e32 v47, v47
	v_rcp_f32_e32 v48, v48
	v_rcp_f32_e32 v49, v49
	v_rcp_f32_e32 v50, v50
	v_rcp_f32_e32 v51, v51
	v_rcp_f32_e32 v52, v52
	v_rcp_f32_e32 v53, v53
	v_rcp_f32_e32 v54, v54
	v_rcp_f32_e32 v55, v55
	v_rcp_f32_e32 v56, v56
	v_rcp_f32_e32 v57, v57
	v_rcp_f32_e32 v58, v58
	v_rcp_f32_e32 v59, v59
	v_rcp_f32_e32 v60, v60
	v_rcp_f32_e32 v61, v61
	v_rcp_f32_e32 v62, v62
	v_rcp_f32_e32 v63, v63
	s_nop 0
	v_cvt_pk_bf16_f32 v32, v32, v33
	v_cvt_pk_bf16_f32 v33, v34, v35
	v_cvt_pk_bf16_f32 v34, v36, v37
	v_cvt_pk_bf16_f32 v35, v38, v39
	v_cvt_pk_bf16_f32 v36, v40, v41
	v_cvt_pk_bf16_f32 v37, v42, v43
	v_cvt_pk_bf16_f32 v38, v44, v45
	v_cvt_pk_bf16_f32 v39, v46, v47
	v_cvt_pk_bf16_f32 v48, v48, v49
	v_cvt_pk_bf16_f32 v49, v50, v51
	v_cvt_pk_bf16_f32 v50, v52, v53
	v_cvt_pk_bf16_f32 v51, v54, v55
	v_cvt_pk_bf16_f32 v52, v56, v57
	v_cvt_pk_bf16_f32 v53, v58, v59
	v_cvt_pk_bf16_f32 v54, v60, v61
	v_cvt_pk_bf16_f32 v55, v62, v63
	v_permlane32_swap_b32_e32 v32, v34
	v_permlane32_swap_b32_e32 v33, v35
	v_permlane32_swap_b32_e32 v36, v38
	v_permlane32_swap_b32_e32 v37, v39
	v_permlane32_swap_b32_e32 v48, v50
	v_permlane32_swap_b32_e32 v49, v51
	v_permlane32_swap_b32_e32 v52, v54
	v_permlane32_swap_b32_e32 v53, v55
	global_store_dwordx4 v181, v[32:35], s[74:75] offset:0
	global_store_dwordx4 v181, v[36:39], s[74:75] offset:32
	global_store_dwordx4 v181, v[48:51], s[74:75] offset:64
	global_store_dwordx4 v181, v[52:55], s[74:75] offset:96
	s_add_u32 s74, s74, 0x44000
	s_addc_u32 s75, s75, 0
	v_pk_fma_f32 v[64:65], v[64:65], v[174:175], v[198:199] op_sel_hi:[1,0,1]
	v_pk_fma_f32 v[66:67], v[66:67], v[174:175], v[200:201] op_sel_hi:[1,0,1]
	v_pk_fma_f32 v[68:69], v[68:69], v[174:175], v[202:203] op_sel_hi:[1,0,1]
	v_pk_fma_f32 v[70:71], v[70:71], v[174:175], v[204:205] op_sel_hi:[1,0,1]
	v_pk_fma_f32 v[72:73], v[72:73], v[174:175], v[206:207] op_sel_hi:[1,0,1]
	v_pk_fma_f32 v[74:75], v[74:75], v[174:175], v[208:209] op_sel_hi:[1,0,1]
	v_pk_fma_f32 v[76:77], v[76:77], v[174:175], v[210:211] op_sel_hi:[1,0,1]
	v_pk_fma_f32 v[78:79], v[78:79], v[174:175], v[212:213] op_sel_hi:[1,0,1]
	v_pk_fma_f32 v[80:81], v[80:81], v[174:175], v[214:215] op_sel_hi:[1,0,1]
	v_pk_fma_f32 v[82:83], v[82:83], v[174:175], v[216:217] op_sel_hi:[1,0,1]
	v_pk_fma_f32 v[84:85], v[84:85], v[174:175], v[218:219] op_sel_hi:[1,0,1]
	v_pk_fma_f32 v[86:87], v[86:87], v[174:175], v[220:221] op_sel_hi:[1,0,1]
	v_pk_fma_f32 v[88:89], v[88:89], v[174:175], v[222:223] op_sel_hi:[1,0,1]
	v_pk_fma_f32 v[90:91], v[90:91], v[174:175], v[224:225] op_sel_hi:[1,0,1]
	v_pk_fma_f32 v[92:93], v[92:93], v[174:175], v[226:227] op_sel_hi:[1,0,1]
	v_pk_fma_f32 v[94:95], v[94:95], v[174:175], v[228:229] op_sel_hi:[1,0,1]
	v_exp_f32_e32 v64, v64
	v_exp_f32_e32 v65, v65
	v_exp_f32_e32 v66, v66
	v_exp_f32_e32 v67, v67
	v_exp_f32_e32 v68, v68
	v_exp_f32_e32 v69, v69
	v_exp_f32_e32 v70, v70
	v_exp_f32_e32 v71, v71
	v_exp_f32_e32 v72, v72
	v_exp_f32_e32 v73, v73
	v_exp_f32_e32 v74, v74
	v_exp_f32_e32 v75, v75
	v_exp_f32_e32 v76, v76
	v_exp_f32_e32 v77, v77
	v_exp_f32_e32 v78, v78
	v_exp_f32_e32 v79, v79
	v_exp_f32_e32 v80, v80
	v_exp_f32_e32 v81, v81
	v_exp_f32_e32 v82, v82
	v_exp_f32_e32 v83, v83
	v_exp_f32_e32 v84, v84
	v_exp_f32_e32 v85, v85
	v_exp_f32_e32 v86, v86
	v_exp_f32_e32 v87, v87
	v_exp_f32_e32 v88, v88
	v_exp_f32_e32 v89, v89
	v_exp_f32_e32 v90, v90
	v_exp_f32_e32 v91, v91
	v_exp_f32_e32 v92, v92
	v_exp_f32_e32 v93, v93
	v_exp_f32_e32 v94, v94
	v_exp_f32_e32 v95, v95
	v_pk_add_f32 v[64:65], v[64:65], 1.0 op_sel_hi:[1,0]
	v_pk_add_f32 v[66:67], v[66:67], 1.0 op_sel_hi:[1,0]
	v_pk_add_f32 v[68:69], v[68:69], 1.0 op_sel_hi:[1,0]
	v_pk_add_f32 v[70:71], v[70:71], 1.0 op_sel_hi:[1,0]
	v_pk_add_f32 v[72:73], v[72:73], 1.0 op_sel_hi:[1,0]
	v_pk_add_f32 v[74:75], v[74:75], 1.0 op_sel_hi:[1,0]
	v_pk_add_f32 v[76:77], v[76:77], 1.0 op_sel_hi:[1,0]
	v_pk_add_f32 v[78:79], v[78:79], 1.0 op_sel_hi:[1,0]
	v_pk_add_f32 v[80:81], v[80:81], 1.0 op_sel_hi:[1,0]
	v_pk_add_f32 v[82:83], v[82:83], 1.0 op_sel_hi:[1,0]
	v_pk_add_f32 v[84:85], v[84:85], 1.0 op_sel_hi:[1,0]
	v_pk_add_f32 v[86:87], v[86:87], 1.0 op_sel_hi:[1,0]
	v_pk_add_f32 v[88:89], v[88:89], 1.0 op_sel_hi:[1,0]
	v_pk_add_f32 v[90:91], v[90:91], 1.0 op_sel_hi:[1,0]
	v_pk_add_f32 v[92:93], v[92:93], 1.0 op_sel_hi:[1,0]
	v_pk_add_f32 v[94:95], v[94:95], 1.0 op_sel_hi:[1,0]
	v_rcp_f32_e32 v64, v64
	v_rcp_f32_e32 v65, v65
	v_rcp_f32_e32 v66, v66
	v_rcp_f32_e32 v67, v67
	v_rcp_f32_e32 v68, v68
	v_rcp_f32_e32 v69, v69
	v_rcp_f32_e32 v70, v70
	v_rcp_f32_e32 v71, v71
	v_rcp_f32_e32 v72, v72
	v_rcp_f32_e32 v73, v73
	v_rcp_f32_e32 v74, v74
	v_rcp_f32_e32 v75, v75
	v_rcp_f32_e32 v76, v76
	v_rcp_f32_e32 v77, v77
	v_rcp_f32_e32 v78, v78
	v_rcp_f32_e32 v79, v79
	v_rcp_f32_e32 v80, v80
	v_rcp_f32_e32 v81, v81
	v_rcp_f32_e32 v82, v82
	v_rcp_f32_e32 v83, v83
	v_rcp_f32_e32 v84, v84
	v_rcp_f32_e32 v85, v85
	v_rcp_f32_e32 v86, v86
	v_rcp_f32_e32 v87, v87
	v_rcp_f32_e32 v88, v88
	v_rcp_f32_e32 v89, v89
	v_rcp_f32_e32 v90, v90
	v_rcp_f32_e32 v91, v91
	v_rcp_f32_e32 v92, v92
	v_rcp_f32_e32 v93, v93
	v_rcp_f32_e32 v94, v94
	v_rcp_f32_e32 v95, v95
	s_nop 0
	v_cvt_pk_bf16_f32 v64, v64, v65
	v_cvt_pk_bf16_f32 v65, v66, v67
	v_cvt_pk_bf16_f32 v66, v68, v69
	v_cvt_pk_bf16_f32 v67, v70, v71
	v_cvt_pk_bf16_f32 v68, v72, v73
	v_cvt_pk_bf16_f32 v69, v74, v75
	v_cvt_pk_bf16_f32 v70, v76, v77
	v_cvt_pk_bf16_f32 v71, v78, v79
	v_cvt_pk_bf16_f32 v80, v80, v81
	v_cvt_pk_bf16_f32 v81, v82, v83
	v_cvt_pk_bf16_f32 v82, v84, v85
	v_cvt_pk_bf16_f32 v83, v86, v87
	v_cvt_pk_bf16_f32 v84, v88, v89
	v_cvt_pk_bf16_f32 v85, v90, v91
	v_cvt_pk_bf16_f32 v86, v92, v93
	v_cvt_pk_bf16_f32 v87, v94, v95
	v_permlane32_swap_b32_e32 v64, v66
	v_permlane32_swap_b32_e32 v65, v67
	v_permlane32_swap_b32_e32 v68, v70
	v_permlane32_swap_b32_e32 v69, v71
	v_permlane32_swap_b32_e32 v80, v82
	v_permlane32_swap_b32_e32 v81, v83
	v_permlane32_swap_b32_e32 v84, v86
	v_permlane32_swap_b32_e32 v85, v87
	global_store_dwordx4 v181, v[64:67], s[74:75] offset:0
	global_store_dwordx4 v181, v[68:71], s[74:75] offset:32
	global_store_dwordx4 v181, v[80:83], s[74:75] offset:64
	global_store_dwordx4 v181, v[84:87], s[74:75] offset:96
	s_add_u32 s74, s74, 0x44000
	s_addc_u32 s75, s75, 0
	v_pk_fma_f32 v[96:97], v[96:97], v[174:175], v[198:199] op_sel:[0,1,0] op_sel_hi:[1,1,1]
	v_pk_fma_f32 v[98:99], v[98:99], v[174:175], v[200:201] op_sel:[0,1,0] op_sel_hi:[1,1,1]
	v_pk_fma_f32 v[100:101], v[100:101], v[174:175], v[202:203] op_sel:[0,1,0] op_sel_hi:[1,1,1]
	v_pk_fma_f32 v[102:103], v[102:103], v[174:175], v[204:205] op_sel:[0,1,0] op_sel_hi:[1,1,1]
	v_pk_fma_f32 v[104:105], v[104:105], v[174:175], v[206:207] op_sel:[0,1,0] op_sel_hi:[1,1,1]
	v_pk_fma_f32 v[106:107], v[106:107], v[174:175], v[208:209] op_sel:[0,1,0] op_sel_hi:[1,1,1]
	v_pk_fma_f32 v[108:109], v[108:109], v[174:175], v[210:211] op_sel:[0,1,0] op_sel_hi:[1,1,1]
	v_pk_fma_f32 v[110:111], v[110:111], v[174:175], v[212:213] op_sel:[0,1,0] op_sel_hi:[1,1,1]
	v_pk_fma_f32 v[112:113], v[112:113], v[174:175], v[214:215] op_sel:[0,1,0] op_sel_hi:[1,1,1]
	v_pk_fma_f32 v[114:115], v[114:115], v[174:175], v[216:217] op_sel:[0,1,0] op_sel_hi:[1,1,1]
	v_pk_fma_f32 v[116:117], v[116:117], v[174:175], v[218:219] op_sel:[0,1,0] op_sel_hi:[1,1,1]
	v_pk_fma_f32 v[118:119], v[118:119], v[174:175], v[220:221] op_sel:[0,1,0] op_sel_hi:[1,1,1]
	v_pk_fma_f32 v[120:121], v[120:121], v[174:175], v[222:223] op_sel:[0,1,0] op_sel_hi:[1,1,1]
	v_pk_fma_f32 v[122:123], v[122:123], v[174:175], v[224:225] op_sel:[0,1,0] op_sel_hi:[1,1,1]
	v_pk_fma_f32 v[124:125], v[124:125], v[174:175], v[226:227] op_sel:[0,1,0] op_sel_hi:[1,1,1]
	v_pk_fma_f32 v[126:127], v[126:127], v[174:175], v[228:229] op_sel:[0,1,0] op_sel_hi:[1,1,1]
	v_exp_f32_e32 v96, v96
	v_exp_f32_e32 v97, v97
	v_exp_f32_e32 v98, v98
	v_exp_f32_e32 v99, v99
	v_exp_f32_e32 v100, v100
	v_exp_f32_e32 v101, v101
	v_exp_f32_e32 v102, v102
	v_exp_f32_e32 v103, v103
	v_exp_f32_e32 v104, v104
	v_exp_f32_e32 v105, v105
	v_exp_f32_e32 v106, v106
	v_exp_f32_e32 v107, v107
	v_exp_f32_e32 v108, v108
	v_exp_f32_e32 v109, v109
	v_exp_f32_e32 v110, v110
	v_exp_f32_e32 v111, v111
	v_exp_f32_e32 v112, v112
	v_exp_f32_e32 v113, v113
	v_exp_f32_e32 v114, v114
	v_exp_f32_e32 v115, v115
	v_exp_f32_e32 v116, v116
	v_exp_f32_e32 v117, v117
	v_exp_f32_e32 v118, v118
	v_exp_f32_e32 v119, v119
	v_exp_f32_e32 v120, v120
	v_exp_f32_e32 v121, v121
	v_exp_f32_e32 v122, v122
	v_exp_f32_e32 v123, v123
	v_exp_f32_e32 v124, v124
	v_exp_f32_e32 v125, v125
	v_exp_f32_e32 v126, v126
	v_exp_f32_e32 v127, v127
	v_pk_add_f32 v[96:97], v[96:97], 1.0 op_sel_hi:[1,0]
	v_pk_add_f32 v[98:99], v[98:99], 1.0 op_sel_hi:[1,0]
	v_pk_add_f32 v[100:101], v[100:101], 1.0 op_sel_hi:[1,0]
	v_pk_add_f32 v[102:103], v[102:103], 1.0 op_sel_hi:[1,0]
	v_pk_add_f32 v[104:105], v[104:105], 1.0 op_sel_hi:[1,0]
	v_pk_add_f32 v[106:107], v[106:107], 1.0 op_sel_hi:[1,0]
	v_pk_add_f32 v[108:109], v[108:109], 1.0 op_sel_hi:[1,0]
	v_pk_add_f32 v[110:111], v[110:111], 1.0 op_sel_hi:[1,0]
	v_pk_add_f32 v[112:113], v[112:113], 1.0 op_sel_hi:[1,0]
	v_pk_add_f32 v[114:115], v[114:115], 1.0 op_sel_hi:[1,0]
	v_pk_add_f32 v[116:117], v[116:117], 1.0 op_sel_hi:[1,0]
	v_pk_add_f32 v[118:119], v[118:119], 1.0 op_sel_hi:[1,0]
	v_pk_add_f32 v[120:121], v[120:121], 1.0 op_sel_hi:[1,0]
	v_pk_add_f32 v[122:123], v[122:123], 1.0 op_sel_hi:[1,0]
	v_pk_add_f32 v[124:125], v[124:125], 1.0 op_sel_hi:[1,0]
	v_pk_add_f32 v[126:127], v[126:127], 1.0 op_sel_hi:[1,0]
	v_rcp_f32_e32 v96, v96
	v_rcp_f32_e32 v97, v97
	v_rcp_f32_e32 v98, v98
	v_rcp_f32_e32 v99, v99
	v_rcp_f32_e32 v100, v100
	v_rcp_f32_e32 v101, v101
	v_rcp_f32_e32 v102, v102
	v_rcp_f32_e32 v103, v103
	v_rcp_f32_e32 v104, v104
	v_rcp_f32_e32 v105, v105
	v_rcp_f32_e32 v106, v106
	v_rcp_f32_e32 v107, v107
	v_rcp_f32_e32 v108, v108
	v_rcp_f32_e32 v109, v109
	v_rcp_f32_e32 v110, v110
	v_rcp_f32_e32 v111, v111
	v_rcp_f32_e32 v112, v112
	v_rcp_f32_e32 v113, v113
	v_rcp_f32_e32 v114, v114
	v_rcp_f32_e32 v115, v115
	v_rcp_f32_e32 v116, v116
	v_rcp_f32_e32 v117, v117
	v_rcp_f32_e32 v118, v118
	v_rcp_f32_e32 v119, v119
	v_rcp_f32_e32 v120, v120
	v_rcp_f32_e32 v121, v121
	v_rcp_f32_e32 v122, v122
	v_rcp_f32_e32 v123, v123
	v_rcp_f32_e32 v124, v124
	v_rcp_f32_e32 v125, v125
	v_rcp_f32_e32 v126, v126
	v_rcp_f32_e32 v127, v127
	s_nop 0
	v_cvt_pk_bf16_f32 v96, v96, v97
	v_cvt_pk_bf16_f32 v97, v98, v99
	v_cvt_pk_bf16_f32 v98, v100, v101
	v_cvt_pk_bf16_f32 v99, v102, v103
	v_cvt_pk_bf16_f32 v100, v104, v105
	v_cvt_pk_bf16_f32 v101, v106, v107
	v_cvt_pk_bf16_f32 v102, v108, v109
	v_cvt_pk_bf16_f32 v103, v110, v111
	v_cvt_pk_bf16_f32 v112, v112, v113
	v_cvt_pk_bf16_f32 v113, v114, v115
	v_cvt_pk_bf16_f32 v114, v116, v117
	v_cvt_pk_bf16_f32 v115, v118, v119
	v_cvt_pk_bf16_f32 v116, v120, v121
	v_cvt_pk_bf16_f32 v117, v122, v123
	v_cvt_pk_bf16_f32 v118, v124, v125
	v_cvt_pk_bf16_f32 v119, v126, v127
	v_permlane32_swap_b32_e32 v96, v98
	v_permlane32_swap_b32_e32 v97, v99
	v_permlane32_swap_b32_e32 v100, v102
	v_permlane32_swap_b32_e32 v101, v103
	v_permlane32_swap_b32_e32 v112, v114
	v_permlane32_swap_b32_e32 v113, v115
	v_permlane32_swap_b32_e32 v116, v118
	v_permlane32_swap_b32_e32 v117, v119
	global_store_dwordx4 v181, v[96:99], s[74:75] offset:0
	global_store_dwordx4 v181, v[100:103], s[74:75] offset:32
	global_store_dwordx4 v181, v[112:115], s[74:75] offset:64
	global_store_dwordx4 v181, v[116:119], s[74:75] offset:96
	s_branch .Lpe_ret_L1
.Lpe_vt_L1:
	s_lshl_b32 s35, s34, 2
	s_add_u32 s35, s35, s28
	s_add_u32 s36, s28, 6
	s_cmp_eq_u32 s25, 8
	s_cselect_b32 s35, s36, s35
	s_lshr_b32 s36, s29, 11
	s_mul_i32 s36, s36, 10
	s_add_u32 s36, s36, s35
	s_lshl_b32 s36, s36, 18
	s_and_b32 s37, s29, 0x7ff
	s_lshl_b32 s37, s37, 1
	s_add_u32 s36, s36, s37
	s_add_u32 s38, s72, 0x14920000
	s_addc_u32 s39, s73, 0
	s_add_u32 s38, s38, s36
	s_addc_u32 s39, s39, 0
	s_mul_i32 s36, s26, 10240
	s_add_u32 s36, s36, 0x10000
	v_lshlrev_b32_e32 v180, 1, v197
	v_mul_u32_u24_e32 v181, 36, v146
	v_add3_u32 v180, v180, v181, s36
	v_lshrrev_b32_e32 v181, 3, v179
	v_and_b32_e32 v146, 7, v179
	v_lshlrev_b32_e32 v146, 4, v146
	v_mul_u32_u24_e32 v198, 144, v181
	v_add3_u32 v198, v198, v146, s36
	v_lshl_add_u32 v199, v181, 12, v146
	s_waitcnt vmcnt(0)
	v_mov_b32_e32 v197, 0x358637bd
	v_pk_add_f32 v[128:129], v[128:129], v[130:131]
	v_pk_add_f32 v[132:133], v[132:133], v[134:135]
	v_pk_add_f32 v[136:137], v[136:137], v[138:139]
	v_pk_add_f32 v[140:141], v[140:141], v[142:143]
	v_pk_add_f32 v[164:165], v[164:165], v[166:167]
	v_pk_add_f32 v[168:169], v[168:169], v[170:171]
	v_pk_add_f32 v[246:247], v[246:247], v[248:249]
	v_pk_add_f32 v[250:251], v[250:251], v[252:253]
	v_pk_add_f32 v[128:129], v[128:129], v[132:133]
	v_pk_add_f32 v[136:137], v[136:137], v[140:141]
	v_pk_add_f32 v[164:165], v[164:165], v[168:169]
	v_pk_add_f32 v[246:247], v[246:247], v[250:251]
	v_add_f32_e32 v128, v128, v129
	v_add_f32_e32 v136, v136, v137
	v_add_f32_e32 v164, v164, v165
	v_add_f32_e32 v246, v246, v247
	v_fmamk_f32 v128, v128, 0x3a800000, v197
	v_fmamk_f32 v136, v136, 0x3a800000, v197
	v_fmamk_f32 v164, v164, 0x3a800000, v197
	v_fmamk_f32 v246, v246, 0x3a800000, v197
	v_rsq_f32_e32 v172, v128
	v_rsq_f32_e32 v173, v136
	v_rsq_f32_e32 v174, v164
	v_rsq_f32_e32 v175, v246
	s_nop 0
	s_add_u32 s76, s99, s90
	s_cmp_lt_u32 s76, 0x440
	s_cselect_b32 s80, 1, 0
	s_cselect_b32 s83, 0x200000, 0
	s_lshl_b32 s76, s24, 19
	s_lshl_b32 s77, s26, 16
	s_add_u32 s76, s76, s77
	s_and_b32 s77, s24, 7
	s_lshl_b32 s77, s77, 8
	s_add_u32 s76, s76, s77
	s_add_u32 s78, s72, 0xa120000
	s_addc_u32 s79, s73, 0
	s_add_u32 s78, s78, s76
	s_addc_u32 s79, s79, 0
	s_lshl_b32 s76, s25, 19
	s_add_u32 s76, s76, s83
	s_add_u32 s76, s76, s77
	s_lshl_b32 s77, s26, 16
	s_add_u32 s76, s76, s77
	s_add_u32 s82, s72, 0x880000
	s_addc_u32 s83, s73, 0
	s_add_u32 s82, s82, s76
	s_addc_u32 s83, s83, 0
	s_lshl_b32 s76, s26, 12
	s_mov_b32 m0, s76
	s_nop 0
	global_load_lds_dwordx4 v177, s[78:79]
	s_add_u32 s78, s78, 0x4000
	s_addc_u32 s79, s79, 0
	s_add_u32 s76, s76, 0x400
	s_mov_b32 m0, s76
	s_nop 0
	global_load_lds_dwordx4 v185, s[78:79]
	s_add_u32 s78, s78, 0x4000
	s_addc_u32 s79, s79, 0
	s_add_u32 s76, s76, 0x400
	s_mov_b32 m0, s76
	s_nop 0
	global_load_lds_dwordx4 v177, s[78:79]
	s_add_u32 s78, s78, 0x4000
	s_addc_u32 s79, s79, 0
	s_add_u32 s76, s76, 0x400
	s_mov_b32 m0, s76
	s_nop 0
	global_load_lds_dwordx4 v185, s[78:79]
	s_add_u32 s78, s78, 0x4000
	s_addc_u32 s79, s79, 0
	s_add_u32 s76, s76, 0x400
	s_add_u32 s76, s76, 0x7000
	s_mov_b32 m0, s76
	s_nop 0
	global_load_lds_dwordx4 v177, s[82:83]
	s_add_u32 s82, s82, 0x4000
	s_addc_u32 s83, s83, 0
	s_add_u32 s76, s76, 0x400
	s_mov_b32 m0, s76
	s_nop 0
	global_load_lds_dwordx4 v185, s[82:83]
	s_add_u32 s82, s82, 0x4000
	s_addc_u32 s83, s83, 0
	s_add_u32 s76, s76, 0x400
	s_mov_b32 m0, s76
	s_nop 0
	global_load_lds_dwordx4 v177, s[82:83]
	s_add_u32 s82, s82, 0x4000
	s_addc_u32 s83, s83, 0
	s_add_u32 s76, s76, 0x400
	s_mov_b32 m0, s76
	s_nop 0
	global_load_lds_dwordx4 v185, s[82:83]
	s_add_u32 s82, s82, 0x4000
	s_addc_u32 s83, s83, 0
	s_add_u32 s76, s76, 0x400
	v_pk_mul_f32 v[0:1], v[0:1], v[172:173] op_sel_hi:[1,0]
	v_pk_mul_f32 v[2:3], v[2:3], v[172:173] op_sel_hi:[1,0]
	v_pk_mul_f32 v[4:5], v[4:5], v[172:173] op_sel_hi:[1,0]
	v_pk_mul_f32 v[6:7], v[6:7], v[172:173] op_sel_hi:[1,0]
	v_pk_mul_f32 v[8:9], v[8:9], v[172:173] op_sel_hi:[1,0]
	v_pk_mul_f32 v[10:11], v[10:11], v[172:173] op_sel_hi:[1,0]
	v_pk_mul_f32 v[12:13], v[12:13], v[172:173] op_sel_hi:[1,0]
	v_pk_mul_f32 v[14:15], v[14:15], v[172:173] op_sel_hi:[1,0]
	v_pk_mul_f32 v[16:17], v[16:17], v[172:173] op_sel_hi:[1,0]
	v_pk_mul_f32 v[18:19], v[18:19], v[172:173] op_sel_hi:[1,0]
	v_pk_mul_f32 v[20:21], v[20:21], v[172:173] op_sel_hi:[1,0]
	v_pk_mul_f32 v[22:23], v[22:23], v[172:173] op_sel_hi:[1,0]
	v_pk_mul_f32 v[24:25], v[24:25], v[172:173] op_sel_hi:[1,0]
	v_pk_mul_f32 v[26:27], v[26:27], v[172:173] op_sel_hi:[1,0]
	v_pk_mul_f32 v[28:29], v[28:29], v[172:173] op_sel_hi:[1,0]
	v_pk_mul_f32 v[30:31], v[30:31], v[172:173] op_sel_hi:[1,0]
	v_pk_mul_f32 v[32:33], v[32:33], v[172:173] op_sel:[0,1] op_sel_hi:[1,1]
	v_pk_mul_f32 v[34:35], v[34:35], v[172:173] op_sel:[0,1] op_sel_hi:[1,1]
	v_pk_mul_f32 v[36:37], v[36:37], v[172:173] op_sel:[0,1] op_sel_hi:[1,1]
	v_pk_mul_f32 v[38:39], v[38:39], v[172:173] op_sel:[0,1] op_sel_hi:[1,1]
	v_pk_mul_f32 v[40:41], v[40:41], v[172:173] op_sel:[0,1] op_sel_hi:[1,1]
	v_pk_mul_f32 v[42:43], v[42:43], v[172:173] op_sel:[0,1] op_sel_hi:[1,1]
	v_pk_mul_f32 v[44:45], v[44:45], v[172:173] op_sel:[0,1] op_sel_hi:[1,1]
	v_pk_mul_f32 v[46:47], v[46:47], v[172:173] op_sel:[0,1] op_sel_hi:[1,1]
	v_pk_mul_f32 v[48:49], v[48:49], v[172:173] op_sel:[0,1] op_sel_hi:[1,1]
	v_pk_mul_f32 v[50:51], v[50:51], v[172:173] op_sel:[0,1] op_sel_hi:[1,1]
	v_pk_mul_f32 v[52:53], v[52:53], v[172:173] op_sel:[0,1] op_sel_hi:[1,1]
	v_pk_mul_f32 v[54:55], v[54:55], v[172:173] op_sel:[0,1] op_sel_hi:[1,1]
	v_pk_mul_f32 v[56:57], v[56:57], v[172:173] op_sel:[0,1] op_sel_hi:[1,1]
	v_pk_mul_f32 v[58:59], v[58:59], v[172:173] op_sel:[0,1] op_sel_hi:[1,1]
	v_pk_mul_f32 v[60:61], v[60:61], v[172:173] op_sel:[0,1] op_sel_hi:[1,1]
	v_pk_mul_f32 v[62:63], v[62:63], v[172:173] op_sel:[0,1] op_sel_hi:[1,1]
	v_pk_mul_f32 v[64:65], v[64:65], v[174:175] op_sel_hi:[1,0]
	v_pk_mul_f32 v[66:67], v[66:67], v[174:175] op_sel_hi:[1,0]
	v_pk_mul_f32 v[68:69], v[68:69], v[174:175] op_sel_hi:[1,0]
	v_pk_mul_f32 v[70:71], v[70:71], v[174:175] op_sel_hi:[1,0]
	v_pk_mul_f32 v[72:73], v[72:73], v[174:175] op_sel_hi:[1,0]
	v_pk_mul_f32 v[74:75], v[74:75], v[174:175] op_sel_hi:[1,0]
	v_pk_mul_f32 v[76:77], v[76:77], v[174:175] op_sel_hi:[1,0]
	v_pk_mul_f32 v[78:79], v[78:79], v[174:175] op_sel_hi:[1,0]
	v_pk_mul_f32 v[80:81], v[80:81], v[174:175] op_sel_hi:[1,0]
	v_pk_mul_f32 v[82:83], v[82:83], v[174:175] op_sel_hi:[1,0]
	v_pk_mul_f32 v[84:85], v[84:85], v[174:175] op_sel_hi:[1,0]
	v_pk_mul_f32 v[86:87], v[86:87], v[174:175] op_sel_hi:[1,0]
	v_pk_mul_f32 v[88:89], v[88:89], v[174:175] op_sel_hi:[1,0]
	v_pk_mul_f32 v[90:91], v[90:91], v[174:175] op_sel_hi:[1,0]
	v_pk_mul_f32 v[92:93], v[92:93], v[174:175] op_sel_hi:[1,0]
	v_pk_mul_f32 v[94:95], v[94:95], v[174:175] op_sel_hi:[1,0]
	v_pk_mul_f32 v[96:97], v[96:97], v[174:175] op_sel:[0,1] op_sel_hi:[1,1]
	v_pk_mul_f32 v[98:99], v[98:99], v[174:175] op_sel:[0,1] op_sel_hi:[1,1]
	v_pk_mul_f32 v[100:101], v[100:101], v[174:175] op_sel:[0,1] op_sel_hi:[1,1]
	v_pk_mul_f32 v[102:103], v[102:103], v[174:175] op_sel:[0,1] op_sel_hi:[1,1]
	v_pk_mul_f32 v[104:105], v[104:105], v[174:175] op_sel:[0,1] op_sel_hi:[1,1]
	v_pk_mul_f32 v[106:107], v[106:107], v[174:175] op_sel:[0,1] op_sel_hi:[1,1]
	v_pk_mul_f32 v[108:109], v[108:109], v[174:175] op_sel:[0,1] op_sel_hi:[1,1]
	v_pk_mul_f32 v[110:111], v[110:111], v[174:175] op_sel:[0,1] op_sel_hi:[1,1]
	v_pk_mul_f32 v[112:113], v[112:113], v[174:175] op_sel:[0,1] op_sel_hi:[1,1]
	v_pk_mul_f32 v[114:115], v[114:115], v[174:175] op_sel:[0,1] op_sel_hi:[1,1]
	v_pk_mul_f32 v[116:117], v[116:117], v[174:175] op_sel:[0,1] op_sel_hi:[1,1]
	v_pk_mul_f32 v[118:119], v[118:119], v[174:175] op_sel:[0,1] op_sel_hi:[1,1]
	v_pk_mul_f32 v[120:121], v[120:121], v[174:175] op_sel:[0,1] op_sel_hi:[1,1]
	v_pk_mul_f32 v[122:123], v[122:123], v[174:175] op_sel:[0,1] op_sel_hi:[1,1]
	v_pk_mul_f32 v[124:125], v[124:125], v[174:175] op_sel:[0,1] op_sel_hi:[1,1]
	v_pk_mul_f32 v[126:127], v[126:127], v[174:175] op_sel:[0,1] op_sel_hi:[1,1]
	v_cvt_pk_bf16_f32 v0, v0, v1
	v_cvt_pk_bf16_f32 v1, v2, v3
	v_cvt_pk_bf16_f32 v2, v4, v5
	v_cvt_pk_bf16_f32 v3, v6, v7
	v_cvt_pk_bf16_f32 v4, v8, v9
	v_cvt_pk_bf16_f32 v5, v10, v11
	v_cvt_pk_bf16_f32 v6, v12, v13
	v_cvt_pk_bf16_f32 v7, v14, v15
	ds_write_b16 v180, v0 offset:0
	ds_write_b16_d16_hi v180, v0 offset:144
	ds_write_b16 v180, v1 offset:288
	ds_write_b16_d16_hi v180, v1 offset:432
	ds_write_b16 v180, v2 offset:1152
	ds_write_b16_d16_hi v180, v2 offset:1296
	ds_write_b16 v180, v3 offset:1440
	ds_write_b16_d16_hi v180, v3 offset:1584
	ds_write_b16 v180, v4 offset:2304
	ds_write_b16_d16_hi v180, v4 offset:2448
	ds_write_b16 v180, v5 offset:2592
	ds_write_b16_d16_hi v180, v5 offset:2736
	ds_write_b16 v180, v6 offset:3456
	ds_write_b16_d16_hi v180, v6 offset:3600
	ds_write_b16 v180, v7 offset:3744
	ds_write_b16_d16_hi v180, v7 offset:3888
	v_cvt_pk_bf16_f32 v16, v16, v17
	v_cvt_pk_bf16_f32 v17, v18, v19
	v_cvt_pk_bf16_f32 v18, v20, v21
	v_cvt_pk_bf16_f32 v19, v22, v23
	v_cvt_pk_bf16_f32 v20, v24, v25
	v_cvt_pk_bf16_f32 v21, v26, v27
	v_cvt_pk_bf16_f32 v22, v28, v29
	v_cvt_pk_bf16_f32 v23, v30, v31
	ds_write_b16 v180, v16 offset:4608
	ds_write_b16_d16_hi v180, v16 offset:4752
	ds_write_b16 v180, v17 offset:4896
	ds_write_b16_d16_hi v180, v17 offset:5040
	ds_write_b16 v180, v18 offset:5760
	ds_write_b16_d16_hi v180, v18 offset:5904
	ds_write_b16 v180, v19 offset:6048
	ds_write_b16_d16_hi v180, v19 offset:6192
	ds_write_b16 v180, v20 offset:6912
	ds_write_b16_d16_hi v180, v20 offset:7056
	ds_write_b16 v180, v21 offset:7200
	ds_write_b16_d16_hi v180, v21 offset:7344
	ds_write_b16 v180, v22 offset:8064
	ds_write_b16_d16_hi v180, v22 offset:8208
	ds_write_b16 v180, v23 offset:8352
	ds_write_b16_d16_hi v180, v23 offset:8496
	v_cvt_pk_bf16_f32 v32, v32, v33
	v_cvt_pk_bf16_f32 v33, v34, v35
	v_cvt_pk_bf16_f32 v34, v36, v37
	v_cvt_pk_bf16_f32 v35, v38, v39
	v_cvt_pk_bf16_f32 v36, v40, v41
	v_cvt_pk_bf16_f32 v37, v42, v43
	v_cvt_pk_bf16_f32 v38, v44, v45
	v_cvt_pk_bf16_f32 v39, v46, v47
	ds_write_b16 v180, v32 offset:64
	ds_write_b16_d16_hi v180, v32 offset:208
	ds_write_b16 v180, v33 offset:352
	ds_write_b16_d16_hi v180, v33 offset:496
	ds_write_b16 v180, v34 offset:1216
	ds_write_b16_d16_hi v180, v34 offset:1360
	ds_write_b16 v180, v35 offset:1504
	ds_write_b16_d16_hi v180, v35 offset:1648
	ds_write_b16 v180, v36 offset:2368
	ds_write_b16_d16_hi v180, v36 offset:2512
	ds_write_b16 v180, v37 offset:2656
	ds_write_b16_d16_hi v180, v37 offset:2800
	ds_write_b16 v180, v38 offset:3520
	ds_write_b16_d16_hi v180, v38 offset:3664
	ds_write_b16 v180, v39 offset:3808
	ds_write_b16_d16_hi v180, v39 offset:3952
	v_cvt_pk_bf16_f32 v48, v48, v49
	v_cvt_pk_bf16_f32 v49, v50, v51
	v_cvt_pk_bf16_f32 v50, v52, v53
	v_cvt_pk_bf16_f32 v51, v54, v55
	v_cvt_pk_bf16_f32 v52, v56, v57
	v_cvt_pk_bf16_f32 v53, v58, v59
	v_cvt_pk_bf16_f32 v54, v60, v61
	v_cvt_pk_bf16_f32 v55, v62, v63
	ds_write_b16 v180, v48 offset:4672
	ds_write_b16_d16_hi v180, v48 offset:4816
	ds_write_b16 v180, v49 offset:4960
	ds_write_b16_d16_hi v180, v49 offset:5104
	ds_write_b16 v180, v50 offset:5824
	ds_write_b16_d16_hi v180, v50 offset:5968
	ds_write_b16 v180, v51 offset:6112
	ds_write_b16_d16_hi v180, v51 offset:6256
	ds_write_b16 v180, v52 offset:6976
	ds_write_b16_d16_hi v180, v52 offset:7120
	ds_write_b16 v180, v53 offset:7264
	ds_write_b16_d16_hi v180, v53 offset:7408
	ds_write_b16 v180, v54 offset:8128
	ds_write_b16_d16_hi v180, v54 offset:8272
	ds_write_b16 v180, v55 offset:8416
	ds_write_b16_d16_hi v180, v55 offset:8560
	s_waitcnt lgkmcnt(0)
	ds_read_b128 v[0:3], v198 offset:0
	ds_read_b128 v[4:7], v198 offset:1152
	ds_read_b128 v[8:11], v198 offset:2304
	ds_read_b128 v[12:15], v198 offset:3456
	ds_read_b128 v[16:19], v198 offset:4608
	ds_read_b128 v[20:23], v198 offset:5760
	ds_read_b128 v[24:27], v198 offset:6912
	ds_read_b128 v[28:31], v198 offset:8064
	s_waitcnt lgkmcnt(7)
	global_store_dwordx4 v199, v[0:3], s[38:39]
	s_add_u32 s38, s38, 0x8000
	s_addc_u32 s39, s39, 0
	s_waitcnt lgkmcnt(6)
	global_store_dwordx4 v199, v[4:7], s[38:39]
	s_add_u32 s38, s38, 0x8000
	s_addc_u32 s39, s39, 0
	s_waitcnt lgkmcnt(5)
	global_store_dwordx4 v199, v[8:11], s[38:39]
	s_add_u32 s38, s38, 0x8000
	s_addc_u32 s39, s39, 0
	s_waitcnt lgkmcnt(4)
	global_store_dwordx4 v199, v[12:15], s[38:39]
	s_add_u32 s38, s38, 0x8000
	s_addc_u32 s39, s39, 0
	s_waitcnt lgkmcnt(3)
	global_store_dwordx4 v199, v[16:19], s[38:39]
	s_add_u32 s38, s38, 0x8000
	s_addc_u32 s39, s39, 0
	s_waitcnt lgkmcnt(2)
	global_store_dwordx4 v199, v[20:23], s[38:39]
	s_add_u32 s38, s38, 0x8000
	s_addc_u32 s39, s39, 0
	s_waitcnt lgkmcnt(1)
	global_store_dwordx4 v199, v[24:27], s[38:39]
	s_add_u32 s38, s38, 0x8000
	s_addc_u32 s39, s39, 0
	s_waitcnt lgkmcnt(0)
	global_store_dwordx4 v199, v[28:31], s[38:39]
	s_sub_u32 s38, s38, 229248
	s_subb_u32 s39, s39, 0
	v_cvt_pk_bf16_f32 v64, v64, v65
	v_cvt_pk_bf16_f32 v65, v66, v67
	v_cvt_pk_bf16_f32 v66, v68, v69
	v_cvt_pk_bf16_f32 v67, v70, v71
	v_cvt_pk_bf16_f32 v68, v72, v73
	v_cvt_pk_bf16_f32 v69, v74, v75
	v_cvt_pk_bf16_f32 v70, v76, v77
	v_cvt_pk_bf16_f32 v71, v78, v79
	ds_write_b16 v180, v64 offset:0
	ds_write_b16_d16_hi v180, v64 offset:144
	ds_write_b16 v180, v65 offset:288
	ds_write_b16_d16_hi v180, v65 offset:432
	ds_write_b16 v180, v66 offset:1152
	ds_write_b16_d16_hi v180, v66 offset:1296
	ds_write_b16 v180, v67 offset:1440
	ds_write_b16_d16_hi v180, v67 offset:1584
	ds_write_b16 v180, v68 offset:2304
	ds_write_b16_d16_hi v180, v68 offset:2448
	ds_write_b16 v180, v69 offset:2592
	ds_write_b16_d16_hi v180, v69 offset:2736
	ds_write_b16 v180, v70 offset:3456
	ds_write_b16_d16_hi v180, v70 offset:3600
	ds_write_b16 v180, v71 offset:3744
	ds_write_b16_d16_hi v180, v71 offset:3888
	v_cvt_pk_bf16_f32 v80, v80, v81
	v_cvt_pk_bf16_f32 v81, v82, v83
	v_cvt_pk_bf16_f32 v82, v84, v85
	v_cvt_pk_bf16_f32 v83, v86, v87
	v_cvt_pk_bf16_f32 v84, v88, v89
	v_cvt_pk_bf16_f32 v85, v90, v91
	v_cvt_pk_bf16_f32 v86, v92, v93
	v_cvt_pk_bf16_f32 v87, v94, v95
	ds_write_b16 v180, v80 offset:4608
	ds_write_b16_d16_hi v180, v80 offset:4752
	ds_write_b16 v180, v81 offset:4896
	ds_write_b16_d16_hi v180, v81 offset:5040
	ds_write_b16 v180, v82 offset:5760
	ds_write_b16_d16_hi v180, v82 offset:5904
	ds_write_b16 v180, v83 offset:6048
	ds_write_b16_d16_hi v180, v83 offset:6192
	ds_write_b16 v180, v84 offset:6912
	ds_write_b16_d16_hi v180, v84 offset:7056
	ds_write_b16 v180, v85 offset:7200
	ds_write_b16_d16_hi v180, v85 offset:7344
	ds_write_b16 v180, v86 offset:8064
	ds_write_b16_d16_hi v180, v86 offset:8208
	ds_write_b16 v180, v87 offset:8352
	ds_write_b16_d16_hi v180, v87 offset:8496
	v_cvt_pk_bf16_f32 v96, v96, v97
	v_cvt_pk_bf16_f32 v97, v98, v99
	v_cvt_pk_bf16_f32 v98, v100, v101
	v_cvt_pk_bf16_f32 v99, v102, v103
	v_cvt_pk_bf16_f32 v100, v104, v105
	v_cvt_pk_bf16_f32 v101, v106, v107
	v_cvt_pk_bf16_f32 v102, v108, v109
	v_cvt_pk_bf16_f32 v103, v110, v111
	ds_write_b16 v180, v96 offset:64
	ds_write_b16_d16_hi v180, v96 offset:208
	ds_write_b16 v180, v97 offset:352
	ds_write_b16_d16_hi v180, v97 offset:496
	ds_write_b16 v180, v98 offset:1216
	ds_write_b16_d16_hi v180, v98 offset:1360
	ds_write_b16 v180, v99 offset:1504
	ds_write_b16_d16_hi v180, v99 offset:1648
	ds_write_b16 v180, v100 offset:2368
	ds_write_b16_d16_hi v180, v100 offset:2512
	ds_write_b16 v180, v101 offset:2656
	ds_write_b16_d16_hi v180, v101 offset:2800
	ds_write_b16 v180, v102 offset:3520
	ds_write_b16_d16_hi v180, v102 offset:3664
	ds_write_b16 v180, v103 offset:3808
	ds_write_b16_d16_hi v180, v103 offset:3952
	v_cvt_pk_bf16_f32 v112, v112, v113
	v_cvt_pk_bf16_f32 v113, v114, v115
	v_cvt_pk_bf16_f32 v114, v116, v117
	v_cvt_pk_bf16_f32 v115, v118, v119
	v_cvt_pk_bf16_f32 v116, v120, v121
	v_cvt_pk_bf16_f32 v117, v122, v123
	v_cvt_pk_bf16_f32 v118, v124, v125
	v_cvt_pk_bf16_f32 v119, v126, v127
	ds_write_b16 v180, v112 offset:4672
	ds_write_b16_d16_hi v180, v112 offset:4816
	ds_write_b16 v180, v113 offset:4960
	ds_write_b16_d16_hi v180, v113 offset:5104
	ds_write_b16 v180, v114 offset:5824
	ds_write_b16_d16_hi v180, v114 offset:5968
	ds_write_b16 v180, v115 offset:6112
	ds_write_b16_d16_hi v180, v115 offset:6256
	ds_write_b16 v180, v116 offset:6976
	ds_write_b16_d16_hi v180, v116 offset:7120
	ds_write_b16 v180, v117 offset:7264
	ds_write_b16_d16_hi v180, v117 offset:7408
	ds_write_b16 v180, v118 offset:8128
	ds_write_b16_d16_hi v180, v118 offset:8272
	ds_write_b16 v180, v119 offset:8416
	ds_write_b16_d16_hi v180, v119 offset:8560
	s_waitcnt lgkmcnt(0)
	ds_read_b128 v[64:67], v198 offset:0
	ds_read_b128 v[68:71], v198 offset:1152
	ds_read_b128 v[72:75], v198 offset:2304
	ds_read_b128 v[76:79], v198 offset:3456
	ds_read_b128 v[80:83], v198 offset:4608
	ds_read_b128 v[84:87], v198 offset:5760
	ds_read_b128 v[88:91], v198 offset:6912
	ds_read_b128 v[92:95], v198 offset:8064
	s_waitcnt lgkmcnt(7)
	global_store_dwordx4 v199, v[64:67], s[38:39]
	s_add_u32 s38, s38, 0x8000
	s_addc_u32 s39, s39, 0
	s_waitcnt lgkmcnt(6)
	global_store_dwordx4 v199, v[68:71], s[38:39]
	s_add_u32 s38, s38, 0x8000
	s_addc_u32 s39, s39, 0
	s_waitcnt lgkmcnt(5)
	global_store_dwordx4 v199, v[72:75], s[38:39]
	s_add_u32 s38, s38, 0x8000
	s_addc_u32 s39, s39, 0
	s_waitcnt lgkmcnt(4)
	global_store_dwordx4 v199, v[76:79], s[38:39]
	s_add_u32 s38, s38, 0x8000
	s_addc_u32 s39, s39, 0
	s_waitcnt lgkmcnt(3)
	global_store_dwordx4 v199, v[80:83], s[38:39]
	s_add_u32 s38, s38, 0x8000
	s_addc_u32 s39, s39, 0
	s_waitcnt lgkmcnt(2)
	global_store_dwordx4 v199, v[84:87], s[38:39]
	s_add_u32 s38, s38, 0x8000
	s_addc_u32 s39, s39, 0
	s_waitcnt lgkmcnt(1)
	global_store_dwordx4 v199, v[88:91], s[38:39]
	s_add_u32 s38, s38, 0x8000
	s_addc_u32 s39, s39, 0
	s_waitcnt lgkmcnt(0)
	global_store_dwordx4 v199, v[92:95], s[38:39]
.Lpe_ret_L1:
	s_branch .LBB0_723
.LBB0_774:
	s_waitcnt vmcnt(0)
	s_barrier
	s_mov_b64 s[0:1], exec
	v_readlane_b32 s2, v254, 23
	v_readlane_b32 s3, v254, 24
	s_and_b64 s[2:3], s[0:1], s[2:3]
	s_mov_b64 exec, s[2:3]
	s_cbranch_execz .LBB0_826
	v_mov_b32_e32 v0, 0x24000
	s_waitcnt vmcnt(0) expcnt(0) lgkmcnt(0)
	ds_read_b32 v2, v0
	v_mov_b32_e32 v0, 0x24004
	ds_read_b32 v0, v0
	s_waitcnt lgkmcnt(1)
	v_cmp_ne_u32_e32 vcc, 0, v2
	s_cbranch_vccnz .LBB0_790
	v_readlane_b32 s2, v254, 2
	v_readlane_b32 s36, v254, 0
	s_mul_i32 s33, s91, s2
	v_readlane_b32 s37, v254, 1
	s_add_u32 s2, s36, 0x1ae20200
	s_addc_u32 s3, s37, 0
	s_add_u32 s4, s36, 0x1ae20400
	s_addc_u32 s5, s37, 0
	s_add_u32 s6, s36, 0x1ae20500
	s_addc_u32 s7, s37, 0
	s_add_u32 s8, s36, 0x1ae20600
	s_addc_u32 s9, s37, 0
	s_add_u32 s10, s36, 0x1ae20700
	s_addc_u32 s11, s37, 0
	s_add_u32 s12, s36, 0x1ae20800
	s_addc_u32 s13, s37, 0
	s_add_u32 s14, s36, 0x1ae20900
	s_addc_u32 s15, s37, 0
	s_add_u32 s16, s36, 0x1ae20a00
	s_addc_u32 s17, s37, 0
	s_add_u32 s18, s36, 0x1ae20b00
	s_addc_u32 s19, s37, 0
	s_add_u32 s20, s36, 0x1ae20c00
	s_addc_u32 s21, s37, 0
	s_add_u32 s22, s36, 0x1ae20d00
	s_addc_u32 s23, s37, 0
	s_add_u32 s24, s36, 0x1ae20e00
	s_addc_u32 s25, s37, 0
	s_add_u32 s26, s36, 0x1ae20f00
	s_addc_u32 s27, s37, 0
	s_add_u32 s28, s36, 0x1ae21000
	s_addc_u32 s29, s37, 0
	s_add_u32 s30, s36, 0x1ae21100
	s_addc_u32 s31, s37, 0
	s_add_u32 s34, s36, 0x1ae21200
	s_addc_u32 s35, s37, 0
	s_add_u32 s36, s36, 0x1ae21300
	s_mul_i32 s33, s33, s90
	s_addc_u32 s37, s37, 0
	s_mov_b32 s44, 1
	v_mov_b32_e32 v16, 0
	s_branch .LBB0_778
